# write-through (sc1) 16-byte stores in the GEMM and rope phases; no L2 write-back in the grid barrier after those phases
# speedup vs baseline: 1.0034x; 1.0034x over previous
.LBB0_676:
	v_lshl_add_u32 v144, s12, 8, v139
	v_lshl_or_b32 v146, s37, 8, v141
	v_ashrrev_i32_e32 v145, 31, v144
	v_readlane_b32 s18, v253, 56
	v_ashrrev_i32_e32 v147, 31, v146
	v_lshlrev_b64 v[148:149], 13, v[144:145]
	v_readlane_b32 s19, v253, 57
	v_lshlrev_b64 v[146:147], 1, v[146:147]
	v_cvt_pk_bf16_f32 v108, v108, v109
	v_lshl_add_u64 v[148:149], s[18:19], 0, v[148:149]
	v_lshl_add_u64 v[148:149], v[148:149], 0, v[146:147]
	v_cvt_pk_bf16_f32 v109, v110, v111
	v_cvt_pk_bf16_f32 v110, v104, v105
	v_or_b32_e32 v104, 16, v144
	v_cvt_pk_bf16_f32 v92, v92, v93
	v_cvt_pk_bf16_f32 v93, v94, v95
	v_cvt_pk_bf16_f32 v94, v88, v89
	v_or_b32_e32 v88, 32, v144
	v_cvt_pk_bf16_f32 v76, v76, v77
	v_cvt_pk_bf16_f32 v77, v78, v79
	v_cvt_pk_bf16_f32 v78, v72, v73
	v_or_b32_e32 v72, 48, v144
	s_mov_b32 s9, 0x100000
	v_ashrrev_i32_e32 v105, 31, v104
	v_ashrrev_i32_e32 v89, 31, v88
	v_ashrrev_i32_e32 v73, 31, v72
	v_cvt_pk_bf16_f32 v60, v60, v61
	v_cvt_pk_bf16_f32 v61, v62, v63
	v_cvt_pk_bf16_f32 v62, v56, v57
	v_add_co_u32_e32 v56, vcc, s9, v148
	v_lshlrev_b64 v[104:105], 13, v[104:105]
	v_lshlrev_b64 v[88:89], 13, v[88:89]
	v_lshlrev_b64 v[72:73], 13, v[72:73]
	v_cvt_pk_bf16_f32 v68, v68, v69
	v_cvt_pk_bf16_f32 v69, v70, v71
	v_cvt_pk_bf16_f32 v70, v64, v65
	v_lshl_add_u64 v[64:65], v[148:149], 0, s[0:1]
	v_addc_co_u32_e32 v57, vcc, 0, v149, vcc
	v_cvt_pk_bf16_f32 v44, v44, v45
	v_cvt_pk_bf16_f32 v45, v46, v47
	v_cvt_pk_bf16_f32 v46, v40, v41
	v_cvt_pk_bf16_f32 v47, v42, v43
	s_mov_b32 s9, 0x120000
	v_lshl_add_u64 v[104:105], s[18:19], 0, v[104:105]
	v_lshl_add_u64 v[88:89], s[18:19], 0, v[88:89]
	v_lshl_add_u64 v[72:73], s[18:19], 0, v[72:73]
	global_store_dwordx4 v[64:65], v[44:47], off offset:256 sc1
	s_mov_b64 s[18:19], 0x120000
	v_cvt_pk_bf16_f32 v28, v28, v29
	v_add_co_u32_e32 v46, vcc, s9, v148
	v_lshl_add_u64 v[44:45], v[148:149], 0, s[18:19]
	s_nop 0
	v_addc_co_u32_e32 v47, vcc, 0, v149, vcc
	v_cvt_pk_bf16_f32 v29, v30, v31
	v_cvt_pk_bf16_f32 v30, v24, v25
	v_cvt_pk_bf16_f32 v31, v26, v27
	s_mov_b32 s9, 0x140000
	global_store_dwordx4 v[44:45], v[28:31], off offset:256 sc1
	s_mov_b64 s[18:19], 0x140000
	v_cvt_pk_bf16_f32 v111, v106, v107
	v_add_co_u32_e32 v30, vcc, s9, v148
	v_lshl_add_u64 v[28:29], v[148:149], 0, s[18:19]
	s_nop 0
	v_addc_co_u32_e32 v31, vcc, 0, v149, vcc
	v_cvt_pk_bf16_f32 v12, v12, v13
	v_cvt_pk_bf16_f32 v13, v14, v15
	v_cvt_pk_bf16_f32 v14, v8, v9
	v_cvt_pk_bf16_f32 v15, v10, v11
	s_mov_b32 s9, 0x160000
	global_store_dwordx4 v[148:149], v[108:111], off offset:256 sc1
	v_cvt_pk_bf16_f32 v95, v90, v91
	global_store_dwordx4 v[28:29], v[12:15], off offset:256 sc1
	v_lshl_add_u64 v[108:109], v[104:105], 0, v[146:147]
	global_store_dwordx4 v[108:109], v[92:95], off offset:256 sc1
	v_add_co_u32_e32 v14, vcc, s9, v148
	s_nop 0
	v_lshl_add_u64 v[92:93], v[88:89], 0, v[146:147]
	v_cvt_pk_bf16_f32 v79, v74, v75
	s_mov_b64 s[18:19], 0x160000
	v_addc_co_u32_e32 v15, vcc, 0, v149, vcc
	v_readlane_b32 s54, v254, 48
	v_cvt_pk_bf16_f32 v124, v124, v125
	v_cvt_pk_bf16_f32 v125, v126, v127
	v_cvt_pk_bf16_f32 v126, v120, v121
	v_cvt_pk_bf16_f32 v127, v122, v123
	v_cvt_pk_bf16_f32 v104, v116, v117
	v_cvt_pk_bf16_f32 v105, v118, v119
	v_cvt_pk_bf16_f32 v106, v112, v113
	v_cvt_pk_bf16_f32 v107, v114, v115
	v_cvt_pk_bf16_f32 v88, v100, v101
	v_cvt_pk_bf16_f32 v89, v102, v103
	v_cvt_pk_bf16_f32 v90, v96, v97
	v_cvt_pk_bf16_f32 v91, v98, v99
	global_store_dwordx4 v[92:93], v[76:79], off offset:256 sc1
	v_cvt_pk_bf16_f32 v74, v80, v81
	v_cvt_pk_bf16_f32 v75, v82, v83
	v_lshl_add_u64 v[76:77], v[72:73], 0, v[146:147]
	v_cvt_pk_bf16_f32 v72, v84, v85
	v_cvt_pk_bf16_f32 v73, v86, v87
	v_cvt_pk_bf16_f32 v71, v66, v67
	v_cvt_pk_bf16_f32 v63, v58, v59
	v_cvt_pk_bf16_f32 v40, v52, v53
	v_cvt_pk_bf16_f32 v41, v54, v55
	v_cvt_pk_bf16_f32 v42, v48, v49
	v_cvt_pk_bf16_f32 v43, v50, v51
	v_cvt_pk_bf16_f32 v24, v36, v37
	v_cvt_pk_bf16_f32 v25, v38, v39
	v_cvt_pk_bf16_f32 v26, v32, v33
	v_cvt_pk_bf16_f32 v27, v34, v35
	v_lshl_add_u64 v[12:13], v[148:149], 0, s[18:19]
	v_cvt_pk_bf16_f32 v8, v20, v21
	v_cvt_pk_bf16_f32 v9, v22, v23
	v_cvt_pk_bf16_f32 v10, v16, v17
	v_cvt_pk_bf16_f32 v11, v18, v19
	v_cvt_pk_bf16_f32 v4, v4, v5
	v_cvt_pk_bf16_f32 v5, v6, v7
	v_cvt_pk_bf16_f32 v6, v0, v1
	v_cvt_pk_bf16_f32 v7, v2, v3
	s_andn2_b64 vcc, exec, s[4:5]
	s_mov_b64 s[4:5], -1
	v_readlane_b32 s55, v254, 49
	global_store_dwordx4 v[148:149], v[124:127], off sc1
	global_store_dwordx4 v[108:109], v[104:107], off sc1
	global_store_dwordx4 v[92:93], v[88:91], off sc1
	global_store_dwordx4 v[76:77], v[72:75], off sc1
	global_store_dwordx4 v[76:77], v[68:71], off offset:256 sc1
	global_store_dwordx4 v[56:57], v[60:63], off sc1
	global_store_dwordx4 v[46:47], v[40:43], off sc1
	global_store_dwordx4 v[30:31], v[24:27], off sc1
	global_store_dwordx4 v[14:15], v[8:11], off sc1
	global_store_dwordx4 v[12:13], v[4:7], off offset:256 sc1
	s_cbranch_vccnz .LBB0_669
	s_andn2_b64 vcc, exec, s[2:3]
	s_cbranch_vccnz .LBB0_668
	s_barrier
	s_branch .LBB0_668

.LBB0_683:
	s_or_b64 exec, exec, s[4:5]
	s_waitcnt vmcnt(0)
	v_mul_f32_e32 v6, v6, v7
	ds_write_b32 v44, v6 offset:8184
	s_waitcnt lgkmcnt(0)
	s_sub_i32 s4, 0, s3
	ds_read2_b32 v[50:51], v43 offset0:33 offset1:41
	ds_read2_b32 v[52:53], v43 offset1:8
	ds_read2_b32 v[54:55], v43 offset0:66 offset1:74
	ds_read2_b32 v[56:57], v43 offset0:99 offset1:107
	ds_read2_b32 v[58:59], v43 offset0:132 offset1:140
	ds_read2_b32 v[60:61], v43 offset0:165 offset1:173
	ds_read2_b32 v[62:63], v43 offset0:198 offset1:206
	ds_read2_b32 v[64:65], v43 offset0:231 offset1:239
	s_add_i32 s4, s4, s10
	v_add_u32_e32 v66, s4, v9
	s_ashr_i32 s3, s2, 31
	v_ashrrev_i32_e32 v67, 31, v66
	v_lshl_add_u64 v[6:7], s[2:3], 1, v[4:5]
	v_lshlrev_b64 v[68:69], 12, v[66:67]
	s_waitcnt lgkmcnt(6)
	v_cvt_pk_bf16_f32 v46, v52, v50
	s_waitcnt lgkmcnt(4)
	v_cvt_pk_bf16_f32 v47, v54, v56
	s_waitcnt lgkmcnt(2)
	v_cvt_pk_bf16_f32 v48, v58, v60
	s_waitcnt lgkmcnt(0)
	v_cvt_pk_bf16_f32 v49, v62, v64
	v_lshl_add_u64 v[68:69], v[6:7], 0, v[68:69]
	v_add_u32_e32 v50, 8, v66
	global_store_dwordx4 v[68:69], v[46:49], off sc1
	v_add_u32_e32 v68, 16, v66
	v_ashrrev_i32_e32 v69, 31, v68
	v_cvt_pk_bf16_f32 v46, v53, v51
	v_ashrrev_i32_e32 v51, 31, v50
	v_lshlrev_b64 v[50:51], 12, v[50:51]
	v_cvt_pk_bf16_f32 v47, v55, v57
	v_cvt_pk_bf16_f32 v48, v59, v61
	v_cvt_pk_bf16_f32 v49, v63, v65
	v_lshl_add_u64 v[50:51], v[6:7], 0, v[50:51]
	global_store_dwordx4 v[50:51], v[46:49], off sc1
	ds_read2_b32 v[50:51], v43 offset0:49 offset1:57
	ds_read2_b32 v[52:53], v43 offset0:16 offset1:24
	ds_read2_b32 v[54:55], v43 offset0:82 offset1:90
	ds_read2_b32 v[56:57], v43 offset0:115 offset1:123
	ds_read2_b32 v[58:59], v43 offset0:148 offset1:156
	ds_read2_b32 v[60:61], v43 offset0:181 offset1:189
	ds_read2_b32 v[62:63], v43 offset0:214 offset1:222
	ds_read2_b32 v[64:65], v43 offset0:247 offset1:255
	v_lshlrev_b64 v[68:69], 12, v[68:69]
	s_waitcnt lgkmcnt(6)
	v_cvt_pk_bf16_f32 v46, v52, v50
	s_waitcnt lgkmcnt(4)
	v_cvt_pk_bf16_f32 v47, v54, v56
	s_waitcnt lgkmcnt(2)
	v_cvt_pk_bf16_f32 v48, v58, v60
	s_waitcnt lgkmcnt(0)
	v_cvt_pk_bf16_f32 v49, v62, v64
	v_lshl_add_u64 v[68:69], v[6:7], 0, v[68:69]
	v_add_u32_e32 v50, 24, v66
	global_store_dwordx4 v[68:69], v[46:49], off sc1
	s_add_i32 s2, s11, 0x600
	s_add_i32 s10, s10, 0xc000
	v_cvt_pk_bf16_f32 v46, v53, v51
	v_ashrrev_i32_e32 v51, 31, v50
	v_lshlrev_b64 v[50:51], 12, v[50:51]
	v_cvt_pk_bf16_f32 v47, v55, v57
	v_cvt_pk_bf16_f32 v48, v59, v61
	v_cvt_pk_bf16_f32 v49, v63, v65
	v_lshl_add_u64 v[6:7], v[6:7], 0, v[50:51]
	global_store_dwordx4 v[6:7], v[46:49], off sc1
	s_waitcnt lgkmcnt(0)
	s_cmpk_lt_i32 s11, 0x200
	s_mov_b32 s11, s2
	s_cbranch_scc0 .LBB0_939

.LBB0_941:
	s_mul_hi_i32 s2, s7, 0x2e8ba2e9
	s_lshr_b32 s3, s2, 31
	s_ashr_i32 s2, s2, 6
	s_add_i32 s4, s2, s3
	s_mul_i32 s2, s4, 0xfffffea0
	s_add_i32 s3, s7, s2
	s_lshl_b32 s2, s4, 6
	s_mulk_i32 s4, 0xd400
	s_add_i32 s4, s6, s4
	s_ashr_i32 s5, s4, 31
	v_or_b32_e32 v34, s2, v8
	v_lshl_add_u64 v[44:45], s[4:5], 2, v[2:3]
	v_mad_i64_i32 v[16:17], s[10:11], v34, s93, v[44:45]
	v_or_b32_e32 v15, 2, v34
	global_load_dword v43, v[16:17], off nt
	v_mad_i64_i32 v[16:17], s[10:11], v15, s93, v[44:45]
	v_or_b32_e32 v15, 4, v34
	global_load_dword v48, v[16:17], off nt
	v_mad_i64_i32 v[16:17], s[10:11], v15, s93, v[44:45]
	v_or_b32_e32 v15, 6, v34
	global_load_dword v49, v[16:17], off nt
	v_mad_i64_i32 v[16:17], s[10:11], v15, s93, v[44:45]
	v_or_b32_e32 v15, 8, v34
	global_load_dword v50, v[16:17], off nt
	v_mad_i64_i32 v[16:17], s[10:11], v15, s93, v[44:45]
	v_or_b32_e32 v15, 10, v34
	global_load_dword v35, v[16:17], off nt
	v_mad_i64_i32 v[16:17], s[10:11], v15, s93, v[44:45]
	v_or_b32_e32 v15, 12, v34
	global_load_dword v37, v[16:17], off nt
	v_mad_i64_i32 v[16:17], s[10:11], v15, s93, v[44:45]
	v_or_b32_e32 v15, 14, v34
	global_load_dword v39, v[16:17], off nt
	v_mad_i64_i32 v[16:17], s[10:11], v15, s93, v[44:45]
	v_or_b32_e32 v15, 16, v34
	global_load_dword v41, v[16:17], off nt
	v_mad_i64_i32 v[16:17], s[10:11], v15, s93, v[44:45]
	v_or_b32_e32 v15, 18, v34
	global_load_dword v36, v[16:17], off nt
	v_mad_i64_i32 v[16:17], s[10:11], v15, s93, v[44:45]
	v_or_b32_e32 v15, 20, v34
	global_load_dword v38, v[16:17], off nt
	v_mad_i64_i32 v[16:17], s[10:11], v15, s93, v[44:45]
	v_or_b32_e32 v15, 22, v34
	global_load_dword v40, v[16:17], off nt
	v_mad_i64_i32 v[16:17], s[10:11], v15, s93, v[44:45]
	v_or_b32_e32 v15, 24, v34
	global_load_dword v42, v[16:17], off nt
	v_mad_i64_i32 v[16:17], s[10:11], v15, s93, v[44:45]
	global_load_dword v15, v[16:17], off nt
	v_or_b32_e32 v16, 26, v34
	v_mad_i64_i32 v[16:17], s[10:11], v16, s93, v[44:45]
	global_load_dword v18, v[16:17], off nt
	v_or_b32_e32 v16, 28, v34
	v_mad_i64_i32 v[16:17], s[10:11], v16, s93, v[44:45]
	global_load_dword v22, v[16:17], off nt
	v_or_b32_e32 v16, 30, v34
	v_mad_i64_i32 v[16:17], s[10:11], v16, s93, v[44:45]
	global_load_dword v28, v[16:17], off nt
	v_or_b32_e32 v16, 32, v34
	v_mad_i64_i32 v[16:17], s[10:11], v16, s93, v[44:45]
	global_load_dword v16, v[16:17], off nt
	v_or_b32_e32 v17, 34, v34
	v_mad_i64_i32 v[20:21], s[10:11], v17, s93, v[44:45]
	v_or_b32_e32 v17, 36, v34
	v_mad_i64_i32 v[24:25], s[10:11], v17, s93, v[44:45]
	v_or_b32_e32 v17, 38, v34
	v_mad_i64_i32 v[26:27], s[10:11], v17, s93, v[44:45]
	v_or_b32_e32 v17, 40, v34
	global_load_dword v20, v[20:21], off nt
	v_or_b32_e32 v19, 42, v34
	global_load_dword v24, v[24:25], off nt
	v_or_b32_e32 v31, 60, v34
	global_load_dword v30, v[26:27], off nt
	v_mad_i64_i32 v[26:27], s[10:11], v17, s93, v[44:45]
	global_load_dword v17, v[26:27], off nt
	v_mad_i64_i32 v[26:27], s[10:11], v19, s93, v[44:45]
	v_or_b32_e32 v19, 44, v34
	global_load_dword v23, v[26:27], off nt
	v_mad_i64_i32 v[26:27], s[10:11], v19, s93, v[44:45]
	v_or_b32_e32 v19, 46, v34
	v_mad_i64_i32 v[32:33], s[10:11], v19, s93, v[44:45]
	v_or_b32_e32 v19, 48, v34
	v_mad_i64_i32 v[46:47], s[10:11], v19, s93, v[44:45]
	v_or_b32_e32 v21, 50, v34
	global_load_dword v26, v[26:27], off nt
	s_cmpk_gt_i32 s3, 0xaf
	global_load_dword v32, v[32:33], off nt
	s_cselect_b32 s3, 0xffffea00, 0
	global_load_dword v19, v[46:47], off nt
	v_mad_i64_i32 v[46:47], s[10:11], v21, s93, v[44:45]
	v_or_b32_e32 v21, 52, v34
	global_load_dword v25, v[46:47], off nt
	v_mad_i64_i32 v[46:47], s[10:11], v21, s93, v[44:45]
	v_or_b32_e32 v21, 54, v34
	global_load_dword v29, v[46:47], off nt
	v_mad_i64_i32 v[46:47], s[10:11], v21, s93, v[44:45]
	v_or_b32_e32 v21, 56, v34
	global_load_dword v33, v[46:47], off nt
	v_mad_i64_i32 v[46:47], s[10:11], v21, s93, v[44:45]
	v_or_b32_e32 v27, 58, v34
	global_load_dword v21, v[46:47], off nt
	v_mad_i64_i32 v[46:47], s[10:11], v27, s93, v[44:45]
	v_or_b32_e32 v34, 62, v34
	global_load_dword v27, v[46:47], off nt
	v_mad_i64_i32 v[46:47], s[10:11], v31, s93, v[44:45]
	v_mad_i64_i32 v[44:45], s[10:11], v34, s93, v[44:45]
	global_load_dword v31, v[46:47], off nt
	global_load_dword v34, v[44:45], off nt
	s_waitcnt vmcnt(30)
	ds_write2_b32 v14, v43, v48 offset1:66
	s_waitcnt vmcnt(28)
	ds_write2_b32 v14, v49, v50 offset0:132 offset1:198
	v_add_u32_e32 v43, 0x400, v14
	s_waitcnt vmcnt(26)
	ds_write2_b32 v43, v35, v37 offset0:8 offset1:74
	s_waitcnt vmcnt(24)
	ds_write2_b32 v43, v39, v41 offset0:140 offset1:206
	v_add_u32_e32 v35, 0x800, v14
	s_waitcnt vmcnt(22)
	ds_write2_b32 v35, v36, v38 offset0:16 offset1:82
	s_waitcnt vmcnt(20)
	ds_write2_b32 v35, v40, v42 offset0:148 offset1:214
	v_add_u32_e32 v35, 0xc00, v14
	s_waitcnt vmcnt(18)
	ds_write2_b32 v35, v15, v18 offset0:24 offset1:90
	s_waitcnt vmcnt(16)
	ds_write2_b32 v35, v22, v28 offset0:156 offset1:222
	v_add_u32_e32 v15, 0x1000, v14
	s_waitcnt vmcnt(14)
	ds_write2_b32 v15, v16, v20 offset0:32 offset1:98
	s_waitcnt vmcnt(12)
	ds_write2_b32 v15, v24, v30 offset0:164 offset1:230
	v_add_u32_e32 v15, 0x1400, v14
	s_waitcnt vmcnt(10)
	ds_write2_b32 v15, v17, v23 offset0:40 offset1:106
	s_waitcnt vmcnt(8)
	ds_write2_b32 v15, v26, v32 offset0:172 offset1:238
	v_add_u32_e32 v15, 0x1800, v14
	s_waitcnt vmcnt(6)
	ds_write2_b32 v15, v19, v25 offset0:48 offset1:114
	s_waitcnt vmcnt(4)
	ds_write2_b32 v15, v29, v33 offset0:180 offset1:246
	v_add_u32_e32 v15, 0x1c00, v14
	s_waitcnt vmcnt(2)
	ds_write2_b32 v15, v21, v27 offset0:56 offset1:122
	s_waitcnt vmcnt(0)
	ds_write2_b32 v15, v31, v34 offset0:188 offset1:254
	s_cselect_b32 s5, 0x80, 0
	s_add_i32 s3, s4, s3
	s_waitcnt lgkmcnt(0)
	s_lshl_b32 s3, s3, 1
	s_and_b32 s4, s4, 0x60
	s_and_b32 s3, s3, 0xffffff00
	s_or_b32 s4, s4, s5
	ds_read2_b32 v[22:23], v1 offset0:33 offset1:41
	ds_read2_b32 v[24:25], v1 offset1:8
	ds_read2_b32 v[26:27], v1 offset0:66 offset1:74
	ds_read2_b32 v[28:29], v1 offset0:99 offset1:107
	ds_read2_b32 v[30:31], v1 offset0:132 offset1:140
	ds_read2_b32 v[32:33], v1 offset0:165 offset1:173
	ds_read2_b32 v[34:35], v1 offset0:198 offset1:206
	ds_read2_b32 v[36:37], v1 offset0:231 offset1:239
	s_or_b32 s4, s4, s3
	v_or_b32_e32 v38, s4, v9
	s_ashr_i32 s3, s2, 31
	v_ashrrev_i32_e32 v39, 31, v38
	v_lshl_add_u64 v[20:21], s[2:3], 1, v[4:5]
	v_lshlrev_b64 v[38:39], 12, v[38:39]
	s_waitcnt lgkmcnt(6)
	v_cvt_pk_bf16_f32 v16, v24, v22
	s_waitcnt lgkmcnt(4)
	v_cvt_pk_bf16_f32 v17, v26, v28
	s_waitcnt lgkmcnt(2)
	v_cvt_pk_bf16_f32 v18, v30, v32
	s_waitcnt lgkmcnt(0)
	v_cvt_pk_bf16_f32 v19, v34, v36
	v_lshl_add_u64 v[38:39], v[20:21], 0, v[38:39]
	v_or_b32_e32 v22, s4, v6
	global_store_dwordx4 v[38:39], v[16:19], off sc1
	v_or_b32_e32 v38, s4, v7
	v_ashrrev_i32_e32 v39, 31, v38
	v_cvt_pk_bf16_f32 v16, v25, v23
	v_ashrrev_i32_e32 v23, 31, v22
	v_lshlrev_b64 v[22:23], 12, v[22:23]
	v_cvt_pk_bf16_f32 v17, v27, v29
	v_cvt_pk_bf16_f32 v18, v31, v33
	v_cvt_pk_bf16_f32 v19, v35, v37
	v_lshl_add_u64 v[22:23], v[20:21], 0, v[22:23]
	global_store_dwordx4 v[22:23], v[16:19], off sc1
	ds_read2_b32 v[22:23], v1 offset0:49 offset1:57
	ds_read2_b32 v[24:25], v1 offset0:16 offset1:24
	ds_read2_b32 v[26:27], v1 offset0:82 offset1:90
	ds_read2_b32 v[28:29], v1 offset0:115 offset1:123
	ds_read2_b32 v[30:31], v1 offset0:148 offset1:156
	ds_read2_b32 v[32:33], v1 offset0:181 offset1:189
	ds_read2_b32 v[34:35], v1 offset0:214 offset1:222
	ds_read2_b32 v[36:37], v1 offset0:247 offset1:255
	v_lshlrev_b64 v[38:39], 12, v[38:39]
	s_waitcnt lgkmcnt(6)
	v_cvt_pk_bf16_f32 v16, v24, v22
	s_waitcnt lgkmcnt(4)
	v_cvt_pk_bf16_f32 v17, v26, v28
	s_waitcnt lgkmcnt(2)
	v_cvt_pk_bf16_f32 v18, v30, v32
	s_waitcnt lgkmcnt(0)
	v_cvt_pk_bf16_f32 v19, v34, v36
	v_lshl_add_u64 v[38:39], v[20:21], 0, v[38:39]
	v_or_b32_e32 v22, s4, v13
	global_store_dwordx4 v[38:39], v[16:19], off sc1
	s_add_i32 s2, s7, 0x600
	s_add_i32 s6, s6, 0xc000
	v_cvt_pk_bf16_f32 v16, v25, v23
	v_ashrrev_i32_e32 v23, 31, v22
	v_lshlrev_b64 v[22:23], 12, v[22:23]
	v_cvt_pk_bf16_f32 v17, v27, v29
	v_cvt_pk_bf16_f32 v18, v31, v33
	v_cvt_pk_bf16_f32 v19, v35, v37
	v_lshl_add_u64 v[20:21], v[20:21], 0, v[22:23]
	global_store_dwordx4 v[20:21], v[16:19], off sc1
	s_waitcnt lgkmcnt(0)
	s_cmpk_lt_i32 s7, 0x2600
	s_mov_b32 s7, s2
	s_cbranch_scc1 .LBB0_941

.LBB0_944:
	s_ashr_i32 s2, s8, 31
	s_lshr_b32 s2, s2, 26
	s_add_i32 s2, s8, s2
	s_ashr_i32 s5, s2, 6
	s_andn2_b32 s2, s2, 63
	s_lshl_b32 s3, s5, 11
	v_or_b32_e32 v6, s2, v8
	s_sub_i32 s6, s4, s3
	v_or_b32_e32 v14, 2, v6
	s_ashr_i32 s7, s6, 31
	v_ashrrev_i32_e32 v7, 31, v6
	v_ashrrev_i32_e32 v15, 31, v14
	v_lshl_add_u64 v[4:5], s[6:7], 2, v[2:3]
	v_lshlrev_b64 v[12:13], 13, v[6:7]
	v_lshlrev_b64 v[14:15], 13, v[14:15]
	v_lshl_add_u64 v[12:13], v[4:5], 0, v[12:13]
	v_lshl_add_u64 v[14:15], v[4:5], 0, v[14:15]
	global_load_dword v12, v[12:13], off nt
	v_or_b32_e32 v16, 6, v6
	global_load_dword v13, v[14:15], off nt
	v_or_b32_e32 v14, 4, v6
	v_ashrrev_i32_e32 v15, 31, v14
	v_ashrrev_i32_e32 v17, 31, v16
	v_lshlrev_b64 v[14:15], 13, v[14:15]
	v_lshlrev_b64 v[16:17], 13, v[16:17]
	v_lshl_add_u64 v[14:15], v[4:5], 0, v[14:15]
	v_lshl_add_u64 v[16:17], v[4:5], 0, v[16:17]
	global_load_dword v14, v[14:15], off nt
	v_or_b32_e32 v18, 10, v6
	global_load_dword v15, v[16:17], off nt
	v_or_b32_e32 v16, 8, v6
	v_ashrrev_i32_e32 v17, 31, v16
	v_ashrrev_i32_e32 v19, 31, v18
	v_lshlrev_b64 v[16:17], 13, v[16:17]
	v_lshlrev_b64 v[18:19], 13, v[18:19]
	v_lshl_add_u64 v[16:17], v[4:5], 0, v[16:17]
	v_lshl_add_u64 v[18:19], v[4:5], 0, v[18:19]
	global_load_dword v16, v[16:17], off nt
	v_or_b32_e32 v20, 14, v6
	global_load_dword v17, v[18:19], off nt
	v_or_b32_e32 v18, 12, v6
	v_ashrrev_i32_e32 v19, 31, v18
	v_ashrrev_i32_e32 v21, 31, v20
	v_lshlrev_b64 v[18:19], 13, v[18:19]
	v_lshlrev_b64 v[20:21], 13, v[20:21]
	v_lshl_add_u64 v[18:19], v[4:5], 0, v[18:19]
	v_lshl_add_u64 v[20:21], v[4:5], 0, v[20:21]
	global_load_dword v18, v[18:19], off nt
	v_or_b32_e32 v22, 18, v6
	global_load_dword v19, v[20:21], off nt
	v_or_b32_e32 v20, 16, v6
	v_ashrrev_i32_e32 v21, 31, v20
	v_ashrrev_i32_e32 v23, 31, v22
	v_lshlrev_b64 v[20:21], 13, v[20:21]
	v_lshlrev_b64 v[22:23], 13, v[22:23]
	v_lshl_add_u64 v[20:21], v[4:5], 0, v[20:21]
	v_lshl_add_u64 v[22:23], v[4:5], 0, v[22:23]
	global_load_dword v20, v[20:21], off nt
	v_or_b32_e32 v24, 22, v6
	global_load_dword v21, v[22:23], off nt
	v_or_b32_e32 v22, 20, v6
	v_ashrrev_i32_e32 v23, 31, v22
	v_ashrrev_i32_e32 v25, 31, v24
	v_lshlrev_b64 v[22:23], 13, v[22:23]
	v_lshlrev_b64 v[24:25], 13, v[24:25]
	v_lshl_add_u64 v[22:23], v[4:5], 0, v[22:23]
	v_lshl_add_u64 v[24:25], v[4:5], 0, v[24:25]
	global_load_dword v22, v[22:23], off nt
	v_or_b32_e32 v26, 26, v6
	global_load_dword v23, v[24:25], off nt
	v_or_b32_e32 v24, 24, v6
	v_ashrrev_i32_e32 v25, 31, v24
	v_ashrrev_i32_e32 v27, 31, v26
	v_lshlrev_b64 v[24:25], 13, v[24:25]
	v_lshlrev_b64 v[26:27], 13, v[26:27]
	v_lshl_add_u64 v[24:25], v[4:5], 0, v[24:25]
	v_lshl_add_u64 v[26:27], v[4:5], 0, v[26:27]
	global_load_dword v24, v[24:25], off nt
	v_or_b32_e32 v28, 30, v6
	global_load_dword v25, v[26:27], off nt
	v_or_b32_e32 v26, 28, v6
	v_ashrrev_i32_e32 v27, 31, v26
	v_ashrrev_i32_e32 v29, 31, v28
	v_lshlrev_b64 v[26:27], 13, v[26:27]
	v_lshlrev_b64 v[28:29], 13, v[28:29]
	v_lshl_add_u64 v[26:27], v[4:5], 0, v[26:27]
	v_lshl_add_u64 v[28:29], v[4:5], 0, v[28:29]
	global_load_dword v26, v[26:27], off nt
	v_or_b32_e32 v30, 34, v6
	global_load_dword v27, v[28:29], off nt
	v_or_b32_e32 v28, 32, v6
	v_ashrrev_i32_e32 v29, 31, v28
	v_ashrrev_i32_e32 v31, 31, v30
	v_lshlrev_b64 v[28:29], 13, v[28:29]
	v_lshlrev_b64 v[30:31], 13, v[30:31]
	v_lshl_add_u64 v[28:29], v[4:5], 0, v[28:29]
	v_lshl_add_u64 v[30:31], v[4:5], 0, v[30:31]
	global_load_dword v28, v[28:29], off nt
	v_or_b32_e32 v32, 38, v6
	global_load_dword v29, v[30:31], off nt
	v_or_b32_e32 v30, 36, v6
	v_ashrrev_i32_e32 v31, 31, v30
	v_ashrrev_i32_e32 v33, 31, v32
	v_lshlrev_b64 v[30:31], 13, v[30:31]
	v_lshlrev_b64 v[32:33], 13, v[32:33]
	v_lshl_add_u64 v[30:31], v[4:5], 0, v[30:31]
	v_lshl_add_u64 v[32:33], v[4:5], 0, v[32:33]
	global_load_dword v30, v[30:31], off nt
	v_or_b32_e32 v34, 42, v6
	global_load_dword v31, v[32:33], off nt
	v_or_b32_e32 v32, 40, v6
	v_ashrrev_i32_e32 v33, 31, v32
	v_ashrrev_i32_e32 v35, 31, v34
	v_lshlrev_b64 v[32:33], 13, v[32:33]
	v_lshlrev_b64 v[34:35], 13, v[34:35]
	v_lshl_add_u64 v[32:33], v[4:5], 0, v[32:33]
	v_lshl_add_u64 v[34:35], v[4:5], 0, v[34:35]
	global_load_dword v32, v[32:33], off nt
	v_or_b32_e32 v36, 46, v6
	global_load_dword v33, v[34:35], off nt
	v_or_b32_e32 v34, 44, v6
	v_ashrrev_i32_e32 v35, 31, v34
	v_ashrrev_i32_e32 v37, 31, v36
	v_lshlrev_b64 v[34:35], 13, v[34:35]
	v_lshlrev_b64 v[36:37], 13, v[36:37]
	v_lshl_add_u64 v[34:35], v[4:5], 0, v[34:35]
	v_lshl_add_u64 v[36:37], v[4:5], 0, v[36:37]
	global_load_dword v34, v[34:35], off nt
	v_or_b32_e32 v38, 50, v6
	global_load_dword v35, v[36:37], off nt
	v_or_b32_e32 v36, 48, v6
	v_ashrrev_i32_e32 v37, 31, v36
	v_ashrrev_i32_e32 v39, 31, v38
	v_lshlrev_b64 v[36:37], 13, v[36:37]
	v_lshlrev_b64 v[38:39], 13, v[38:39]
	v_lshl_add_u64 v[36:37], v[4:5], 0, v[36:37]
	v_lshl_add_u64 v[38:39], v[4:5], 0, v[38:39]
	global_load_dword v36, v[36:37], off nt
	v_or_b32_e32 v40, 54, v6
	global_load_dword v37, v[38:39], off nt
	v_or_b32_e32 v38, 52, v6
	v_ashrrev_i32_e32 v39, 31, v38
	v_ashrrev_i32_e32 v41, 31, v40
	v_lshlrev_b64 v[38:39], 13, v[38:39]
	v_lshlrev_b64 v[40:41], 13, v[40:41]
	v_lshl_add_u64 v[38:39], v[4:5], 0, v[38:39]
	v_lshl_add_u64 v[40:41], v[4:5], 0, v[40:41]
	global_load_dword v38, v[38:39], off nt
	v_or_b32_e32 v42, 58, v6
	global_load_dword v39, v[40:41], off nt
	v_or_b32_e32 v40, 56, v6
	v_ashrrev_i32_e32 v41, 31, v40
	v_ashrrev_i32_e32 v43, 31, v42
	v_lshlrev_b64 v[40:41], 13, v[40:41]
	v_lshlrev_b64 v[42:43], 13, v[42:43]
	v_lshl_add_u64 v[40:41], v[4:5], 0, v[40:41]
	v_lshl_add_u64 v[42:43], v[4:5], 0, v[42:43]
	global_load_dword v40, v[40:41], off nt
	s_mul_i32 s5, s5, 0xff500000
	global_load_dword v41, v[42:43], off nt
	v_or_b32_e32 v42, 60, v6
	v_or_b32_e32 v6, 62, v6
	v_ashrrev_i32_e32 v43, 31, v42
	v_ashrrev_i32_e32 v7, 31, v6
	v_lshlrev_b64 v[42:43], 13, v[42:43]
	v_lshlrev_b64 v[6:7], 13, v[6:7]
	v_lshl_add_u64 v[42:43], v[4:5], 0, v[42:43]
	v_lshl_add_u64 v[4:5], v[4:5], 0, v[6:7]
	global_load_dword v42, v[42:43], off nt
	s_ashr_i32 s3, s2, 31
	global_load_dword v4, v[4:5], off nt
	v_add_u32_e32 v5, 0x400, v10
	s_waitcnt vmcnt(30)
	ds_write2_b32 v10, v12, v13 offset1:66
	s_waitcnt vmcnt(28)
	ds_write2_b32 v10, v14, v15 offset0:132 offset1:198
	s_waitcnt vmcnt(26)
	ds_write2_b32 v5, v16, v17 offset0:8 offset1:74
	s_waitcnt vmcnt(24)
	ds_write2_b32 v5, v18, v19 offset0:140 offset1:206
	v_add_u32_e32 v5, 0x800, v10
	s_waitcnt vmcnt(22)
	ds_write2_b32 v5, v20, v21 offset0:16 offset1:82
	s_waitcnt vmcnt(20)
	ds_write2_b32 v5, v22, v23 offset0:148 offset1:214
	v_add_u32_e32 v5, 0xc00, v10
	s_waitcnt vmcnt(18)
	ds_write2_b32 v5, v24, v25 offset0:24 offset1:90
	s_waitcnt vmcnt(16)
	ds_write2_b32 v5, v26, v27 offset0:156 offset1:222
	v_add_u32_e32 v5, 0x1000, v10
	s_waitcnt vmcnt(14)
	ds_write2_b32 v5, v28, v29 offset0:32 offset1:98
	s_waitcnt vmcnt(12)
	ds_write2_b32 v5, v30, v31 offset0:164 offset1:230
	v_add_u32_e32 v5, 0x1400, v10
	s_waitcnt vmcnt(10)
	ds_write2_b32 v5, v32, v33 offset0:40 offset1:106
	s_waitcnt vmcnt(8)
	ds_write2_b32 v5, v34, v35 offset0:172 offset1:238
	v_add_u32_e32 v5, 0x1800, v10
	s_waitcnt vmcnt(6)
	ds_write2_b32 v5, v36, v37 offset0:48 offset1:114
	s_waitcnt vmcnt(4)
	ds_write2_b32 v5, v38, v39 offset0:180 offset1:246
	v_add_u32_e32 v5, 0x1c00, v10
	s_waitcnt vmcnt(2)
	ds_write2_b32 v5, v40, v41 offset0:56 offset1:122
	s_waitcnt vmcnt(0)
	ds_write2_b32 v5, v42, v4 offset0:188 offset1:254
	s_waitcnt lgkmcnt(0)
	ds_read2_b32 v[14:15], v11 offset0:33 offset1:41
	ds_read2_b32 v[16:17], v11 offset1:8
	ds_read2_b32 v[18:19], v11 offset0:66 offset1:74
	ds_read2_b32 v[20:21], v11 offset0:99 offset1:107
	ds_read2_b32 v[22:23], v11 offset0:132 offset1:140
	ds_read2_b32 v[24:25], v11 offset0:165 offset1:173
	ds_read2_b32 v[26:27], v11 offset0:198 offset1:206
	ds_read2_b32 v[28:29], v11 offset0:231 offset1:239
	v_add_u32_e32 v30, s5, v9
	v_lshl_add_u64 v[12:13], s[2:3], 1, v[0:1]
	v_ashrrev_i32_e32 v31, 31, v30
	s_waitcnt lgkmcnt(6)
	v_cvt_pk_bf16_f32 v4, v16, v14
	s_waitcnt lgkmcnt(4)
	v_cvt_pk_bf16_f32 v5, v18, v20
	s_waitcnt lgkmcnt(2)
	v_cvt_pk_bf16_f32 v6, v22, v24
	s_waitcnt lgkmcnt(0)
	v_cvt_pk_bf16_f32 v7, v26, v28
	v_lshl_add_u64 v[32:33], v[30:31], 1, v[12:13]
	v_add_u32_e32 v14, 0xb000, v30
	global_store_dwordx4 v[32:33], v[4:7], off sc1
	v_add_u32_e32 v32, 0x16000, v30
	v_ashrrev_i32_e32 v33, 31, v32
	v_cvt_pk_bf16_f32 v4, v17, v15
	v_ashrrev_i32_e32 v15, 31, v14
	v_cvt_pk_bf16_f32 v5, v19, v21
	v_cvt_pk_bf16_f32 v6, v23, v25
	v_cvt_pk_bf16_f32 v7, v27, v29
	v_lshl_add_u64 v[14:15], v[14:15], 1, v[12:13]
	global_store_dwordx4 v[14:15], v[4:7], off sc1
	ds_read2_b32 v[14:15], v11 offset0:49 offset1:57
	ds_read2_b32 v[16:17], v11 offset0:16 offset1:24
	ds_read2_b32 v[18:19], v11 offset0:82 offset1:90
	ds_read2_b32 v[20:21], v11 offset0:115 offset1:123
	ds_read2_b32 v[22:23], v11 offset0:148 offset1:156
	ds_read2_b32 v[24:25], v11 offset0:181 offset1:189
	ds_read2_b32 v[26:27], v11 offset0:214 offset1:222
	ds_read2_b32 v[28:29], v11 offset0:247 offset1:255
	v_lshl_add_u64 v[32:33], v[32:33], 1, v[12:13]
	s_waitcnt lgkmcnt(6)
	v_cvt_pk_bf16_f32 v4, v16, v14
	s_waitcnt lgkmcnt(4)
	v_cvt_pk_bf16_f32 v5, v18, v20
	s_waitcnt lgkmcnt(2)
	v_cvt_pk_bf16_f32 v6, v22, v24
	s_waitcnt lgkmcnt(0)
	v_cvt_pk_bf16_f32 v7, v26, v28
	v_add_u32_e32 v14, 0x21000, v30
	global_store_dwordx4 v[32:33], v[4:7], off sc1
	s_add_i32 s2, s8, 0x600
	s_add_i32 s4, s4, 0xc000
	v_cvt_pk_bf16_f32 v4, v17, v15
	v_ashrrev_i32_e32 v15, 31, v14
	v_cvt_pk_bf16_f32 v5, v19, v21
	v_cvt_pk_bf16_f32 v6, v23, v25
	v_cvt_pk_bf16_f32 v7, v27, v29
	v_lshl_add_u64 v[12:13], v[14:15], 1, v[12:13]
	global_store_dwordx4 v[12:13], v[4:7], off sc1
	s_waitcnt lgkmcnt(0)
	v_add_u32_e32 v9, 0x10800000, v9
	s_cmpk_lt_i32 s8, 0x1000
	s_mov_b32 s8, s2
	s_cbranch_scc1 .LBB0_944

.LBB0_973:
	s_andn2_saveexec_b64 s[4:5], s[4:5]
	s_cbranch_execz .LBB0_989
	v_mov_b32_e32 v1, s50
	v_add_co_u32_e32 v2, vcc, 0x3000, v1
	v_mov_b32_e32 v1, s51
	s_waitcnt vmcnt(0)
	v_addc_co_u32_e32 v3, vcc, 0, v1, vcc
	flat_atomic_add v1, v[2:3], v217 offset:1024 sc0
	v_cvt_f32_u32_e32 v2, v0
	v_sub_u32_e32 v3, 0, v0
	s_mov_b64 s[8:9], -1
	v_rcp_iflag_f32_e32 v2, v2
	s_nop 0
	v_mul_f32_e32 v2, 0x4f7ffffe, v2
	v_cvt_u32_f32_e32 v2, v2
	v_mul_lo_u32 v3, v3, v2
	v_mul_hi_u32 v3, v2, v3
	v_add_u32_e32 v2, v2, v3
	s_waitcnt vmcnt(0) lgkmcnt(0)
	v_mul_hi_u32 v2, v1, v2
	v_mul_lo_u32 v3, v2, v0
	v_sub_u32_e32 v3, v1, v3
	v_cmp_ge_u32_e32 vcc, v3, v0
	v_add_u32_e32 v4, 1, v2
	s_nop 0
	v_cndmask_b32_e32 v2, v2, v4, vcc
	v_sub_u32_e32 v4, v3, v0
	v_cndmask_b32_e32 v3, v3, v4, vcc
	v_cmp_ge_u32_e32 vcc, v3, v0
	v_add_u32_e32 v3, 1, v2
	s_nop 0
	v_cndmask_b32_e32 v2, v2, v3, vcc
	v_add_u32_e32 v3, 1, v1
	v_mad_u64_u32 v[0:1], s[4:5], v0, v2, v[0:1]
	s_add_u32 s4, s50, 0x3500
	s_addc_u32 s5, s51, 0
	v_cmp_ne_u32_e32 vcc, v3, v0
	v_mov_b64_e32 v[0:1], s[4:5]
	s_and_saveexec_b64 s[6:7], vcc
	s_cbranch_execz .LBB0_986
	v_mov_b64_e32 v[0:1], s[4:5]
	flat_load_dword v0, v[0:1] sc1
	s_mov_b64 s[12:13], 0
	s_waitcnt vmcnt(0) lgkmcnt(0)
	v_cmp_eq_u32_e32 vcc, v0, v2
	s_and_saveexec_b64 s[10:11], vcc
	s_cbranch_execz .LBB0_985
	s_add_u32 s8, s50, 0x200
	s_addc_u32 s9, s51, 0
	s_mov_b32 s25, 1
	s_branch .LBB0_978

.LBB0_991:
	s_waitcnt lgkmcnt(0)
	v_add_f32_e32 v13, v15, v71
	v_fmamk_f32 v13, v13, 0x3c000000, v215
	v_mul_f32_e32 v15, 0x4f800000, v13
	v_cmp_gt_f32_e32 vcc, s92, v13
	s_add_i32 s2, s2, s88
	s_cmpk_gt_i32 s2, 0x23ff
	v_cndmask_b32_e32 v13, v13, v15, vcc
	v_sqrt_f32_e32 v15, v13
	s_nop 0
	v_add_u32_e32 v71, -1, v15
	v_fma_f32 v73, -v71, v15, v13
	v_add_u32_e32 v72, 1, v15
	v_cmp_ge_f32_e64 s[4:5], 0, v73
	s_nop 1
	v_cndmask_b32_e64 v71, v15, v71, s[4:5]
	v_fma_f32 v15, -v72, v15, v13
	v_cmp_lt_f32_e64 s[4:5], 0, v15
	s_nop 1
	v_cndmask_b32_e64 v15, v71, v72, s[4:5]
	v_mul_f32_e32 v71, 0x37800000, v15
	v_cndmask_b32_e32 v15, v15, v71, vcc
	v_cmp_class_f32_e32 vcc, v13, v216
	s_nop 1
	v_cndmask_b32_e32 v13, v15, v13, vcc
	v_div_scale_f32 v15, s[4:5], v13, v13, 1.0
	v_rcp_f32_e32 v71, v15
	s_nop 0
	v_fma_f32 v72, -v15, v71, 1.0
	v_fmac_f32_e32 v71, v72, v71
	v_div_scale_f32 v72, vcc, 1.0, v13, 1.0
	v_mul_f32_e32 v73, v72, v71
	v_fma_f32 v74, -v15, v73, v72
	v_fmac_f32_e32 v73, v74, v71
	v_fma_f32 v15, -v15, v73, v72
	v_div_fmas_f32 v15, v15, v71, v73
	v_div_fixup_f32 v72, v15, v13, 1.0
	v_pk_mul_f32 v[18:19], v[72:73], v[18:19] op_sel_hi:[0,1]
	s_waitcnt vmcnt(6)
	v_pk_mul_f32 v[18:19], v[18:19], v[46:47]
	v_pk_mul_f32 v[16:17], v[72:73], v[16:17] op_sel_hi:[0,1]
	v_pk_mul_f32 v[46:47], v[18:19], v[48:49] op_sel:[1,0] op_sel_hi:[0,1]
	v_pk_mul_f32 v[18:19], v[18:19], v[48:49]
	s_waitcnt vmcnt(4)
	v_pk_mul_f32 v[48:49], v[16:17], v[50:51]
	v_pk_mul_f32 v[16:17], v[72:73], v[26:27] op_sel_hi:[0,1]
	v_pk_mul_f32 v[2:3], v[72:73], v[2:3] op_sel_hi:[0,1]
	v_pk_mul_f32 v[16:17], v[16:17], v[24:25]
	v_pk_mul_f32 v[2:3], v[2:3], v[34:35]
	v_pk_mul_f32 v[24:25], v[16:17], v[32:33] op_sel:[1,0] op_sel_hi:[0,1]
	v_pk_mul_f32 v[26:27], v[2:3], v[28:29] op_sel:[1,0] op_sel_hi:[0,1]
	v_pk_mul_f32 v[6:7], v[72:73], v[6:7] op_sel_hi:[0,1]
	v_pk_mul_f32 v[4:5], v[72:73], v[4:5] op_sel_hi:[0,1]
	v_pk_mul_f32 v[16:17], v[16:17], v[32:33]
	v_mov_b32_e32 v32, v24
	v_mov_b32_e32 v33, v26
	v_mov_b32_e32 v26, v25
	v_pk_mul_f32 v[2:3], v[2:3], v[28:29]
	v_pk_mul_f32 v[6:7], v[6:7], v[40:41]
	v_pk_mul_f32 v[4:5], v[4:5], v[44:45]
	v_pk_add_f32 v[24:25], v[32:33], v[26:27] neg_lo:[0,1] neg_hi:[0,1]
	v_mov_b32_e32 v26, v16
	v_mov_b32_e32 v27, v2
	v_mov_b32_e32 v2, v17
	v_pk_mul_f32 v[40:41], v[6:7], v[42:43] op_sel:[1,0] op_sel_hi:[0,1]
	v_pk_add_f32 v[16:17], v[26:27], v[2:3]
	v_cvt_pk_bf16_f32 v2, v24, v25
	v_pk_mul_f32 v[24:25], v[4:5], v[30:31] op_sel:[1,0] op_sel_hi:[0,1]
	v_pk_mul_f32 v[6:7], v[6:7], v[42:43]
	v_mov_b32_e32 v26, v40
	v_mov_b32_e32 v27, v24
	v_mov_b32_e32 v24, v41
	v_pk_mul_f32 v[4:5], v[4:5], v[30:31]
	v_pk_add_f32 v[24:25], v[26:27], v[24:25] neg_lo:[0,1] neg_hi:[0,1]
	v_mov_b32_e32 v26, v6
	v_mov_b32_e32 v27, v4
	v_mov_b32_e32 v4, v7
	v_pk_add_f32 v[4:5], v[26:27], v[4:5]
	v_cvt_pk_bf16_f32 v16, v16, v17
	v_cvt_pk_bf16_f32 v17, v4, v5
	v_pk_mul_f32 v[4:5], v[48:49], v[36:37] op_sel:[1,0] op_sel_hi:[0,1]
	v_mov_b32_e32 v6, v46
	v_mov_b32_e32 v7, v4
	v_mov_b32_e32 v4, v47
	v_pk_add_f32 v[4:5], v[6:7], v[4:5] neg_lo:[0,1] neg_hi:[0,1]
	v_pk_mul_f32 v[6:7], v[48:49], v[36:37]
	v_pk_mul_f32 v[22:23], v[72:73], v[22:23] op_sel_hi:[0,1]
	v_pk_mul_f32 v[20:21], v[72:73], v[20:21] op_sel_hi:[0,1]
	v_cvt_pk_bf16_f32 v3, v24, v25
	v_mov_b32_e32 v24, v18
	v_mov_b32_e32 v25, v6
	v_mov_b32_e32 v6, v19
	s_waitcnt vmcnt(2)
	v_pk_mul_f32 v[22:23], v[22:23], v[52:53]
	s_waitcnt vmcnt(0)
	v_pk_mul_f32 v[20:21], v[20:21], v[56:57]
	v_pk_add_f32 v[6:7], v[24:25], v[6:7]
	v_pk_mul_f32 v[52:53], v[22:23], v[54:55] op_sel:[1,0] op_sel_hi:[0,1]
	v_cvt_pk_bf16_f32 v18, v6, v7
	v_pk_mul_f32 v[6:7], v[20:21], v[38:39] op_sel:[1,0] op_sel_hi:[0,1]
	v_pk_mul_f32 v[22:23], v[22:23], v[54:55]
	v_mov_b32_e32 v24, v52
	v_mov_b32_e32 v25, v6
	v_mov_b32_e32 v6, v53
	v_pk_mul_f32 v[20:21], v[20:21], v[38:39]
	v_pk_add_f32 v[6:7], v[24:25], v[6:7] neg_lo:[0,1] neg_hi:[0,1]
	v_mov_b32_e32 v24, v22
	v_mov_b32_e32 v25, v20
	v_mov_b32_e32 v20, v23
	v_pk_add_f32 v[20:21], v[24:25], v[20:21]
	v_cvt_pk_bf16_f32 v4, v4, v5
	v_cvt_pk_bf16_f32 v5, v6, v7
	v_cvt_pk_bf16_f32 v19, v20, v21
	global_store_dwordx4 v[0:1], v[2:5], off sc1
	global_store_dwordx4 v[0:1], v[16:19], off offset:64 sc1
	s_cbranch_scc1 .LBB0_1012

.LBB0_994:
	v_and_b32_e32 v0, 2, v15
	v_cmp_eq_u32_e32 vcc, 0, v0
	global_load_dwordx4 v[4:7], v[16:17], off
	global_load_dwordx4 v[0:3], v[16:17], off offset:32
	v_and_b32_e32 v23, 8, v13
	v_cvt_f32_ubyte0_e32 v18, v23
	v_mul_f32_e32 v18, 0xbf549a78, v18
	v_exp_f32_e32 v18, v18
	v_cndmask_b32_e32 v22, v25, v24, vcc
	s_mov_b64 s[12:13], 0x800
	v_cmp_lt_u32_e32 vcc, 31, v15
	v_mul_f32_e32 v18, 0.15915494, v18
	v_mul_f32_e32 v19, v22, v18
	v_floor_f32_e32 v19, v19
	v_fma_f32 v19, v22, v18, -v19
	v_sin_f32_e32 v18, v19
	v_cos_f32_e32 v20, v19
	v_or_b32_e32 v19, 1, v23
	v_cvt_f32_ubyte0_e32 v19, v19
	v_mul_f32_e32 v19, 0xbf549a78, v19
	v_exp_f32_e32 v19, v19
	v_add_u32_e32 v13, 0x200, v13
	s_or_b64 s[10:11], vcc, s[10:11]
	v_mul_f32_e32 v19, 0.15915494, v19
	v_mul_f32_e32 v21, v22, v19
	v_floor_f32_e32 v21, v21
	v_fma_f32 v21, v22, v19, -v21
	v_sin_f32_e32 v19, v21
	v_cos_f32_e32 v21, v21
	s_waitcnt vmcnt(0)
	v_lshlrev_b32_e32 v26, 16, v4
	v_lshlrev_b32_e32 v28, 16, v0
	v_and_b32_e32 v29, 0xffff0000, v0
	v_and_b32_e32 v27, 0xffff0000, v4
	v_pk_mul_f32 v[30:31], v[20:21], v[28:29]
	s_nop 0
	v_pk_fma_f32 v[30:31], v[18:19], v[26:27], v[30:31]
	v_pk_mul_f32 v[18:19], v[18:19], v[28:29]
	v_lshlrev_b32_e32 v28, 16, v1
	v_pk_fma_f32 v[18:19], v[20:21], v[26:27], v[18:19] neg_lo:[0,0,1] neg_hi:[0,0,1]
	v_and_b32_e32 v29, 0xffff0000, v1
	v_cvt_pk_bf16_f32 v4, v18, v19
	v_or_b32_e32 v18, 2, v23
	v_cvt_f32_ubyte0_e32 v18, v18
	v_mul_f32_e32 v18, 0xbf549a78, v18
	v_exp_f32_e32 v18, v18
	v_cvt_pk_bf16_f32 v0, v30, v31
	v_lshlrev_b32_e32 v26, 16, v5
	v_and_b32_e32 v27, 0xffff0000, v5
	v_mul_f32_e32 v18, 0.15915494, v18
	v_mul_f32_e32 v19, v22, v18
	v_floor_f32_e32 v19, v19
	v_fma_f32 v19, v22, v18, -v19
	v_sin_f32_e32 v18, v19
	v_cos_f32_e32 v20, v19
	v_or_b32_e32 v19, 3, v23
	v_cvt_f32_ubyte0_e32 v19, v19
	v_mul_f32_e32 v19, 0xbf549a78, v19
	v_exp_f32_e32 v19, v19
	s_nop 0
	v_mul_f32_e32 v19, 0.15915494, v19
	v_mul_f32_e32 v21, v22, v19
	v_floor_f32_e32 v21, v21
	v_fma_f32 v21, v22, v19, -v21
	v_sin_f32_e32 v19, v21
	v_cos_f32_e32 v21, v21
	s_nop 0
	v_pk_mul_f32 v[30:31], v[20:21], v[28:29]
	s_nop 0
	v_pk_fma_f32 v[30:31], v[18:19], v[26:27], v[30:31]
	v_pk_mul_f32 v[18:19], v[18:19], v[28:29]
	v_lshlrev_b32_e32 v28, 16, v2
	v_pk_fma_f32 v[18:19], v[20:21], v[26:27], v[18:19] neg_lo:[0,0,1] neg_hi:[0,0,1]
	v_and_b32_e32 v29, 0xffff0000, v2
	v_cvt_pk_bf16_f32 v5, v18, v19
	v_or_b32_e32 v18, 4, v23
	v_cvt_f32_ubyte0_e32 v18, v18
	v_mul_f32_e32 v18, 0xbf549a78, v18
	v_exp_f32_e32 v18, v18
	v_cvt_pk_bf16_f32 v1, v30, v31
	v_lshlrev_b32_e32 v26, 16, v6
	v_and_b32_e32 v27, 0xffff0000, v6
	v_mul_f32_e32 v18, 0.15915494, v18
	v_mul_f32_e32 v19, v22, v18
	v_floor_f32_e32 v19, v19
	v_fma_f32 v19, v22, v18, -v19
	v_sin_f32_e32 v18, v19
	v_cos_f32_e32 v20, v19
	v_or_b32_e32 v19, 5, v23
	v_cvt_f32_ubyte0_e32 v19, v19
	v_mul_f32_e32 v19, 0xbf549a78, v19
	v_exp_f32_e32 v19, v19
	s_nop 0
	v_mul_f32_e32 v19, 0.15915494, v19
	v_mul_f32_e32 v21, v22, v19
	v_floor_f32_e32 v21, v21
	v_fma_f32 v21, v22, v19, -v21
	v_sin_f32_e32 v19, v21
	v_cos_f32_e32 v21, v21
	s_nop 0
	v_pk_mul_f32 v[30:31], v[20:21], v[28:29]
	s_nop 0
	v_pk_fma_f32 v[30:31], v[18:19], v[26:27], v[30:31]
	v_pk_mul_f32 v[18:19], v[18:19], v[28:29]
	v_cvt_pk_bf16_f32 v2, v30, v31
	v_pk_fma_f32 v[18:19], v[20:21], v[26:27], v[18:19] neg_lo:[0,0,1] neg_hi:[0,0,1]
	v_lshlrev_b32_e32 v26, 16, v3
	v_cvt_pk_bf16_f32 v6, v18, v19
	v_or_b32_e32 v18, 6, v23
	v_cvt_f32_ubyte0_e32 v18, v18
	v_mul_f32_e32 v18, 0xbf549a78, v18
	v_exp_f32_e32 v18, v18
	v_and_b32_e32 v27, 0xffff0000, v3
	v_mul_f32_e32 v18, 0.15915494, v18
	v_mul_f32_e32 v19, v22, v18
	v_floor_f32_e32 v19, v19
	v_fma_f32 v19, v22, v18, -v19
	v_sin_f32_e32 v18, v19
	v_cos_f32_e32 v20, v19
	v_or_b32_e32 v19, 7, v23
	v_cvt_f32_ubyte0_e32 v19, v19
	v_mul_f32_e32 v19, 0xbf549a78, v19
	v_exp_f32_e32 v19, v19
	v_and_b32_e32 v23, 0xffff0000, v7
	v_mul_f32_e32 v19, 0.15915494, v19
	v_mul_f32_e32 v21, v22, v19
	v_floor_f32_e32 v21, v21
	v_fma_f32 v21, v22, v19, -v21
	v_sin_f32_e32 v19, v21
	v_cos_f32_e32 v21, v21
	v_lshlrev_b32_e32 v22, 16, v7
	v_pk_mul_f32 v[28:29], v[20:21], v[26:27]
	s_nop 0
	v_pk_fma_f32 v[28:29], v[18:19], v[22:23], v[28:29]
	v_pk_mul_f32 v[18:19], v[18:19], v[26:27]
	v_cvt_pk_bf16_f32 v3, v28, v29
	v_pk_fma_f32 v[18:19], v[20:21], v[22:23], v[18:19] neg_lo:[0,0,1] neg_hi:[0,0,1]
	s_nop 0
	v_cvt_pk_bf16_f32 v7, v18, v19
	global_store_dwordx4 v[16:17], v[4:7], off sc1
	global_store_dwordx4 v[16:17], v[0:3], off offset:32 sc1
	v_lshl_add_u64 v[16:17], v[16:17], 0, s[12:13]
	s_nop 0
	v_add_u32_e32 v0, 64, v15
	v_mov_b32_e32 v15, v0
	s_andn2_b64 exec, exec, s[10:11]
	s_cbranch_execnz .LBB0_994
	s_or_b64 exec, exec, s[10:11]

.LBB0_1264:
	s_mul_hi_i32 s7, s16, 0x38e38e39
	s_lshr_b32 s9, s7, 31
	s_ashr_i32 s7, s7, 1
	v_mov_b32_e32 v128, v159
	v_mov_b32_e32 v152, v158
	s_add_i32 s22, s7, s9
	s_lshl_b32 s7, s20, 8
	s_or_b32 s7, s7, s95
	v_lshl_add_u32 v128, v128, 2, s7
	v_ashrrev_i32_e32 v129, 31, v128
	s_cmp_eq_u32 s21, 0
	v_lshlrev_b64 v[150:151], 2, v[128:129]
	s_mov_b32 s96, s74
	s_cbranch_scc1 .LBB0_1266
	s_lshl_b32 s9, s17, 10
	s_lshl_b32 s7, s22, 8
	s_add_i32 s9, s9, s94
	s_add_i32 s9, s9, s7
	v_add_u32_e32 v128, s9, v152
	v_ashrrev_i32_e32 v129, 31, v128
	v_readlane_b32 s20, v253, 62
	v_lshlrev_b64 v[130:131], 13, v[128:129]
	v_readlane_b32 s21, v253, 63
	s_nop 1
	v_lshl_add_u64 v[130:131], s[20:21], 0, v[130:131]
	v_lshl_add_u64 v[130:131], v[130:131], 0, v[150:151]
	global_store_dwordx4 v[130:131], v[124:127], off sc1
	global_store_dwordx4 v[130:131], v[120:123], off offset:64 sc1
	global_store_dwordx4 v[130:131], v[116:119], off offset:512 sc1
	global_store_dwordx4 v[130:131], v[104:107], off offset:576 sc1
	v_add_u32_e32 v130, 16, v128
	v_ashrrev_i32_e32 v131, 31, v130
	v_lshlrev_b64 v[130:131], 13, v[130:131]
	v_lshl_add_u64 v[130:131], s[20:21], 0, v[130:131]
	v_lshl_add_u64 v[130:131], v[130:131], 0, v[150:151]
	global_store_dwordx4 v[130:131], v[112:115], off sc1
	global_store_dwordx4 v[130:131], v[108:111], off offset:64 sc1
	global_store_dwordx4 v[130:131], v[96:99], off offset:512 sc1
	global_store_dwordx4 v[130:131], v[88:91], off offset:576 sc1
	v_add_u32_e32 v130, 32, v128
	v_ashrrev_i32_e32 v131, 31, v130
	v_lshlrev_b64 v[130:131], 13, v[130:131]
	v_lshl_add_u64 v[130:131], s[20:21], 0, v[130:131]
	v_lshl_add_u64 v[130:131], v[130:131], 0, v[150:151]
	global_store_dwordx4 v[130:131], v[100:103], off sc1
	global_store_dwordx4 v[130:131], v[92:95], off offset:64 sc1
	global_store_dwordx4 v[130:131], v[80:83], off offset:512 sc1
	global_store_dwordx4 v[130:131], v[72:75], off offset:576 sc1
	v_add_u32_e32 v130, 48, v128
	v_ashrrev_i32_e32 v131, 31, v130
	v_lshlrev_b64 v[130:131], 13, v[130:131]
	v_lshl_add_u64 v[130:131], s[20:21], 0, v[130:131]
	v_lshl_add_u64 v[130:131], v[130:131], 0, v[150:151]
	global_store_dwordx4 v[130:131], v[84:87], off sc1
	global_store_dwordx4 v[130:131], v[76:79], off offset:64 sc1
	global_store_dwordx4 v[130:131], v[68:71], off offset:512 sc1
	global_store_dwordx4 v[130:131], v[64:67], off offset:576 sc1
	v_add_u32_e32 v130, 0x80, v128
	v_ashrrev_i32_e32 v131, 31, v130
	v_lshlrev_b64 v[130:131], 13, v[130:131]
	v_lshl_add_u64 v[130:131], s[20:21], 0, v[130:131]
	v_lshl_add_u64 v[130:131], v[130:131], 0, v[150:151]
	global_store_dwordx4 v[130:131], v[60:63], off sc1
	global_store_dwordx4 v[130:131], v[56:59], off offset:64 sc1
	global_store_dwordx4 v[130:131], v[48:51], off offset:512 sc1
	global_store_dwordx4 v[130:131], v[40:43], off offset:576 sc1
	v_add_u32_e32 v130, 0x90, v128
	v_ashrrev_i32_e32 v131, 31, v130
	v_lshlrev_b64 v[130:131], 13, v[130:131]
	v_lshl_add_u64 v[130:131], s[20:21], 0, v[130:131]
	v_lshl_add_u64 v[130:131], v[130:131], 0, v[150:151]
	global_store_dwordx4 v[130:131], v[52:55], off sc1
	global_store_dwordx4 v[130:131], v[44:47], off offset:64 sc1
	global_store_dwordx4 v[130:131], v[32:35], off offset:512 sc1
	global_store_dwordx4 v[130:131], v[24:27], off offset:576 sc1
	v_add_u32_e32 v130, 0xa0, v128
	v_add_u32_e32 v128, 0xb0, v128
	v_ashrrev_i32_e32 v131, 31, v130
	v_ashrrev_i32_e32 v129, 31, v128
	v_lshlrev_b64 v[130:131], 13, v[130:131]
	v_lshlrev_b64 v[128:129], 13, v[128:129]
	v_lshl_add_u64 v[130:131], s[20:21], 0, v[130:131]
	v_lshl_add_u64 v[128:129], s[20:21], 0, v[128:129]
	v_lshl_add_u64 v[130:131], v[130:131], 0, v[150:151]
	v_lshl_add_u64 v[128:129], v[128:129], 0, v[150:151]
	s_mov_b64 s[20:21], 0
	global_store_dwordx4 v[130:131], v[36:39], off sc1
	global_store_dwordx4 v[130:131], v[28:31], off offset:64 sc1
	global_store_dwordx4 v[130:131], v[20:23], off offset:512 sc1
	global_store_dwordx4 v[130:131], v[12:15], off offset:576 sc1
	global_store_dwordx4 v[128:129], v[16:19], off sc1
	global_store_dwordx4 v[128:129], v[8:11], off offset:64 sc1
	global_store_dwordx4 v[128:129], v[4:7], off offset:512 sc1
	global_store_dwordx4 v[128:129], v[0:3], off offset:576 sc1
	s_branch .LBB0_1267

.LBB0_1267:
	v_readlane_b32 s88, v254, 50
	v_readlane_b32 s89, v254, 51
	s_andn2_b64 vcc, exec, s[20:21]
	s_cbranch_vccnz .LBB0_1269
	s_mul_i32 s7, s22, 9
	s_cmp_eq_u32 s16, s7
	s_cselect_b64 s[20:21], -1, 0
	s_and_b64 s[24:25], s[20:21], exec
	s_cselect_b32 s9, 4, s22
	s_mul_hi_i32 s11, s9, 0xc000
	s_mul_i32 s9, s9, 0xc000
	s_add_u32 s24, s73, s9
	s_addc_u32 s25, s92, s11
	s_not_b32 s7, s7
	s_add_i32 s7, s16, s7
	s_ashr_i32 s23, s22, 31
	s_lshl_b32 s7, s7, 8
	v_lshl_add_u64 v[140:141], s[24:25], 0, v[150:151]
	s_lshl_b64 s[24:25], s[22:23], 11
	s_ashr_i32 s9, s7, 31
	s_add_u32 s11, s24, s7
	s_addc_u32 s9, s25, s9
	s_lshl_b64 s[22:23], s[22:23], 21
	s_lshl_b32 s7, s16, 8
	s_add_u32 s22, s85, s22
	v_add_u32_e32 v152, s94, v152
	s_addc_u32 s23, s84, s23
	v_add_u32_e32 v156, s7, v152
	s_and_b64 s[16:17], s[20:21], exec
	v_readlane_b32 s24, v253, 50
	v_ashrrev_i32_e32 v157, 31, v156
	v_ashrrev_i32_e32 v153, 31, v152
	s_cselect_b32 s17, 0, s9
	s_cselect_b32 s16, 0, s11
	s_cselect_b32 s21, s23, s82
	s_cselect_b32 s20, s22, s83
	v_readlane_b32 s25, v253, 51
	v_lshlrev_b64 v[174:175], 13, v[156:157]
	v_lshl_add_u64 v[164:165], s[16:17], 0, v[152:153]
	v_lshl_add_u64 v[156:157], s[20:21], 0, v[150:151]
	s_cselect_b32 s21, s84, s82
	s_cselect_b32 s20, s85, s83
	v_add_u32_e32 v182, 16, v152
	v_lshl_add_u64 v[154:155], s[24:25], 0, v[150:151]
	s_cmp_eq_u64 s[20:21], 0
	v_lshlrev_b64 v[164:165], 13, v[164:165]
	v_add_u32_e32 v184, s7, v182
	v_ashrrev_i32_e32 v183, 31, v182
	v_lshl_add_u64 v[162:163], v[154:155], 0, v[174:175]
	v_lshl_add_u64 v[164:165], v[156:157], 0, v[164:165]
	s_cselect_b64 vcc, -1, 0
	v_ashrrev_i32_e32 v185, 31, v184
	v_lshl_add_u64 v[182:183], s[16:17], 0, v[182:183]
	v_add_u32_e32 v198, 32, v152
	v_cndmask_b32_e32 v179, v165, v163, vcc
	v_cndmask_b32_e32 v178, v164, v162, vcc
	v_lshlrev_b64 v[224:225], 13, v[184:185]
	v_lshlrev_b64 v[182:183], 13, v[182:183]
	v_add_u32_e32 v200, s7, v198
	v_ashrrev_i32_e32 v199, 31, v198
	global_load_dwordx4 v[128:131], v[140:141], off offset:576
	global_load_dwordx4 v[132:135], v[140:141], off offset:512
	global_load_dwordx4 v[136:139], v[140:141], off offset:64
	s_nop 0
	global_load_dwordx4 v[140:143], v[140:141], off
	s_nop 0
	global_load_dwordx4 v[162:165], v[178:179], off
	global_load_dwordx4 v[166:169], v[178:179], off offset:64
	global_load_dwordx4 v[170:173], v[178:179], off offset:512
	s_nop 0
	global_load_dwordx4 v[178:181], v[178:179], off offset:576
	v_lshl_add_u64 v[184:185], v[154:155], 0, v[224:225]
	v_lshl_add_u64 v[182:183], v[156:157], 0, v[182:183]
	v_ashrrev_i32_e32 v201, 31, v200
	v_lshl_add_u64 v[198:199], s[16:17], 0, v[198:199]
	v_add_u32_e32 v220, 48, v152
	v_cndmask_b32_e32 v195, v183, v185, vcc
	v_cndmask_b32_e32 v194, v182, v184, vcc
	v_lshlrev_b64 v[250:251], 13, v[200:201]
	v_lshlrev_b64 v[198:199], 13, v[198:199]
	v_add_u32_e32 v222, s7, v220
	v_ashrrev_i32_e32 v221, 31, v220
	global_load_dwordx4 v[182:185], v[194:195], off
	global_load_dwordx4 v[186:189], v[194:195], off offset:64
	global_load_dwordx4 v[190:193], v[194:195], off offset:512
	s_nop 0
	global_load_dwordx4 v[194:197], v[194:195], off offset:576
	v_lshl_add_u64 v[200:201], v[154:155], 0, v[250:251]
	v_lshl_add_u64 v[198:199], v[156:157], 0, v[198:199]
	v_ashrrev_i32_e32 v223, 31, v222
	v_lshl_add_u64 v[220:221], s[16:17], 0, v[220:221]
	v_cndmask_b32_e32 v211, v199, v201, vcc
	v_cndmask_b32_e32 v210, v198, v200, vcc
	v_lshlrev_b64 v[228:229], 13, v[222:223]
	v_lshlrev_b64 v[220:221], 13, v[220:221]
	global_load_dwordx4 v[198:201], v[210:211], off
	global_load_dwordx4 v[202:205], v[210:211], off offset:64
	global_load_dwordx4 v[206:209], v[210:211], off offset:512
	s_nop 0
	global_load_dwordx4 v[210:213], v[210:211], off offset:576
	v_lshl_add_u64 v[222:223], v[154:155], 0, v[228:229]
	v_lshl_add_u64 v[220:221], v[156:157], 0, v[220:221]
	v_cndmask_b32_e32 v221, v221, v223, vcc
	v_cndmask_b32_e32 v220, v220, v222, vcc
	global_load_dwordx4 v[238:241], v[220:221], off
	global_load_dwordx4 v[242:245], v[220:221], off offset:64
	global_load_dwordx4 v[246:249], v[220:221], off offset:512
	s_nop 0
	global_load_dwordx4 v[220:223], v[220:221], off offset:576
	v_lshl_add_u64 v[174:175], s[24:25], 0, v[174:175]
	v_lshl_add_u64 v[174:175], v[174:175], 0, v[150:151]
	s_waitcnt vmcnt(0)
	v_pk_fma_f32 v[122:123], v[122:123], v[138:139], v[168:169]
	v_pk_fma_f32 v[118:119], v[118:119], v[134:135], v[172:173]
	v_pk_fma_f32 v[106:107], v[106:107], v[130:131], v[180:181]
	v_pk_fma_f32 v[104:105], v[104:105], v[128:129], v[178:179]
	v_pk_fma_f32 v[116:117], v[116:117], v[132:133], v[170:171]
	global_store_dwordx4 v[174:175], v[104:107], off offset:576 sc1
	global_store_dwordx4 v[174:175], v[116:119], off offset:512 sc1
	v_pk_fma_f32 v[126:127], v[126:127], v[142:143], v[164:165]
	v_lshl_add_u64 v[104:105], s[24:25], 0, v[224:225]
	v_lshl_add_u64 v[116:117], v[104:105], 0, v[150:151]
	v_pk_fma_f32 v[124:125], v[124:125], v[140:141], v[162:163]
	v_pk_fma_f32 v[106:107], v[114:115], v[142:143], v[184:185]
	v_pk_fma_f32 v[104:105], v[112:113], v[140:141], v[182:183]
	v_pk_fma_f32 v[98:99], v[98:99], v[134:135], v[192:193]
	v_pk_fma_f32 v[90:91], v[90:91], v[130:131], v[196:197]
	v_pk_fma_f32 v[88:89], v[88:89], v[128:129], v[194:195]
	v_pk_fma_f32 v[96:97], v[96:97], v[132:133], v[190:191]
	global_store_dwordx4 v[116:117], v[88:91], off offset:576 sc1
	global_store_dwordx4 v[116:117], v[96:99], off offset:512 sc1
	v_pk_fma_f32 v[120:121], v[120:121], v[136:137], v[166:167]
	v_lshl_add_u64 v[88:89], s[24:25], 0, v[250:251]
	v_lshl_add_u64 v[96:97], v[88:89], 0, v[150:151]
	v_pk_fma_f32 v[82:83], v[82:83], v[134:135], v[208:209]
	v_pk_fma_f32 v[74:75], v[74:75], v[130:131], v[212:213]
	v_pk_fma_f32 v[72:73], v[72:73], v[128:129], v[210:211]
	v_pk_fma_f32 v[80:81], v[80:81], v[132:133], v[206:207]
	global_store_dwordx4 v[96:97], v[72:75], off offset:576 sc1
	global_store_dwordx4 v[96:97], v[80:83], off offset:512 sc1
	v_pk_fma_f32 v[66:67], v[66:67], v[130:131], v[222:223]
	v_lshl_add_u64 v[72:73], s[24:25], 0, v[228:229]
	v_lshl_add_u64 v[80:81], v[72:73], 0, v[150:151]
	v_pk_fma_f32 v[64:65], v[64:65], v[128:129], v[220:221]
	v_pk_fma_f32 v[74:75], v[86:87], v[142:143], v[240:241]
	v_pk_fma_f32 v[72:73], v[84:85], v[140:141], v[238:239]
	global_store_dwordx4 v[80:81], v[64:67], off offset:576 sc1
	global_store_dwordx4 v[80:81], v[72:75], off sc1
	v_pk_fma_f32 v[70:71], v[70:71], v[134:135], v[248:249]
	v_add_u32_e32 v64, 0x80, v152
	v_pk_fma_f32 v[74:75], v[78:79], v[138:139], v[244:245]
	v_pk_fma_f32 v[72:73], v[76:77], v[136:137], v[242:243]
	v_pk_fma_f32 v[68:69], v[68:69], v[132:133], v[246:247]
	v_add_u32_e32 v66, s7, v64
	v_ashrrev_i32_e32 v65, 31, v64
	v_pk_fma_f32 v[90:91], v[102:103], v[142:143], v[200:201]
	v_pk_fma_f32 v[88:89], v[100:101], v[140:141], v[198:199]
	global_store_dwordx4 v[80:81], v[72:75], off offset:64 sc1
	global_store_dwordx4 v[80:81], v[68:71], off offset:512 sc1
	v_ashrrev_i32_e32 v67, 31, v66
	v_lshl_add_u64 v[64:65], s[16:17], 0, v[64:65]
	v_add_u32_e32 v80, 0x90, v152
	global_store_dwordx4 v[116:117], v[104:107], off sc1
	global_store_dwordx4 v[96:97], v[88:91], off sc1
	v_lshlrev_b64 v[162:163], 13, v[66:67]
	v_pk_fma_f32 v[106:107], v[110:111], v[138:139], v[188:189]
	v_pk_fma_f32 v[104:105], v[108:109], v[136:137], v[186:187]
	v_pk_fma_f32 v[90:91], v[94:95], v[138:139], v[204:205]
	v_pk_fma_f32 v[88:89], v[92:93], v[136:137], v[202:203]
	v_lshlrev_b64 v[64:65], 13, v[64:65]
	v_add_u32_e32 v82, s7, v80
	v_ashrrev_i32_e32 v81, 31, v80
	global_store_dwordx4 v[174:175], v[124:127], off sc1
	global_store_dwordx4 v[174:175], v[120:123], off offset:64 sc1
	global_store_dwordx4 v[116:117], v[104:107], off offset:64 sc1
	global_store_dwordx4 v[96:97], v[88:91], off offset:64 sc1
	v_lshl_add_u64 v[66:67], v[154:155], 0, v[162:163]
	v_lshl_add_u64 v[64:65], v[156:157], 0, v[64:65]
	v_ashrrev_i32_e32 v83, 31, v82
	v_lshl_add_u64 v[80:81], s[16:17], 0, v[80:81]
	v_add_u32_e32 v96, 0xa0, v152
	v_cndmask_b32_e32 v77, v65, v67, vcc
	v_cndmask_b32_e32 v76, v64, v66, vcc
	v_lshlrev_b64 v[164:165], 13, v[82:83]
	v_lshlrev_b64 v[80:81], 13, v[80:81]
	v_add_u32_e32 v98, s7, v96
	v_ashrrev_i32_e32 v97, 31, v96
	global_load_dwordx4 v[64:67], v[76:77], off
	global_load_dwordx4 v[68:71], v[76:77], off offset:64
	global_load_dwordx4 v[72:75], v[76:77], off offset:512
	s_nop 0
	global_load_dwordx4 v[76:79], v[76:77], off offset:576
	v_lshl_add_u64 v[82:83], v[154:155], 0, v[164:165]
	v_lshl_add_u64 v[80:81], v[156:157], 0, v[80:81]
	v_ashrrev_i32_e32 v99, 31, v98
	v_lshl_add_u64 v[96:97], s[16:17], 0, v[96:97]
	v_add_u32_e32 v112, 0xb0, v152
	v_cndmask_b32_e32 v93, v81, v83, vcc
	v_cndmask_b32_e32 v92, v80, v82, vcc
	v_lshlrev_b64 v[166:167], 13, v[98:99]
	v_lshlrev_b64 v[96:97], 13, v[96:97]
	v_add_u32_e32 v114, s7, v112
	v_ashrrev_i32_e32 v113, 31, v112
	global_load_dwordx4 v[80:83], v[92:93], off
	global_load_dwordx4 v[84:87], v[92:93], off offset:64
	global_load_dwordx4 v[88:91], v[92:93], off offset:512
	s_nop 0
	global_load_dwordx4 v[92:95], v[92:93], off offset:576
	v_lshl_add_u64 v[98:99], v[154:155], 0, v[166:167]
	v_lshl_add_u64 v[96:97], v[156:157], 0, v[96:97]
	v_ashrrev_i32_e32 v115, 31, v114
	v_lshl_add_u64 v[112:113], s[16:17], 0, v[112:113]
	v_cndmask_b32_e32 v109, v97, v99, vcc
	v_cndmask_b32_e32 v108, v96, v98, vcc
	v_lshlrev_b64 v[152:153], 13, v[114:115]
	v_lshlrev_b64 v[112:113], 13, v[112:113]
	global_load_dwordx4 v[96:99], v[108:109], off
	global_load_dwordx4 v[100:103], v[108:109], off offset:64
	global_load_dwordx4 v[104:107], v[108:109], off offset:512
	s_nop 0
	global_load_dwordx4 v[108:111], v[108:109], off offset:576
	v_lshl_add_u64 v[114:115], v[154:155], 0, v[152:153]
	v_lshl_add_u64 v[112:113], v[156:157], 0, v[112:113]
	v_cndmask_b32_e32 v125, v113, v115, vcc
	v_cndmask_b32_e32 v124, v112, v114, vcc
	global_load_dwordx4 v[112:115], v[124:125], off
	global_load_dwordx4 v[116:119], v[124:125], off offset:64
	global_load_dwordx4 v[120:123], v[124:125], off offset:512
	s_nop 0
	global_load_dwordx4 v[124:127], v[124:125], off offset:576
	v_lshl_add_u64 v[154:155], s[24:25], 0, v[162:163]
	v_lshl_add_u64 v[154:155], v[154:155], 0, v[150:151]
	s_waitcnt vmcnt(15)
	v_pk_fma_f32 v[62:63], v[62:63], v[142:143], v[66:67]
	v_pk_fma_f32 v[60:61], v[60:61], v[140:141], v[64:65]
	s_waitcnt vmcnt(13)
	v_pk_fma_f32 v[50:51], v[50:51], v[134:135], v[74:75]
	s_waitcnt vmcnt(12)
	v_pk_fma_f32 v[42:43], v[42:43], v[130:131], v[78:79]
	v_pk_fma_f32 v[40:41], v[40:41], v[128:129], v[76:77]
	v_pk_fma_f32 v[48:49], v[48:49], v[132:133], v[72:73]
	global_store_dwordx4 v[154:155], v[40:43], off offset:576 sc1
	global_store_dwordx4 v[154:155], v[48:51], off offset:512 sc1
	v_pk_fma_f32 v[58:59], v[58:59], v[138:139], v[70:71]
	v_lshl_add_u64 v[40:41], s[24:25], 0, v[164:165]
	v_lshl_add_u64 v[48:49], v[40:41], 0, v[150:151]
	v_pk_fma_f32 v[56:57], v[56:57], v[136:137], v[68:69]
	s_waitcnt vmcnt(13)
	v_pk_fma_f32 v[42:43], v[54:55], v[142:143], v[82:83]
	v_pk_fma_f32 v[40:41], v[52:53], v[140:141], v[80:81]
	s_waitcnt vmcnt(11)
	v_pk_fma_f32 v[34:35], v[34:35], v[134:135], v[90:91]
	s_waitcnt vmcnt(10)
	v_pk_fma_f32 v[26:27], v[26:27], v[130:131], v[94:95]
	v_pk_fma_f32 v[24:25], v[24:25], v[128:129], v[92:93]
	v_pk_fma_f32 v[32:33], v[32:33], v[132:133], v[88:89]
	global_store_dwordx4 v[48:49], v[24:27], off offset:576 sc1
	global_store_dwordx4 v[48:49], v[32:35], off offset:512 sc1
	global_store_dwordx4 v[48:49], v[40:43], off sc1
	v_lshl_add_u64 v[24:25], s[24:25], 0, v[166:167]
	v_lshl_add_u64 v[32:33], v[24:25], 0, v[150:151]
	s_waitcnt vmcnt(12)
	v_pk_fma_f32 v[26:27], v[38:39], v[142:143], v[98:99]
	s_waitcnt vmcnt(9)
	v_pk_fma_f32 v[14:15], v[14:15], v[130:131], v[110:111]
	v_pk_fma_f32 v[12:13], v[12:13], v[128:129], v[108:109]
	v_pk_fma_f32 v[24:25], v[36:37], v[140:141], v[96:97]
	v_pk_fma_f32 v[22:23], v[22:23], v[134:135], v[106:107]
	v_pk_fma_f32 v[20:21], v[20:21], v[132:133], v[104:105]
	global_store_dwordx4 v[32:33], v[12:15], off offset:576 sc1
	v_pk_fma_f32 v[42:43], v[46:47], v[138:139], v[86:87]
	v_pk_fma_f32 v[40:41], v[44:45], v[136:137], v[84:85]
	v_lshl_add_u64 v[12:13], s[24:25], 0, v[152:153]
	global_store_dwordx4 v[32:33], v[24:27], off sc1
	global_store_dwordx4 v[32:33], v[20:23], off offset:512 sc1
	s_waitcnt vmcnt(11)
	v_pk_fma_f32 v[14:15], v[18:19], v[142:143], v[114:115]
	v_pk_fma_f32 v[26:27], v[30:31], v[138:139], v[102:103]
	v_pk_fma_f32 v[24:25], v[28:29], v[136:137], v[100:101]
	v_lshl_add_u64 v[20:21], v[12:13], 0, v[150:151]
	v_pk_fma_f32 v[12:13], v[16:17], v[140:141], v[112:113]
	s_waitcnt vmcnt(10)
	v_pk_fma_f32 v[10:11], v[10:11], v[138:139], v[118:119]
	v_pk_fma_f32 v[8:9], v[8:9], v[136:137], v[116:117]
	s_waitcnt vmcnt(9)
	v_pk_fma_f32 v[6:7], v[6:7], v[134:135], v[122:123]
	v_pk_fma_f32 v[4:5], v[4:5], v[132:133], v[120:121]
	s_waitcnt vmcnt(8)
	v_pk_fma_f32 v[2:3], v[2:3], v[130:131], v[126:127]
	v_pk_fma_f32 v[0:1], v[0:1], v[128:129], v[124:125]
	global_store_dwordx4 v[154:155], v[60:63], off sc1
	global_store_dwordx4 v[154:155], v[56:59], off offset:64 sc1
	global_store_dwordx4 v[48:49], v[40:43], off offset:64 sc1
	global_store_dwordx4 v[32:33], v[24:27], off offset:64 sc1
	global_store_dwordx4 v[20:21], v[12:15], off sc1
	global_store_dwordx4 v[20:21], v[8:11], off offset:64 sc1
	global_store_dwordx4 v[20:21], v[4:7], off offset:512 sc1
	global_store_dwordx4 v[20:21], v[0:3], off offset:576 sc1

.LBB0_1302:
	s_andn2_saveexec_b64 s[4:5], s[4:5]
	s_cbranch_execz .LBB0_1318
	v_mov_b32_e32 v1, s56
	v_add_co_u32_e32 v2, vcc, 0x3000, v1
	v_mov_b32_e32 v1, s57
	s_waitcnt vmcnt(0)
	v_addc_co_u32_e32 v3, vcc, 0, v1, vcc
	flat_atomic_add v1, v[2:3], v217 offset:1024 sc0
	v_cvt_f32_u32_e32 v2, v0
	v_sub_u32_e32 v3, 0, v0
	s_mov_b64 s[8:9], -1
	v_rcp_iflag_f32_e32 v2, v2
	s_nop 0
	v_mul_f32_e32 v2, 0x4f7ffffe, v2
	v_cvt_u32_f32_e32 v2, v2
	v_mul_lo_u32 v3, v3, v2
	v_mul_hi_u32 v3, v2, v3
	v_add_u32_e32 v2, v2, v3
	s_waitcnt vmcnt(0) lgkmcnt(0)
	v_mul_hi_u32 v2, v1, v2
	v_mul_lo_u32 v3, v2, v0
	v_sub_u32_e32 v3, v1, v3
	v_cmp_ge_u32_e32 vcc, v3, v0
	v_add_u32_e32 v4, 1, v2
	s_nop 0
	v_cndmask_b32_e32 v2, v2, v4, vcc
	v_sub_u32_e32 v4, v3, v0
	v_cndmask_b32_e32 v3, v3, v4, vcc
	v_cmp_ge_u32_e32 vcc, v3, v0
	v_add_u32_e32 v3, 1, v2
	s_nop 0
	v_cndmask_b32_e32 v2, v2, v3, vcc
	v_add_u32_e32 v3, 1, v1
	v_mad_u64_u32 v[0:1], s[4:5], v0, v2, v[0:1]
	s_add_u32 s4, s56, 0x3500
	s_addc_u32 s5, s57, 0
	v_cmp_ne_u32_e32 vcc, v3, v0
	v_mov_b64_e32 v[0:1], s[4:5]
	s_and_saveexec_b64 s[6:7], vcc
	s_cbranch_execz .LBB0_1315
	v_mov_b64_e32 v[0:1], s[4:5]
	flat_load_dword v0, v[0:1] sc1
	s_mov_b64 s[12:13], 0
	s_waitcnt vmcnt(0) lgkmcnt(0)
	v_cmp_eq_u32_e32 vcc, v0, v2
	s_and_saveexec_b64 s[10:11], vcc
	s_cbranch_execz .LBB0_1314
	s_add_u32 s8, s56, 0x200
	s_addc_u32 s9, s57, 0
	s_mov_b32 s25, 1
	s_branch .LBB0_1307

.LBB0_1386:
	v_mov_b32_e32 v242, v238
	v_mov_b32_e32 v128, v239
	s_nop 0
	v_lshl_add_u32 v167, v128, 3, s33
	v_lshl_add_u32 v188, s6, 7, v167
	v_ashrrev_i32_e32 v189, 31, v188
	v_lshlrev_b64 v[128:129], 2, v[188:189]
	v_lshl_add_u64 v[212:213], s[54:55], 0, v[128:129]
	v_lshl_add_u64 v[208:209], s[20:21], 0, v[128:129]
	v_lshl_add_u64 v[206:207], s[2:3], 0, v[128:129]
	v_lshl_add_u64 v[210:211], s[18:19], 0, v[128:129]
	global_load_dwordx4 v[144:147], v[212:213], off
	global_load_dwordx4 v[148:151], v[210:211], off
	global_load_dwordx4 v[152:155], v[208:209], off
	global_load_dwordx4 v[156:159], v[206:207], off
	v_cmp_gt_i32_e32 vcc, 2, v242
	s_and_b64 s[10:11], s[16:17], vcc
	s_and_saveexec_b64 s[6:7], s[10:11]
	s_cbranch_execz .LBB0_1388
	v_readlane_b32 s10, v254, 0
	v_readlane_b32 s11, v254, 1
	v_lshl_add_u32 v130, s30, 2, v242
	v_cvt_pk_bf16_f32 v131, v86, v87
	v_mov_b64_e32 v[128:129], s[10:11]
	v_mad_i64_i32 v[128:129], s[10:11], v130, s43, v[128:129]
	v_lshl_add_u64 v[132:133], v[188:189], 1, v[128:129]
	v_cvt_pk_bf16_f32 v128, v116, v117
	v_cvt_pk_bf16_f32 v129, v118, v119
	v_cvt_pk_bf16_f32 v130, v84, v85
	global_store_dwordx4 v[132:133], v[128:131], off sc1
	v_add_co_u32_e32 v132, vcc, 0x2000, v132
	s_nop 0
	v_cvt_pk_bf16_f32 v128, v52, v53
	v_cvt_pk_bf16_f32 v129, v54, v55
	v_cvt_pk_bf16_f32 v130, v20, v21
	v_cvt_pk_bf16_f32 v131, v22, v23
	v_addc_co_u32_e32 v133, vcc, 0, v133, vcc
	global_store_dwordx4 v[132:133], v[128:131], off offset:3072 sc1
.LBB0_1388:
	s_or_b64 exec, exec, s[6:7]
	v_cmp_lt_i32_e32 vcc, 13, v242
	s_and_b64 s[10:11], s[14:15], vcc
	s_and_saveexec_b64 s[6:7], s[10:11]
	s_cbranch_execz .LBB0_1390
	s_lshl_b32 s10, s30, 2
	v_add3_u32 v130, s10, -12, v242
	v_readlane_b32 s10, v254, 0
	v_readlane_b32 s11, v254, 1
	v_cvt_pk_bf16_f32 v131, v66, v67
	s_nop 0
	v_mov_b64_e32 v[128:129], s[10:11]
	v_mad_i64_i32 v[128:129], s[10:11], v130, s43, v[128:129]
	v_lshl_add_u64 v[132:133], v[188:189], 1, v[128:129]
	v_cvt_pk_bf16_f32 v128, v88, v89
	v_cvt_pk_bf16_f32 v129, v90, v91
	v_cvt_pk_bf16_f32 v130, v64, v65
	global_store_dwordx4 v[132:133], v[128:131], off sc1
	v_add_co_u32_e32 v132, vcc, 0x2000, v132
	s_nop 0
	v_cvt_pk_bf16_f32 v128, v32, v33
	v_cvt_pk_bf16_f32 v129, v34, v35
	v_cvt_pk_bf16_f32 v130, v0, v1
	v_cvt_pk_bf16_f32 v131, v2, v3
	v_addc_co_u32_e32 v133, vcc, 0, v133, vcc
	global_store_dwordx4 v[132:133], v[128:131], off offset:3072 sc1

.LBB0_1433:
	s_or_b64 exec, exec, s[6:7]
	v_or_b32_e32 v132, 4, v188
	v_ashrrev_i32_e32 v133, 31, v132
	v_lshlrev_b64 v[136:137], 2, v[132:133]
	s_waitcnt lgkmcnt(0)
	s_barrier
	v_lshl_add_u64 v[132:133], s[18:19], 0, v[136:137]
	v_lshl_add_u64 v[136:137], s[20:21], 0, v[136:137]
	global_load_dwordx4 v[128:131], v[212:213], off offset:16
	v_lshlrev_b32_e32 v247, 2, v167
	global_load_dwordx4 v[132:135], v[132:133], off
	s_nop 0
	global_load_dwordx4 v[136:139], v[136:137], off
	s_nop 0
	global_load_dwordx4 v[140:143], v[206:207], off offset:16
	v_readlane_b32 s10, v254, 60
	v_cmp_eq_u32_e64 s[6:7], 15, v242
	v_cmp_eq_u32_e32 vcc, 0, v242
	v_add_u32_e32 v167, s10, v247
	ds_read_b128 v[190:193], v167
	v_readlane_b32 s10, v254, 63
	v_mov_b32_e32 v169, v168
	v_mov_b32_e32 v179, v178
	v_add_u32_e32 v244, s10, v247
	ds_read_b128 v[194:197], v244 offset:2048
	s_waitcnt lgkmcnt(0)
	v_pk_mul_f32 v[190:191], v[170:171], v[190:191]
	v_mov_b32_e32 v167, v166
	v_cndmask_b32_e64 v175, v116, v190, s[6:7]
	v_pk_mul_f32 v[192:193], v[166:167], v[192:193]
	v_pk_mul_f32 v[222:223], v[172:173], v[194:195]
	v_mov_b32_dpp v190, v175 row_ror:1 row_mask:0xf bank_mask:0xf
	v_cndmask_b32_e32 v175, v116, v124, vcc
	v_pk_mul_f32 v[220:221], v[168:169], v[196:197]
	v_readlane_b32 s10, v255, 0
	v_mov_b32_dpp v194, v175 row_ror:15 row_mask:0xf bank_mask:0xf
	v_cndmask_b32_e64 v175, v117, v191, s[6:7]
	s_movk_i32 s23, 0x5000
	v_add_u32_e32 v246, s73, v247
	v_mov_b32_dpp v191, v175 row_ror:1 row_mask:0xf bank_mask:0xf
	v_cndmask_b32_e32 v175, v117, v125, vcc
	v_add_u32_e32 v245, s94, v247
	s_nop 0
	v_mov_b32_dpp v195, v175 row_ror:15 row_mask:0xf bank_mask:0xf
	v_cndmask_b32_e64 v175, v118, v192, s[6:7]
	s_waitcnt vmcnt(4)
	v_pk_fma_f32 v[194:195], v[152:153], v[194:195], v[156:157]
	v_mov_b32_dpp v192, v175 row_ror:1 row_mask:0xf bank_mask:0xf
	v_cndmask_b32_e32 v175, v118, v126, vcc
	v_pk_fma_f32 v[194:195], v[148:149], v[116:117], v[194:195]
	v_cndmask_b32_e64 v116, v124, v116, s[6:7]
	v_mov_b32_dpp v196, v175 row_ror:15 row_mask:0xf bank_mask:0xf
	v_cndmask_b32_e64 v175, v119, v193, s[6:7]
	v_pk_fma_f32 v[204:205], v[144:145], v[190:191], v[194:195]
	v_cndmask_b32_e64 v117, v125, v117, s[6:7]
	v_mov_b32_dpp v193, v175 row_ror:1 row_mask:0xf bank_mask:0xf
	v_cndmask_b32_e32 v175, v119, v127, vcc
	v_mov_b32_dpp v116, v116 row_ror:1 row_mask:0xf bank_mask:0xf
	v_mov_b32_dpp v117, v117 row_ror:1 row_mask:0xf bank_mask:0xf
	v_mov_b32_dpp v197, v175 row_ror:15 row_mask:0xf bank_mask:0xf
	v_cndmask_b32_e32 v175, v124, v120, vcc
	v_pk_fma_f32 v[196:197], v[154:155], v[196:197], v[158:159]
	s_nop 0
	v_mov_b32_dpp v190, v175 row_ror:15 row_mask:0xf bank_mask:0xf
	v_cndmask_b32_e32 v175, v125, v121, vcc
	v_pk_fma_f32 v[196:197], v[150:151], v[118:119], v[196:197]
	v_cndmask_b32_e64 v118, v126, v118, s[6:7]
	v_mov_b32_dpp v191, v175 row_ror:15 row_mask:0xf bank_mask:0xf
	v_cndmask_b32_e32 v175, v126, v122, vcc
	v_pk_fma_f32 v[202:203], v[146:147], v[192:193], v[196:197]
	v_cndmask_b32_e64 v119, v127, v119, s[6:7]
	v_mov_b32_dpp v192, v175 row_ror:15 row_mask:0xf bank_mask:0xf
	v_cndmask_b32_e32 v175, v127, v123, vcc
	v_pk_fma_f32 v[190:191], v[152:153], v[190:191], v[156:157]
	v_mov_b32_dpp v118, v118 row_ror:1 row_mask:0xf bank_mask:0xf
	v_mov_b32_dpp v193, v175 row_ror:15 row_mask:0xf bank_mask:0xf
	v_pk_fma_f32 v[192:193], v[154:155], v[192:193], v[158:159]
	v_mov_b32_dpp v119, v119 row_ror:1 row_mask:0xf bank_mask:0xf
	v_pk_fma_f32 v[190:191], v[148:149], v[124:125], v[190:191]
	v_pk_fma_f32 v[192:193], v[150:151], v[126:127], v[192:193]
	v_pk_fma_f32 v[200:201], v[144:145], v[116:117], v[190:191]
	v_pk_fma_f32 v[198:199], v[146:147], v[118:119], v[192:193]
	v_cndmask_b32_e32 v117, v120, v112, vcc
	v_cndmask_b32_e32 v119, v121, v113, vcc
	v_cndmask_b32_e64 v116, v120, v124, s[6:7]
	v_mov_b32_dpp v118, v117 row_ror:15 row_mask:0xf bank_mask:0xf
	v_mov_b32_dpp v119, v119 row_ror:15 row_mask:0xf bank_mask:0xf
	v_cndmask_b32_e64 v117, v121, v125, s[6:7]
	v_cndmask_b32_e32 v125, v122, v114, vcc
	v_pk_fma_f32 v[118:119], v[152:153], v[118:119], v[156:157]
	v_mov_b32_dpp v116, v116 row_ror:1 row_mask:0xf bank_mask:0xf
	v_mov_b32_dpp v117, v117 row_ror:1 row_mask:0xf bank_mask:0xf
	v_cndmask_b32_e64 v124, v122, v126, s[6:7]
	v_mov_b32_dpp v126, v125 row_ror:15 row_mask:0xf bank_mask:0xf
	v_cndmask_b32_e64 v125, v123, v127, s[6:7]
	v_cndmask_b32_e32 v127, v123, v115, vcc
	v_pk_fma_f32 v[118:119], v[148:149], v[120:121], v[118:119]
	v_mov_b32_e32 v175, v174
	v_mov_b32_dpp v127, v127 row_ror:15 row_mask:0xf bank_mask:0xf
	v_pk_fma_f32 v[196:197], v[144:145], v[116:117], v[118:119]
	v_cndmask_b32_e32 v117, v112, v222, vcc
	v_cndmask_b32_e32 v119, v113, v223, vcc
	v_pk_fma_f32 v[126:127], v[154:155], v[126:127], v[158:159]
	v_mov_b32_dpp v118, v117 row_ror:15 row_mask:0xf bank_mask:0xf
	v_cndmask_b32_e64 v117, v113, v121, s[6:7]
	v_mov_b32_dpp v119, v119 row_ror:15 row_mask:0xf bank_mask:0xf
	v_cndmask_b32_e32 v121, v114, v220, vcc
	v_pk_fma_f32 v[126:127], v[150:151], v[122:123], v[126:127]
	v_cndmask_b32_e64 v116, v112, v120, s[6:7]
	v_cndmask_b32_e64 v120, v114, v122, s[6:7]
	v_mov_b32_dpp v122, v121 row_ror:15 row_mask:0xf bank_mask:0xf
	v_cndmask_b32_e64 v121, v115, v123, s[6:7]
	v_cndmask_b32_e32 v123, v115, v221, vcc
	v_pk_fma_f32 v[118:119], v[152:153], v[118:119], v[156:157]
	v_mov_b32_dpp v116, v116 row_ror:1 row_mask:0xf bank_mask:0xf
	v_mov_b32_dpp v117, v117 row_ror:1 row_mask:0xf bank_mask:0xf
	v_mov_b32_dpp v123, v123 row_ror:15 row_mask:0xf bank_mask:0xf
	v_pk_fma_f32 v[112:113], v[148:149], v[112:113], v[118:119]
	v_pk_fma_f32 v[122:123], v[154:155], v[122:123], v[158:159]
	v_pk_fma_f32 v[192:193], v[144:145], v[116:117], v[112:113]
	v_add_u32_e32 v112, s10, v247
	v_readlane_b32 s10, v255, 1
	v_mov_b32_dpp v120, v120 row_ror:1 row_mask:0xf bank_mask:0xf
	v_mov_b32_dpp v121, v121 row_ror:1 row_mask:0xf bank_mask:0xf
	v_pk_fma_f32 v[114:115], v[150:151], v[114:115], v[122:123]
	v_add_u32_e32 v243, s10, v247
	v_pk_fma_f32 v[190:191], v[146:147], v[120:121], v[114:115]
	ds_read_b128 v[112:115], v112
	ds_read_b128 v[116:119], v243 offset:2048
	v_mov_b32_dpp v124, v124 row_ror:1 row_mask:0xf bank_mask:0xf
	v_mov_b32_dpp v125, v125 row_ror:1 row_mask:0xf bank_mask:0xf
	v_pk_fma_f32 v[194:195], v[146:147], v[124:125], v[126:127]
	s_waitcnt lgkmcnt(1)
	v_pk_mul_f32 v[114:115], v[174:175], v[114:115]
	s_waitcnt lgkmcnt(0)
	v_pk_mul_f32 v[220:221], v[178:179], v[118:119]
	v_pk_mul_f32 v[222:223], v[182:183], v[116:117]
	v_cndmask_b32_e32 v116, v100, v104, vcc
	v_cndmask_b32_e32 v117, v101, v105, vcc
	v_cndmask_b32_e32 v118, v102, v106, vcc
	v_cndmask_b32_e32 v119, v103, v107, vcc
	v_pk_mul_f32 v[112:113], v[180:181], v[112:113]
	v_mov_b32_dpp v116, v116 row_ror:15 row_mask:0xf bank_mask:0xf
	v_mov_b32_dpp v117, v117 row_ror:15 row_mask:0xf bank_mask:0xf
	v_mov_b32_dpp v118, v118 row_ror:15 row_mask:0xf bank_mask:0xf
	v_mov_b32_dpp v119, v119 row_ror:15 row_mask:0xf bank_mask:0xf
	v_cndmask_b32_e64 v112, v100, v112, s[6:7]
	v_cndmask_b32_e64 v113, v101, v113, s[6:7]
	v_cndmask_b32_e64 v114, v102, v114, s[6:7]
	v_cndmask_b32_e64 v115, v103, v115, s[6:7]
	v_pk_fma_f32 v[118:119], v[154:155], v[118:119], v[158:159]
	v_pk_fma_f32 v[116:117], v[152:153], v[116:117], v[156:157]
	v_mov_b32_dpp v112, v112 row_ror:1 row_mask:0xf bank_mask:0xf
	v_mov_b32_dpp v113, v113 row_ror:1 row_mask:0xf bank_mask:0xf
	v_mov_b32_dpp v114, v114 row_ror:1 row_mask:0xf bank_mask:0xf
	v_mov_b32_dpp v115, v115 row_ror:1 row_mask:0xf bank_mask:0xf
	v_pk_fma_f32 v[116:117], v[148:149], v[100:101], v[116:117]
	v_pk_fma_f32 v[118:119], v[150:151], v[102:103], v[118:119]
	v_pk_fma_f32 v[126:127], v[144:145], v[112:113], v[116:117]
	v_pk_fma_f32 v[124:125], v[146:147], v[114:115], v[118:119]
	v_cndmask_b32_e32 v112, v104, v96, vcc
	v_cndmask_b32_e32 v113, v105, v97, vcc
	v_cndmask_b32_e32 v114, v106, v98, vcc
	v_cndmask_b32_e32 v115, v107, v99, vcc
	v_mov_b32_dpp v112, v112 row_ror:15 row_mask:0xf bank_mask:0xf
	v_mov_b32_dpp v113, v113 row_ror:15 row_mask:0xf bank_mask:0xf
	v_mov_b32_dpp v114, v114 row_ror:15 row_mask:0xf bank_mask:0xf
	v_mov_b32_dpp v115, v115 row_ror:15 row_mask:0xf bank_mask:0xf
	v_cndmask_b32_e64 v100, v104, v100, s[6:7]
	v_cndmask_b32_e64 v101, v105, v101, s[6:7]
	v_cndmask_b32_e64 v102, v106, v102, s[6:7]
	v_cndmask_b32_e64 v103, v107, v103, s[6:7]
	v_pk_fma_f32 v[114:115], v[154:155], v[114:115], v[158:159]
	v_pk_fma_f32 v[112:113], v[152:153], v[112:113], v[156:157]
	v_mov_b32_dpp v100, v100 row_ror:1 row_mask:0xf bank_mask:0xf
	v_mov_b32_dpp v101, v101 row_ror:1 row_mask:0xf bank_mask:0xf
	v_mov_b32_dpp v102, v102 row_ror:1 row_mask:0xf bank_mask:0xf
	v_mov_b32_dpp v103, v103 row_ror:1 row_mask:0xf bank_mask:0xf
	v_pk_fma_f32 v[112:113], v[148:149], v[104:105], v[112:113]
	v_pk_fma_f32 v[114:115], v[150:151], v[106:107], v[114:115]
	v_pk_fma_f32 v[122:123], v[144:145], v[100:101], v[112:113]
	v_pk_fma_f32 v[120:121], v[146:147], v[102:103], v[114:115]
	v_cndmask_b32_e32 v101, v96, v88, vcc
	v_cndmask_b32_e32 v103, v97, v89, vcc
	v_add_co_u32_e64 v212, s[10:11], s23, v212
	v_mov_b32_dpp v102, v101 row_ror:15 row_mask:0xf bank_mask:0xf
	v_mov_b32_dpp v103, v103 row_ror:15 row_mask:0xf bank_mask:0xf
	v_cndmask_b32_e64 v100, v96, v104, s[6:7]
	v_cndmask_b32_e64 v101, v97, v105, s[6:7]
	v_pk_fma_f32 v[102:103], v[152:153], v[102:103], v[156:157]
	v_addc_co_u32_e64 v213, s[10:11], 0, v213, s[10:11]
	v_mov_b32_dpp v100, v100 row_ror:1 row_mask:0xf bank_mask:0xf
	v_mov_b32_dpp v101, v101 row_ror:1 row_mask:0xf bank_mask:0xf
	v_cndmask_b32_e32 v105, v98, v90, vcc
	v_pk_fma_f32 v[102:103], v[148:149], v[96:97], v[102:103]
	v_add_co_u32_e64 v210, s[10:11], s23, v210
	v_cndmask_b32_e64 v104, v98, v106, s[6:7]
	v_mov_b32_dpp v106, v105 row_ror:15 row_mask:0xf bank_mask:0xf
	v_cndmask_b32_e64 v105, v99, v107, s[6:7]
	v_cndmask_b32_e32 v107, v99, v91, vcc
	v_pk_fma_f32 v[118:119], v[144:145], v[100:101], v[102:103]
	v_cndmask_b32_e32 v100, v88, v222, vcc
	v_cndmask_b32_e32 v101, v89, v223, vcc
	v_addc_co_u32_e64 v211, s[10:11], 0, v211, s[10:11]
	v_mov_b32_dpp v107, v107 row_ror:15 row_mask:0xf bank_mask:0xf
	v_mov_b32_dpp v100, v100 row_ror:15 row_mask:0xf bank_mask:0xf
	v_mov_b32_dpp v101, v101 row_ror:15 row_mask:0xf bank_mask:0xf
	v_cndmask_b32_e32 v102, v90, v220, vcc
	v_cndmask_b32_e32 v103, v91, v221, vcc
	v_add_co_u32_e64 v208, s[10:11], s23, v208
	v_pk_fma_f32 v[106:107], v[154:155], v[106:107], v[158:159]
	v_cndmask_b32_e64 v96, v88, v96, s[6:7]
	v_cndmask_b32_e64 v97, v89, v97, s[6:7]
	v_mov_b32_dpp v102, v102 row_ror:15 row_mask:0xf bank_mask:0xf
	v_mov_b32_dpp v103, v103 row_ror:15 row_mask:0xf bank_mask:0xf
	v_pk_fma_f32 v[100:101], v[152:153], v[100:101], v[156:157]
	v_addc_co_u32_e64 v209, s[10:11], 0, v209, s[10:11]
	v_pk_fma_f32 v[106:107], v[150:151], v[98:99], v[106:107]
	v_mov_b32_dpp v96, v96 row_ror:1 row_mask:0xf bank_mask:0xf
	v_mov_b32_dpp v97, v97 row_ror:1 row_mask:0xf bank_mask:0xf
	v_cndmask_b32_e64 v98, v90, v98, s[6:7]
	v_cndmask_b32_e64 v99, v91, v99, s[6:7]
	v_pk_fma_f32 v[102:103], v[154:155], v[102:103], v[158:159]
	v_pk_fma_f32 v[88:89], v[148:149], v[88:89], v[100:101]
	v_add_co_u32_e64 v206, s[10:11], s23, v206
	v_mov_b32_dpp v104, v104 row_ror:1 row_mask:0xf bank_mask:0xf
	v_mov_b32_dpp v105, v105 row_ror:1 row_mask:0xf bank_mask:0xf
	v_mov_b32_dpp v98, v98 row_ror:1 row_mask:0xf bank_mask:0xf
	v_mov_b32_dpp v99, v99 row_ror:1 row_mask:0xf bank_mask:0xf
	v_pk_fma_f32 v[90:91], v[150:151], v[90:91], v[102:103]
	v_pk_fma_f32 v[114:115], v[144:145], v[96:97], v[88:89]
	v_addc_co_u32_e64 v207, s[10:11], 0, v207, s[10:11]
	v_add_u32_e32 v144, 0xfffffc10, v246
	v_pk_fma_f32 v[116:117], v[146:147], v[104:105], v[106:107]
	v_pk_fma_f32 v[112:113], v[146:147], v[98:99], v[90:91]
	global_load_dwordx4 v[88:91], v[212:213], off offset:2048
	global_load_dwordx4 v[96:99], v[210:211], off offset:2048
	global_load_dwordx4 v[100:103], v[208:209], off offset:2048
	global_load_dwordx4 v[104:107], v[206:207], off offset:2048
	s_waitcnt vmcnt(4)
	ds_read_b128 v[144:147], v144
	ds_read_b128 v[148:151], v244 offset:2064
	v_readlane_b32 s10, v255, 2
	s_waitcnt lgkmcnt(1)
	v_pk_mul_f32 v[144:145], v[170:171], v[144:145]
	s_waitcnt lgkmcnt(0)
	v_pk_mul_f32 v[154:155], v[172:173], v[148:149]
	v_cndmask_b32_e32 v148, v84, v108, vcc
	v_cndmask_b32_e32 v149, v85, v109, vcc
	v_pk_mul_f32 v[152:153], v[168:169], v[150:151]
	v_mov_b32_dpp v148, v148 row_ror:15 row_mask:0xf bank_mask:0xf
	v_mov_b32_dpp v149, v149 row_ror:15 row_mask:0xf bank_mask:0xf
	v_cndmask_b32_e32 v150, v86, v110, vcc
	v_cndmask_b32_e32 v151, v87, v111, vcc
	v_pk_mul_f32 v[146:147], v[166:167], v[146:147]
	v_cndmask_b32_e64 v144, v84, v144, s[6:7]
	v_cndmask_b32_e64 v145, v85, v145, s[6:7]
	v_mov_b32_dpp v150, v150 row_ror:15 row_mask:0xf bank_mask:0xf
	v_mov_b32_dpp v151, v151 row_ror:15 row_mask:0xf bank_mask:0xf
	v_pk_fma_f32 v[148:149], v[136:137], v[148:149], v[140:141]
	v_mov_b32_dpp v144, v144 row_ror:1 row_mask:0xf bank_mask:0xf
	v_mov_b32_dpp v145, v145 row_ror:1 row_mask:0xf bank_mask:0xf
	v_cndmask_b32_e64 v146, v86, v146, s[6:7]
	v_cndmask_b32_e64 v147, v87, v147, s[6:7]
	v_pk_fma_f32 v[150:151], v[138:139], v[150:151], v[142:143]
	v_pk_fma_f32 v[148:149], v[132:133], v[84:85], v[148:149]
	v_mov_b32_dpp v146, v146 row_ror:1 row_mask:0xf bank_mask:0xf
	v_mov_b32_dpp v147, v147 row_ror:1 row_mask:0xf bank_mask:0xf
	v_pk_fma_f32 v[150:151], v[134:135], v[86:87], v[150:151]
	v_pk_fma_f32 v[158:159], v[128:129], v[144:145], v[148:149]
	v_cndmask_b32_e32 v144, v108, v92, vcc
	v_cndmask_b32_e32 v145, v109, v93, vcc
	v_pk_fma_f32 v[156:157], v[130:131], v[146:147], v[150:151]
	v_mov_b32_dpp v144, v144 row_ror:15 row_mask:0xf bank_mask:0xf
	v_mov_b32_dpp v145, v145 row_ror:15 row_mask:0xf bank_mask:0xf
	v_cndmask_b32_e32 v146, v110, v94, vcc
	v_cndmask_b32_e32 v147, v111, v95, vcc
	v_cndmask_b32_e64 v84, v108, v84, s[6:7]
	v_cndmask_b32_e64 v85, v109, v85, s[6:7]
	v_mov_b32_dpp v146, v146 row_ror:15 row_mask:0xf bank_mask:0xf
	v_mov_b32_dpp v147, v147 row_ror:15 row_mask:0xf bank_mask:0xf
	v_pk_fma_f32 v[144:145], v[136:137], v[144:145], v[140:141]
	v_mov_b32_dpp v84, v84 row_ror:1 row_mask:0xf bank_mask:0xf
	v_mov_b32_dpp v85, v85 row_ror:1 row_mask:0xf bank_mask:0xf
	v_cndmask_b32_e64 v86, v110, v86, s[6:7]
	v_cndmask_b32_e64 v87, v111, v87, s[6:7]
	v_pk_fma_f32 v[146:147], v[138:139], v[146:147], v[142:143]
	v_pk_fma_f32 v[144:145], v[132:133], v[108:109], v[144:145]
	v_mov_b32_dpp v86, v86 row_ror:1 row_mask:0xf bank_mask:0xf
	v_mov_b32_dpp v87, v87 row_ror:1 row_mask:0xf bank_mask:0xf
	v_pk_fma_f32 v[146:147], v[134:135], v[110:111], v[146:147]
	v_pk_fma_f32 v[150:151], v[128:129], v[84:85], v[144:145]
	v_cndmask_b32_e32 v85, v92, v80, vcc
	v_pk_fma_f32 v[148:149], v[130:131], v[86:87], v[146:147]
	v_cndmask_b32_e64 v84, v92, v108, s[6:7]
	v_mov_b32_dpp v86, v85 row_ror:15 row_mask:0xf bank_mask:0xf
	v_cndmask_b32_e64 v85, v93, v109, s[6:7]
	v_cndmask_b32_e32 v109, v94, v82, vcc
	v_cndmask_b32_e32 v87, v93, v81, vcc
	v_cndmask_b32_e64 v108, v94, v110, s[6:7]
	v_mov_b32_dpp v110, v109 row_ror:15 row_mask:0xf bank_mask:0xf
	v_cndmask_b32_e64 v109, v95, v111, s[6:7]
	v_cndmask_b32_e32 v111, v95, v83, vcc
	v_mov_b32_dpp v87, v87 row_ror:15 row_mask:0xf bank_mask:0xf
	v_pk_fma_f32 v[86:87], v[136:137], v[86:87], v[140:141]
	v_mov_b32_dpp v111, v111 row_ror:15 row_mask:0xf bank_mask:0xf
	v_pk_fma_f32 v[110:111], v[138:139], v[110:111], v[142:143]
	v_mov_b32_dpp v84, v84 row_ror:1 row_mask:0xf bank_mask:0xf
	v_mov_b32_dpp v85, v85 row_ror:1 row_mask:0xf bank_mask:0xf
	v_mov_b32_dpp v108, v108 row_ror:1 row_mask:0xf bank_mask:0xf
	v_mov_b32_dpp v109, v109 row_ror:1 row_mask:0xf bank_mask:0xf
	v_pk_fma_f32 v[110:111], v[134:135], v[94:95], v[110:111]
	v_pk_fma_f32 v[86:87], v[132:133], v[92:93], v[86:87]
	v_pk_fma_f32 v[108:109], v[130:131], v[108:109], v[110:111]
	v_pk_fma_f32 v[110:111], v[128:129], v[84:85], v[86:87]
	v_cndmask_b32_e32 v85, v80, v154, vcc
	v_cndmask_b32_e32 v87, v81, v155, vcc
	v_cndmask_b32_e64 v84, v80, v92, s[6:7]
	v_mov_b32_dpp v86, v85 row_ror:15 row_mask:0xf bank_mask:0xf
	v_cndmask_b32_e64 v85, v81, v93, s[6:7]
	v_cndmask_b32_e32 v93, v82, v152, vcc
	v_mov_b32_dpp v87, v87 row_ror:15 row_mask:0xf bank_mask:0xf
	v_cndmask_b32_e64 v92, v82, v94, s[6:7]
	v_mov_b32_dpp v94, v93 row_ror:15 row_mask:0xf bank_mask:0xf
	v_cndmask_b32_e64 v93, v83, v95, s[6:7]
	v_cndmask_b32_e32 v95, v83, v153, vcc
	v_pk_fma_f32 v[86:87], v[136:137], v[86:87], v[140:141]
	v_mov_b32_dpp v84, v84 row_ror:1 row_mask:0xf bank_mask:0xf
	v_mov_b32_dpp v95, v95 row_ror:15 row_mask:0xf bank_mask:0xf
	v_mov_b32_dpp v85, v85 row_ror:1 row_mask:0xf bank_mask:0xf
	v_pk_fma_f32 v[94:95], v[138:139], v[94:95], v[142:143]
	v_pk_fma_f32 v[80:81], v[132:133], v[80:81], v[86:87]
	v_mov_b32_dpp v92, v92 row_ror:1 row_mask:0xf bank_mask:0xf
	v_mov_b32_dpp v93, v93 row_ror:1 row_mask:0xf bank_mask:0xf
	v_pk_fma_f32 v[82:83], v[134:135], v[82:83], v[94:95]
	v_pk_fma_f32 v[94:95], v[128:129], v[84:85], v[80:81]
	v_add_u32_e32 v80, 0xfffffc10, v245
	v_pk_fma_f32 v[92:93], v[130:131], v[92:93], v[82:83]
	ds_read_b128 v[80:83], v80
	ds_read_b128 v[84:87], v243 offset:2064
	s_waitcnt lgkmcnt(1)
	v_pk_mul_f32 v[82:83], v[174:175], v[82:83]
	s_waitcnt lgkmcnt(0)
	v_pk_mul_f32 v[220:221], v[178:179], v[86:87]
	v_pk_mul_f32 v[222:223], v[182:183], v[84:85]
	v_cndmask_b32_e32 v84, v72, v76, vcc
	v_cndmask_b32_e32 v85, v73, v77, vcc
	v_cndmask_b32_e32 v86, v74, v78, vcc
	v_cndmask_b32_e32 v87, v75, v79, vcc
	v_pk_mul_f32 v[80:81], v[180:181], v[80:81]
	v_mov_b32_dpp v84, v84 row_ror:15 row_mask:0xf bank_mask:0xf
	v_mov_b32_dpp v85, v85 row_ror:15 row_mask:0xf bank_mask:0xf
	v_mov_b32_dpp v86, v86 row_ror:15 row_mask:0xf bank_mask:0xf
	v_mov_b32_dpp v87, v87 row_ror:15 row_mask:0xf bank_mask:0xf
	v_cndmask_b32_e64 v80, v72, v80, s[6:7]
	v_cndmask_b32_e64 v81, v73, v81, s[6:7]
	v_cndmask_b32_e64 v82, v74, v82, s[6:7]
	v_cndmask_b32_e64 v83, v75, v83, s[6:7]
	v_pk_fma_f32 v[84:85], v[136:137], v[84:85], v[140:141]
	v_pk_fma_f32 v[86:87], v[138:139], v[86:87], v[142:143]
	v_mov_b32_dpp v80, v80 row_ror:1 row_mask:0xf bank_mask:0xf
	v_mov_b32_dpp v81, v81 row_ror:1 row_mask:0xf bank_mask:0xf
	v_mov_b32_dpp v82, v82 row_ror:1 row_mask:0xf bank_mask:0xf
	v_mov_b32_dpp v83, v83 row_ror:1 row_mask:0xf bank_mask:0xf
	v_pk_fma_f32 v[86:87], v[134:135], v[74:75], v[86:87]
	v_pk_fma_f32 v[84:85], v[132:133], v[72:73], v[84:85]
	v_pk_fma_f32 v[152:153], v[130:131], v[82:83], v[86:87]
	v_pk_fma_f32 v[154:155], v[128:129], v[80:81], v[84:85]
	v_cndmask_b32_e32 v80, v76, v68, vcc
	v_cndmask_b32_e32 v81, v77, v69, vcc
	v_cndmask_b32_e32 v82, v78, v70, vcc
	v_cndmask_b32_e32 v83, v79, v71, vcc
	v_mov_b32_dpp v80, v80 row_ror:15 row_mask:0xf bank_mask:0xf
	v_mov_b32_dpp v81, v81 row_ror:15 row_mask:0xf bank_mask:0xf
	v_mov_b32_dpp v82, v82 row_ror:15 row_mask:0xf bank_mask:0xf
	v_mov_b32_dpp v83, v83 row_ror:15 row_mask:0xf bank_mask:0xf
	v_cndmask_b32_e64 v72, v76, v72, s[6:7]
	v_cndmask_b32_e64 v73, v77, v73, s[6:7]
	v_cndmask_b32_e64 v74, v78, v74, s[6:7]
	v_cndmask_b32_e64 v75, v79, v75, s[6:7]
	v_pk_fma_f32 v[80:81], v[136:137], v[80:81], v[140:141]
	v_pk_fma_f32 v[82:83], v[138:139], v[82:83], v[142:143]
	v_mov_b32_dpp v72, v72 row_ror:1 row_mask:0xf bank_mask:0xf
	v_mov_b32_dpp v73, v73 row_ror:1 row_mask:0xf bank_mask:0xf
	v_mov_b32_dpp v74, v74 row_ror:1 row_mask:0xf bank_mask:0xf
	v_mov_b32_dpp v75, v75 row_ror:1 row_mask:0xf bank_mask:0xf
	v_pk_fma_f32 v[82:83], v[134:135], v[78:79], v[82:83]
	v_pk_fma_f32 v[80:81], v[132:133], v[76:77], v[80:81]
	v_pk_fma_f32 v[144:145], v[130:131], v[74:75], v[82:83]
	v_pk_fma_f32 v[146:147], v[128:129], v[72:73], v[80:81]
	v_cndmask_b32_e32 v73, v68, v64, vcc
	v_cndmask_b32_e32 v75, v69, v65, vcc
	v_cndmask_b32_e64 v72, v68, v76, s[6:7]
	v_mov_b32_dpp v74, v73 row_ror:15 row_mask:0xf bank_mask:0xf
	v_mov_b32_dpp v75, v75 row_ror:15 row_mask:0xf bank_mask:0xf
	v_cndmask_b32_e64 v73, v69, v77, s[6:7]
	v_cndmask_b32_e32 v77, v70, v66, vcc
	v_pk_fma_f32 v[74:75], v[136:137], v[74:75], v[140:141]
	v_mov_b32_dpp v72, v72 row_ror:1 row_mask:0xf bank_mask:0xf
	v_mov_b32_dpp v73, v73 row_ror:1 row_mask:0xf bank_mask:0xf
	v_cndmask_b32_e64 v76, v70, v78, s[6:7]
	v_mov_b32_dpp v78, v77 row_ror:15 row_mask:0xf bank_mask:0xf
	v_cndmask_b32_e64 v77, v71, v79, s[6:7]
	v_cndmask_b32_e32 v79, v71, v67, vcc
	v_pk_fma_f32 v[74:75], v[132:133], v[68:69], v[74:75]
	v_cndmask_b32_e64 v68, v64, v68, s[6:7]
	v_mov_b32_dpp v79, v79 row_ror:15 row_mask:0xf bank_mask:0xf
	v_pk_fma_f32 v[86:87], v[128:129], v[72:73], v[74:75]
	v_cndmask_b32_e32 v72, v64, v222, vcc
	v_cndmask_b32_e32 v73, v65, v223, vcc
	v_cndmask_b32_e32 v74, v66, v220, vcc
	v_cndmask_b32_e32 v75, v67, v221, vcc
	v_pk_fma_f32 v[78:79], v[138:139], v[78:79], v[142:143]
	v_mov_b32_dpp v72, v72 row_ror:15 row_mask:0xf bank_mask:0xf
	v_mov_b32_dpp v73, v73 row_ror:15 row_mask:0xf bank_mask:0xf
	v_mov_b32_dpp v74, v74 row_ror:15 row_mask:0xf bank_mask:0xf
	v_mov_b32_dpp v75, v75 row_ror:15 row_mask:0xf bank_mask:0xf
	v_pk_fma_f32 v[78:79], v[134:135], v[70:71], v[78:79]
	v_cndmask_b32_e64 v69, v65, v69, s[6:7]
	v_cndmask_b32_e64 v70, v66, v70, s[6:7]
	v_cndmask_b32_e64 v71, v67, v71, s[6:7]
	v_pk_fma_f32 v[74:75], v[138:139], v[74:75], v[142:143]
	v_pk_fma_f32 v[72:73], v[136:137], v[72:73], v[140:141]
	v_mov_b32_dpp v76, v76 row_ror:1 row_mask:0xf bank_mask:0xf
	v_mov_b32_dpp v77, v77 row_ror:1 row_mask:0xf bank_mask:0xf
	v_mov_b32_dpp v68, v68 row_ror:1 row_mask:0xf bank_mask:0xf
	v_mov_b32_dpp v69, v69 row_ror:1 row_mask:0xf bank_mask:0xf
	v_mov_b32_dpp v70, v70 row_ror:1 row_mask:0xf bank_mask:0xf
	v_mov_b32_dpp v71, v71 row_ror:1 row_mask:0xf bank_mask:0xf
	v_pk_fma_f32 v[66:67], v[134:135], v[66:67], v[74:75]
	v_pk_fma_f32 v[64:65], v[132:133], v[64:65], v[72:73]
	v_pk_fma_f32 v[84:85], v[130:131], v[76:77], v[78:79]
	v_pk_fma_f32 v[80:81], v[130:131], v[70:71], v[66:67]
	v_pk_fma_f32 v[82:83], v[128:129], v[68:69], v[64:65]
	global_load_dwordx4 v[64:67], v[212:213], off offset:2064
	global_load_dwordx4 v[68:71], v[210:211], off offset:2064
	global_load_dwordx4 v[72:75], v[208:209], off offset:2064
	global_load_dwordx4 v[76:79], v[206:207], off offset:2064
	v_add_u32_e32 v128, s10, v247
	ds_read_b128 v[128:131], v128
	ds_read_b128 v[132:135], v244 offset:2560
	s_movk_i32 s10, 0x2c00
	s_waitcnt lgkmcnt(1)
	v_pk_mul_f32 v[128:129], v[170:171], v[128:129]
	s_waitcnt lgkmcnt(0)
	v_pk_mul_f32 v[138:139], v[172:173], v[132:133]
	v_cndmask_b32_e32 v132, v52, v60, vcc
	v_cndmask_b32_e32 v133, v53, v61, vcc
	v_pk_mul_f32 v[136:137], v[168:169], v[134:135]
	v_mov_b32_dpp v132, v132 row_ror:15 row_mask:0xf bank_mask:0xf
	v_mov_b32_dpp v133, v133 row_ror:15 row_mask:0xf bank_mask:0xf
	v_cndmask_b32_e32 v134, v54, v62, vcc
	v_cndmask_b32_e32 v135, v55, v63, vcc
	v_pk_mul_f32 v[130:131], v[166:167], v[130:131]
	v_cndmask_b32_e64 v128, v52, v128, s[6:7]
	v_cndmask_b32_e64 v129, v53, v129, s[6:7]
	v_mov_b32_dpp v134, v134 row_ror:15 row_mask:0xf bank_mask:0xf
	v_mov_b32_dpp v135, v135 row_ror:15 row_mask:0xf bank_mask:0xf
	s_waitcnt vmcnt(4)
	v_pk_fma_f32 v[132:133], v[100:101], v[132:133], v[104:105]
	v_mov_b32_dpp v128, v128 row_ror:1 row_mask:0xf bank_mask:0xf
	v_mov_b32_dpp v129, v129 row_ror:1 row_mask:0xf bank_mask:0xf
	v_cndmask_b32_e64 v130, v54, v130, s[6:7]
	v_cndmask_b32_e64 v131, v55, v131, s[6:7]
	v_pk_fma_f32 v[134:135], v[102:103], v[134:135], v[106:107]
	v_pk_fma_f32 v[140:141], v[96:97], v[52:53], v[132:133]
	v_mov_b32_dpp v130, v130 row_ror:1 row_mask:0xf bank_mask:0xf
	v_mov_b32_dpp v131, v131 row_ror:1 row_mask:0xf bank_mask:0xf
	v_pk_fma_f32 v[132:133], v[98:99], v[54:55], v[134:135]
	v_pk_fma_f32 v[134:135], v[88:89], v[128:129], v[140:141]
	v_cndmask_b32_e32 v128, v60, v56, vcc
	v_cndmask_b32_e32 v129, v61, v57, vcc
	v_pk_fma_f32 v[132:133], v[90:91], v[130:131], v[132:133]
	v_mov_b32_dpp v128, v128 row_ror:15 row_mask:0xf bank_mask:0xf
	v_mov_b32_dpp v129, v129 row_ror:15 row_mask:0xf bank_mask:0xf
	v_cndmask_b32_e32 v130, v62, v58, vcc
	v_cndmask_b32_e32 v131, v63, v59, vcc
	v_cndmask_b32_e64 v52, v60, v52, s[6:7]
	v_cndmask_b32_e64 v53, v61, v53, s[6:7]
	v_mov_b32_dpp v130, v130 row_ror:15 row_mask:0xf bank_mask:0xf
	v_mov_b32_dpp v131, v131 row_ror:15 row_mask:0xf bank_mask:0xf
	v_pk_fma_f32 v[128:129], v[100:101], v[128:129], v[104:105]
	v_mov_b32_dpp v52, v52 row_ror:1 row_mask:0xf bank_mask:0xf
	v_mov_b32_dpp v53, v53 row_ror:1 row_mask:0xf bank_mask:0xf
	v_cndmask_b32_e64 v54, v62, v54, s[6:7]
	v_cndmask_b32_e64 v55, v63, v55, s[6:7]
	v_pk_fma_f32 v[130:131], v[102:103], v[130:131], v[106:107]
	v_pk_fma_f32 v[140:141], v[96:97], v[60:61], v[128:129]
	v_mov_b32_dpp v54, v54 row_ror:1 row_mask:0xf bank_mask:0xf
	v_mov_b32_dpp v55, v55 row_ror:1 row_mask:0xf bank_mask:0xf
	v_pk_fma_f32 v[128:129], v[98:99], v[62:63], v[130:131]
	v_pk_fma_f32 v[130:131], v[88:89], v[52:53], v[140:141]
	v_cndmask_b32_e32 v53, v56, v48, vcc
	v_pk_fma_f32 v[128:129], v[90:91], v[54:55], v[128:129]
	v_cndmask_b32_e64 v52, v56, v60, s[6:7]
	v_mov_b32_dpp v54, v53 row_ror:15 row_mask:0xf bank_mask:0xf
	v_cndmask_b32_e64 v53, v57, v61, s[6:7]
	v_cndmask_b32_e32 v61, v58, v50, vcc
	v_cndmask_b32_e32 v55, v57, v49, vcc
	v_cndmask_b32_e64 v60, v58, v62, s[6:7]
	v_mov_b32_dpp v62, v61 row_ror:15 row_mask:0xf bank_mask:0xf
	v_cndmask_b32_e64 v61, v59, v63, s[6:7]
	v_cndmask_b32_e32 v63, v59, v51, vcc
	v_mov_b32_dpp v55, v55 row_ror:15 row_mask:0xf bank_mask:0xf
	v_pk_fma_f32 v[54:55], v[100:101], v[54:55], v[104:105]
	v_mov_b32_dpp v63, v63 row_ror:15 row_mask:0xf bank_mask:0xf
	v_pk_fma_f32 v[62:63], v[102:103], v[62:63], v[106:107]
	v_mov_b32_dpp v52, v52 row_ror:1 row_mask:0xf bank_mask:0xf
	v_mov_b32_dpp v53, v53 row_ror:1 row_mask:0xf bank_mask:0xf
	v_mov_b32_dpp v60, v60 row_ror:1 row_mask:0xf bank_mask:0xf
	v_mov_b32_dpp v61, v61 row_ror:1 row_mask:0xf bank_mask:0xf
	v_pk_fma_f32 v[54:55], v[96:97], v[56:57], v[54:55]
	v_pk_fma_f32 v[62:63], v[98:99], v[58:59], v[62:63]
	s_nop 0
	v_pk_fma_f32 v[60:61], v[90:91], v[60:61], v[62:63]
	v_pk_fma_f32 v[62:63], v[88:89], v[52:53], v[54:55]
	v_cndmask_b32_e32 v53, v48, v138, vcc
	v_cndmask_b32_e32 v55, v49, v139, vcc
	v_cndmask_b32_e64 v52, v48, v56, s[6:7]
	v_mov_b32_dpp v54, v53 row_ror:15 row_mask:0xf bank_mask:0xf
	v_cndmask_b32_e64 v53, v49, v57, s[6:7]
	v_cndmask_b32_e32 v57, v50, v136, vcc
	v_mov_b32_dpp v55, v55 row_ror:15 row_mask:0xf bank_mask:0xf
	v_cndmask_b32_e64 v56, v50, v58, s[6:7]
	v_mov_b32_dpp v58, v57 row_ror:15 row_mask:0xf bank_mask:0xf
	v_cndmask_b32_e64 v57, v51, v59, s[6:7]
	v_cndmask_b32_e32 v59, v51, v137, vcc
	v_pk_fma_f32 v[54:55], v[100:101], v[54:55], v[104:105]
	v_mov_b32_dpp v52, v52 row_ror:1 row_mask:0xf bank_mask:0xf
	v_mov_b32_dpp v59, v59 row_ror:15 row_mask:0xf bank_mask:0xf
	v_mov_b32_dpp v53, v53 row_ror:1 row_mask:0xf bank_mask:0xf
	v_pk_fma_f32 v[58:59], v[102:103], v[58:59], v[106:107]
	v_pk_fma_f32 v[48:49], v[96:97], v[48:49], v[54:55]
	v_mov_b32_dpp v56, v56 row_ror:1 row_mask:0xf bank_mask:0xf
	v_mov_b32_dpp v57, v57 row_ror:1 row_mask:0xf bank_mask:0xf
	v_pk_fma_f32 v[50:51], v[98:99], v[50:51], v[58:59]
	v_pk_fma_f32 v[58:59], v[88:89], v[52:53], v[48:49]
	v_add_u32_e32 v48, s95, v247
	v_pk_fma_f32 v[56:57], v[90:91], v[56:57], v[50:51]
	ds_read_b128 v[48:51], v48
	ds_read_b128 v[52:55], v243 offset:2560
	v_cndmask_b32_e32 v138, v46, v42, vcc
	v_cndmask_b32_e32 v139, v47, v43, vcc
	s_waitcnt lgkmcnt(1)
	v_pk_mul_f32 v[48:49], v[180:181], v[48:49]
	v_pk_mul_f32 v[50:51], v[174:175], v[50:51]
	v_cndmask_b32_e64 v48, v44, v48, s[6:7]
	v_cndmask_b32_e64 v49, v45, v49, s[6:7]
	v_mov_b32_dpp v138, v138 row_ror:15 row_mask:0xf bank_mask:0xf
	v_mov_b32_dpp v136, v48 row_ror:1 row_mask:0xf bank_mask:0xf
	v_cndmask_b32_e32 v48, v44, v40, vcc
	v_mov_b32_dpp v137, v49 row_ror:1 row_mask:0xf bank_mask:0xf
	v_cndmask_b32_e32 v49, v45, v41, vcc
	v_mov_b32_dpp v48, v48 row_ror:15 row_mask:0xf bank_mask:0xf
	v_mov_b32_dpp v139, v139 row_ror:15 row_mask:0xf bank_mask:0xf
	v_mov_b32_dpp v49, v49 row_ror:15 row_mask:0xf bank_mask:0xf
	v_cndmask_b32_e64 v50, v46, v50, s[6:7]
	v_cndmask_b32_e64 v51, v47, v51, s[6:7]
	v_pk_fma_f32 v[138:139], v[102:103], v[138:139], v[106:107]
	v_pk_fma_f32 v[48:49], v[100:101], v[48:49], v[104:105]
	v_mov_b32_dpp v50, v50 row_ror:1 row_mask:0xf bank_mask:0xf
	v_mov_b32_dpp v51, v51 row_ror:1 row_mask:0xf bank_mask:0xf
	v_pk_fma_f32 v[140:141], v[96:97], v[44:45], v[48:49]
	v_pk_fma_f32 v[48:49], v[98:99], v[46:47], v[138:139]
	v_cndmask_b32_e64 v44, v40, v44, s[6:7]
	v_cndmask_b32_e64 v45, v41, v45, s[6:7]
	v_pk_fma_f32 v[48:49], v[90:91], v[50:51], v[48:49]
	v_pk_fma_f32 v[50:51], v[88:89], v[136:137], v[140:141]
	v_mov_b32_dpp v136, v44 row_ror:1 row_mask:0xf bank_mask:0xf
	v_cndmask_b32_e32 v44, v40, v36, vcc
	v_mov_b32_dpp v137, v45 row_ror:1 row_mask:0xf bank_mask:0xf
	v_cndmask_b32_e32 v45, v41, v37, vcc
	v_cndmask_b32_e32 v138, v42, v38, vcc
	v_cndmask_b32_e32 v139, v43, v39, vcc
	v_mov_b32_dpp v44, v44 row_ror:15 row_mask:0xf bank_mask:0xf
	v_mov_b32_dpp v45, v45 row_ror:15 row_mask:0xf bank_mask:0xf
	v_mov_b32_dpp v138, v138 row_ror:15 row_mask:0xf bank_mask:0xf
	v_mov_b32_dpp v139, v139 row_ror:15 row_mask:0xf bank_mask:0xf
	v_cndmask_b32_e64 v46, v42, v46, s[6:7]
	v_cndmask_b32_e64 v47, v43, v47, s[6:7]
	v_pk_fma_f32 v[138:139], v[102:103], v[138:139], v[106:107]
	v_pk_fma_f32 v[44:45], v[100:101], v[44:45], v[104:105]
	v_mov_b32_dpp v46, v46 row_ror:1 row_mask:0xf bank_mask:0xf
	v_mov_b32_dpp v47, v47 row_ror:1 row_mask:0xf bank_mask:0xf
	v_pk_fma_f32 v[140:141], v[96:97], v[40:41], v[44:45]
	v_pk_fma_f32 v[44:45], v[98:99], v[42:43], v[138:139]
	v_cndmask_b32_e64 v40, v36, v40, s[6:7]
	v_cndmask_b32_e64 v41, v37, v41, s[6:7]
	s_waitcnt lgkmcnt(0)
	v_pk_mul_f32 v[54:55], v[178:179], v[54:55]
	v_pk_mul_f32 v[52:53], v[182:183], v[52:53]
	v_pk_fma_f32 v[44:45], v[90:91], v[46:47], v[44:45]
	v_pk_fma_f32 v[46:47], v[88:89], v[136:137], v[140:141]
	v_mov_b32_dpp v136, v40 row_ror:1 row_mask:0xf bank_mask:0xf
	v_cndmask_b32_e32 v40, v36, v32, vcc
	v_mov_b32_dpp v137, v41 row_ror:1 row_mask:0xf bank_mask:0xf
	v_cndmask_b32_e32 v41, v37, v33, vcc
	v_cndmask_b32_e32 v138, v38, v34, vcc
	v_cndmask_b32_e32 v139, v39, v35, vcc
	v_mov_b32_dpp v40, v40 row_ror:15 row_mask:0xf bank_mask:0xf
	v_mov_b32_dpp v41, v41 row_ror:15 row_mask:0xf bank_mask:0xf
	v_mov_b32_dpp v138, v138 row_ror:15 row_mask:0xf bank_mask:0xf
	v_mov_b32_dpp v139, v139 row_ror:15 row_mask:0xf bank_mask:0xf
	v_cndmask_b32_e32 v52, v32, v52, vcc
	v_cndmask_b32_e32 v53, v33, v53, vcc
	v_cndmask_b32_e32 v54, v34, v54, vcc
	v_cndmask_b32_e32 v55, v35, v55, vcc
	v_pk_fma_f32 v[138:139], v[102:103], v[138:139], v[106:107]
	v_pk_fma_f32 v[40:41], v[100:101], v[40:41], v[104:105]
	v_mov_b32_dpp v52, v52 row_ror:15 row_mask:0xf bank_mask:0xf
	v_mov_b32_dpp v53, v53 row_ror:15 row_mask:0xf bank_mask:0xf
	v_mov_b32_dpp v54, v54 row_ror:15 row_mask:0xf bank_mask:0xf
	v_mov_b32_dpp v55, v55 row_ror:15 row_mask:0xf bank_mask:0xf
	v_cndmask_b32_e64 v42, v38, v42, s[6:7]
	v_cndmask_b32_e64 v43, v39, v43, s[6:7]
	v_pk_fma_f32 v[140:141], v[96:97], v[36:37], v[40:41]
	v_pk_fma_f32 v[40:41], v[98:99], v[38:39], v[138:139]
	v_cndmask_b32_e64 v36, v32, v36, s[6:7]
	v_cndmask_b32_e64 v37, v33, v37, s[6:7]
	v_cndmask_b32_e64 v38, v34, v38, s[6:7]
	v_cndmask_b32_e64 v39, v35, v39, s[6:7]
	v_pk_fma_f32 v[54:55], v[102:103], v[54:55], v[106:107]
	v_pk_fma_f32 v[52:53], v[100:101], v[52:53], v[104:105]
	v_mov_b32_dpp v36, v36 row_ror:1 row_mask:0xf bank_mask:0xf
	v_mov_b32_dpp v37, v37 row_ror:1 row_mask:0xf bank_mask:0xf
	v_mov_b32_dpp v38, v38 row_ror:1 row_mask:0xf bank_mask:0xf
	v_mov_b32_dpp v39, v39 row_ror:1 row_mask:0xf bank_mask:0xf
	v_pk_fma_f32 v[34:35], v[98:99], v[34:35], v[54:55]
	v_pk_fma_f32 v[52:53], v[96:97], v[32:33], v[52:53]
	v_pk_fma_f32 v[32:33], v[90:91], v[38:39], v[34:35]
	v_pk_fma_f32 v[34:35], v[88:89], v[36:37], v[52:53]
	v_add_u32_e32 v36, 0xfffffe10, v246
	ds_read_b128 v[36:39], v36
	ds_read_b128 v[52:55], v244 offset:2576
	v_mov_b32_dpp v42, v42 row_ror:1 row_mask:0xf bank_mask:0xf
	v_mov_b32_dpp v43, v43 row_ror:1 row_mask:0xf bank_mask:0xf
	v_pk_fma_f32 v[40:41], v[90:91], v[42:43], v[40:41]
	v_pk_fma_f32 v[42:43], v[88:89], v[136:137], v[140:141]
	s_waitcnt lgkmcnt(0)
	v_pk_mul_f32 v[90:91], v[172:173], v[52:53]
	v_cndmask_b32_e32 v52, v20, v28, vcc
	v_cndmask_b32_e32 v53, v21, v29, vcc
	v_pk_mul_f32 v[36:37], v[170:171], v[36:37]
	v_pk_mul_f32 v[88:89], v[168:169], v[54:55]
	v_mov_b32_dpp v52, v52 row_ror:15 row_mask:0xf bank_mask:0xf
	v_mov_b32_dpp v53, v53 row_ror:15 row_mask:0xf bank_mask:0xf
	v_cndmask_b32_e32 v54, v22, v30, vcc
	v_cndmask_b32_e32 v55, v23, v31, vcc
	v_pk_mul_f32 v[38:39], v[166:167], v[38:39]
	v_cndmask_b32_e64 v36, v20, v36, s[6:7]
	v_cndmask_b32_e64 v37, v21, v37, s[6:7]
	v_mov_b32_dpp v54, v54 row_ror:15 row_mask:0xf bank_mask:0xf
	v_mov_b32_dpp v55, v55 row_ror:15 row_mask:0xf bank_mask:0xf
	s_waitcnt vmcnt(0)
	v_pk_fma_f32 v[52:53], v[72:73], v[52:53], v[76:77]
	v_mov_b32_dpp v36, v36 row_ror:1 row_mask:0xf bank_mask:0xf
	v_mov_b32_dpp v37, v37 row_ror:1 row_mask:0xf bank_mask:0xf
	v_cndmask_b32_e64 v38, v22, v38, s[6:7]
	v_cndmask_b32_e64 v39, v23, v39, s[6:7]
	v_pk_fma_f32 v[54:55], v[74:75], v[54:55], v[78:79]
	v_pk_fma_f32 v[96:97], v[68:69], v[20:21], v[52:53]
	v_mov_b32_dpp v38, v38 row_ror:1 row_mask:0xf bank_mask:0xf
	v_mov_b32_dpp v39, v39 row_ror:1 row_mask:0xf bank_mask:0xf
	v_pk_fma_f32 v[52:53], v[70:71], v[22:23], v[54:55]
	v_pk_fma_f32 v[54:55], v[64:65], v[36:37], v[96:97]
	v_cndmask_b32_e32 v36, v28, v24, vcc
	v_cndmask_b32_e32 v37, v29, v25, vcc
	v_pk_fma_f32 v[52:53], v[66:67], v[38:39], v[52:53]
	v_mov_b32_dpp v36, v36 row_ror:15 row_mask:0xf bank_mask:0xf
	v_mov_b32_dpp v37, v37 row_ror:15 row_mask:0xf bank_mask:0xf
	v_cndmask_b32_e32 v38, v30, v26, vcc
	v_cndmask_b32_e32 v39, v31, v27, vcc
	v_cndmask_b32_e64 v20, v28, v20, s[6:7]
	v_cndmask_b32_e64 v21, v29, v21, s[6:7]
	v_mov_b32_dpp v38, v38 row_ror:15 row_mask:0xf bank_mask:0xf
	v_mov_b32_dpp v39, v39 row_ror:15 row_mask:0xf bank_mask:0xf
	v_pk_fma_f32 v[36:37], v[72:73], v[36:37], v[76:77]
	v_mov_b32_dpp v20, v20 row_ror:1 row_mask:0xf bank_mask:0xf
	v_mov_b32_dpp v21, v21 row_ror:1 row_mask:0xf bank_mask:0xf
	v_cndmask_b32_e64 v22, v30, v22, s[6:7]
	v_cndmask_b32_e64 v23, v31, v23, s[6:7]
	v_pk_fma_f32 v[38:39], v[74:75], v[38:39], v[78:79]
	v_pk_fma_f32 v[96:97], v[68:69], v[28:29], v[36:37]
	v_mov_b32_dpp v22, v22 row_ror:1 row_mask:0xf bank_mask:0xf
	v_mov_b32_dpp v23, v23 row_ror:1 row_mask:0xf bank_mask:0xf
	v_pk_fma_f32 v[36:37], v[70:71], v[30:31], v[38:39]
	v_pk_fma_f32 v[38:39], v[64:65], v[20:21], v[96:97]
	v_cndmask_b32_e32 v21, v24, v16, vcc
	v_pk_fma_f32 v[36:37], v[66:67], v[22:23], v[36:37]
	v_cndmask_b32_e64 v20, v24, v28, s[6:7]
	v_mov_b32_dpp v22, v21 row_ror:15 row_mask:0xf bank_mask:0xf
	v_cndmask_b32_e64 v21, v25, v29, s[6:7]
	v_cndmask_b32_e32 v29, v26, v18, vcc
	v_cndmask_b32_e32 v23, v25, v17, vcc
	v_cndmask_b32_e64 v28, v26, v30, s[6:7]
	v_mov_b32_dpp v30, v29 row_ror:15 row_mask:0xf bank_mask:0xf
	v_cndmask_b32_e64 v29, v27, v31, s[6:7]
	v_cndmask_b32_e32 v31, v27, v19, vcc
	v_mov_b32_dpp v23, v23 row_ror:15 row_mask:0xf bank_mask:0xf
	v_pk_fma_f32 v[22:23], v[72:73], v[22:23], v[76:77]
	v_mov_b32_dpp v31, v31 row_ror:15 row_mask:0xf bank_mask:0xf
	v_pk_fma_f32 v[30:31], v[74:75], v[30:31], v[78:79]
	v_mov_b32_dpp v20, v20 row_ror:1 row_mask:0xf bank_mask:0xf
	v_mov_b32_dpp v21, v21 row_ror:1 row_mask:0xf bank_mask:0xf
	v_mov_b32_dpp v28, v28 row_ror:1 row_mask:0xf bank_mask:0xf
	v_mov_b32_dpp v29, v29 row_ror:1 row_mask:0xf bank_mask:0xf
	v_pk_fma_f32 v[22:23], v[68:69], v[24:25], v[22:23]
	v_pk_fma_f32 v[30:31], v[70:71], v[26:27], v[30:31]
	v_cndmask_b32_e32 v137, v6, v2, vcc
	v_pk_fma_f32 v[28:29], v[66:67], v[28:29], v[30:31]
	v_pk_fma_f32 v[30:31], v[64:65], v[20:21], v[22:23]
	v_cndmask_b32_e32 v21, v16, v90, vcc
	v_cndmask_b32_e32 v23, v17, v91, vcc
	v_cndmask_b32_e64 v20, v16, v24, s[6:7]
	v_mov_b32_dpp v22, v21 row_ror:15 row_mask:0xf bank_mask:0xf
	v_cndmask_b32_e64 v21, v17, v25, s[6:7]
	v_cndmask_b32_e32 v25, v18, v88, vcc
	v_mov_b32_dpp v23, v23 row_ror:15 row_mask:0xf bank_mask:0xf
	v_cndmask_b32_e64 v24, v18, v26, s[6:7]
	v_mov_b32_dpp v26, v25 row_ror:15 row_mask:0xf bank_mask:0xf
	v_cndmask_b32_e64 v25, v19, v27, s[6:7]
	v_cndmask_b32_e32 v27, v19, v89, vcc
	v_pk_fma_f32 v[22:23], v[72:73], v[22:23], v[76:77]
	v_mov_b32_dpp v20, v20 row_ror:1 row_mask:0xf bank_mask:0xf
	v_mov_b32_dpp v27, v27 row_ror:15 row_mask:0xf bank_mask:0xf
	v_mov_b32_dpp v21, v21 row_ror:1 row_mask:0xf bank_mask:0xf
	v_pk_fma_f32 v[26:27], v[74:75], v[26:27], v[78:79]
	v_pk_fma_f32 v[16:17], v[68:69], v[16:17], v[22:23]
	v_mov_b32_dpp v24, v24 row_ror:1 row_mask:0xf bank_mask:0xf
	v_mov_b32_dpp v25, v25 row_ror:1 row_mask:0xf bank_mask:0xf
	v_pk_fma_f32 v[18:19], v[70:71], v[18:19], v[26:27]
	v_pk_fma_f32 v[26:27], v[64:65], v[20:21], v[16:17]
	v_add_u32_e32 v16, 0xfffffe10, v245
	v_pk_fma_f32 v[24:25], v[66:67], v[24:25], v[18:19]
	ds_read_b128 v[20:23], v16
	ds_read_b128 v[16:19], v243 offset:2576
	v_cndmask_b32_e32 v139, v7, v3, vcc
	v_mov_b32_dpp v138, v137 row_ror:15 row_mask:0xf bank_mask:0xf
	v_cndmask_b32_e64 v136, v6, v14, s[6:7]
	s_waitcnt lgkmcnt(1)
	v_pk_mul_f32 v[20:21], v[180:181], v[20:21]
	v_pk_mul_f32 v[22:23], v[174:175], v[22:23]
	v_cndmask_b32_e64 v20, v8, v20, s[6:7]
	s_waitcnt lgkmcnt(0)
	v_pk_mul_f32 v[18:19], v[178:179], v[18:19]
	v_pk_mul_f32 v[16:17], v[182:183], v[16:17]
	v_mov_b32_dpp v88, v20 row_ror:1 row_mask:0xf bank_mask:0xf
	v_cndmask_b32_e32 v20, v8, v12, vcc
	v_mov_b32_dpp v139, v139 row_ror:15 row_mask:0xf bank_mask:0xf
	v_cndmask_b32_e32 v16, v0, v16, vcc
	v_mov_b32_dpp v90, v20 row_ror:15 row_mask:0xf bank_mask:0xf
	v_cndmask_b32_e64 v20, v9, v21, s[6:7]
	v_cndmask_b32_e64 v21, v5, v13, s[6:7]
	v_cndmask_b32_e32 v17, v1, v17, vcc
	v_mov_b32_dpp v89, v20 row_ror:1 row_mask:0xf bank_mask:0xf
	v_cndmask_b32_e32 v20, v9, v13, vcc
	v_cndmask_b32_e32 v18, v2, v18, vcc
	v_cndmask_b32_e32 v19, v3, v19, vcc
	v_mov_b32_dpp v91, v20 row_ror:15 row_mask:0xf bank_mask:0xf
	v_cndmask_b32_e64 v20, v10, v22, s[6:7]
	v_pk_fma_f32 v[138:139], v[74:75], v[138:139], v[78:79]
	v_mov_b32_dpp v16, v16 row_ror:15 row_mask:0xf bank_mask:0xf
	v_mov_b32_dpp v96, v20 row_ror:1 row_mask:0xf bank_mask:0xf
	v_cndmask_b32_e32 v20, v10, v14, vcc
	v_mov_b32_dpp v17, v17 row_ror:15 row_mask:0xf bank_mask:0xf
	v_mov_b32_dpp v18, v18 row_ror:15 row_mask:0xf bank_mask:0xf
	v_mov_b32_dpp v98, v20 row_ror:15 row_mask:0xf bank_mask:0xf
	v_cndmask_b32_e64 v20, v11, v23, s[6:7]
	v_mov_b32_dpp v23, v21 row_ror:1 row_mask:0xf bank_mask:0xf
	v_cndmask_b32_e32 v21, v5, v1, vcc
	v_mov_b32_dpp v97, v20 row_ror:1 row_mask:0xf bank_mask:0xf
	v_cndmask_b32_e32 v20, v11, v15, vcc
	v_mov_b32_dpp v21, v21 row_ror:15 row_mask:0xf bank_mask:0xf
	v_mov_b32_dpp v19, v19 row_ror:15 row_mask:0xf bank_mask:0xf
	v_mov_b32_dpp v99, v20 row_ror:15 row_mask:0xf bank_mask:0xf
	v_cndmask_b32_e64 v20, v12, v8, s[6:7]
	v_cndmask_b32_e64 v137, v7, v15, s[6:7]
	v_pk_fma_f32 v[18:19], v[74:75], v[18:19], v[78:79]
	v_mov_b32_dpp v100, v20 row_ror:1 row_mask:0xf bank_mask:0xf
	v_cndmask_b32_e32 v20, v12, v4, vcc
	v_pk_fma_f32 v[16:17], v[72:73], v[16:17], v[76:77]
	v_pk_fma_f32 v[90:91], v[72:73], v[90:91], v[76:77]
	v_mov_b32_dpp v102, v20 row_ror:15 row_mask:0xf bank_mask:0xf
	v_cndmask_b32_e64 v20, v13, v9, s[6:7]
	v_pk_fma_f32 v[16:17], v[68:69], v[0:1], v[16:17]
	v_pk_fma_f32 v[98:99], v[74:75], v[98:99], v[78:79]
	v_mov_b32_dpp v101, v20 row_ror:1 row_mask:0xf bank_mask:0xf
	v_cndmask_b32_e32 v20, v13, v5, vcc
	v_pk_fma_f32 v[90:91], v[68:69], v[8:9], v[90:91]
	v_pk_fma_f32 v[8:9], v[70:71], v[10:11], v[98:99]
	v_mov_b32_dpp v103, v20 row_ror:15 row_mask:0xf bank_mask:0xf
	v_cndmask_b32_e64 v20, v14, v10, s[6:7]
	v_pk_fma_f32 v[102:103], v[72:73], v[102:103], v[76:77]
	v_mov_b32_dpp v136, v136 row_ror:1 row_mask:0xf bank_mask:0xf
	v_mov_b32_dpp v104, v20 row_ror:1 row_mask:0xf bank_mask:0xf
	v_cndmask_b32_e32 v20, v14, v6, vcc
	v_pk_fma_f32 v[102:103], v[68:69], v[12:13], v[102:103]
	v_mov_b32_dpp v137, v137 row_ror:1 row_mask:0xf bank_mask:0xf
	v_mov_b32_dpp v106, v20 row_ror:15 row_mask:0xf bank_mask:0xf
	v_cndmask_b32_e64 v20, v15, v11, s[6:7]
	v_pk_fma_f32 v[10:11], v[64:65], v[88:89], v[90:91]
	v_pk_fma_f32 v[8:9], v[66:67], v[96:97], v[8:9]
	v_mov_b32_dpp v105, v20 row_ror:1 row_mask:0xf bank_mask:0xf
	v_cndmask_b32_e32 v20, v15, v7, vcc
	s_nop 1
	v_mov_b32_dpp v107, v20 row_ror:15 row_mask:0xf bank_mask:0xf
	v_cndmask_b32_e64 v20, v4, v12, s[6:7]
	v_pk_fma_f32 v[106:107], v[74:75], v[106:107], v[78:79]
	s_nop 0
	v_mov_b32_dpp v22, v20 row_ror:1 row_mask:0xf bank_mask:0xf
	v_cndmask_b32_e32 v20, v4, v0, vcc
	v_pk_fma_f32 v[12:13], v[70:71], v[14:15], v[106:107]
	v_pk_fma_f32 v[14:15], v[64:65], v[100:101], v[102:103]
	v_mov_b32_dpp v20, v20 row_ror:15 row_mask:0xf bank_mask:0xf
	v_pk_fma_f32 v[20:21], v[72:73], v[20:21], v[76:77]
	v_pk_fma_f32 v[12:13], v[66:67], v[104:105], v[12:13]
	v_pk_fma_f32 v[140:141], v[68:69], v[4:5], v[20:21]
	v_pk_fma_f32 v[20:21], v[70:71], v[6:7], v[138:139]
	v_cndmask_b32_e64 v4, v0, v4, s[6:7]
	v_cndmask_b32_e64 v5, v1, v5, s[6:7]
	v_cndmask_b32_e64 v6, v2, v6, s[6:7]
	v_cndmask_b32_e64 v7, v3, v7, s[6:7]
	v_mov_b32_dpp v4, v4 row_ror:1 row_mask:0xf bank_mask:0xf
	v_mov_b32_dpp v5, v5 row_ror:1 row_mask:0xf bank_mask:0xf
	v_mov_b32_dpp v6, v6 row_ror:1 row_mask:0xf bank_mask:0xf
	v_mov_b32_dpp v7, v7 row_ror:1 row_mask:0xf bank_mask:0xf
	v_pk_fma_f32 v[2:3], v[70:71], v[2:3], v[18:19]
	v_pk_fma_f32 v[22:23], v[64:65], v[22:23], v[140:141]
	v_pk_fma_f32 v[0:1], v[66:67], v[6:7], v[2:3]
	v_pk_fma_f32 v[2:3], v[64:65], v[4:5], v[16:17]
	v_mul_f32_e32 v4, 0xbfb8aa3b, v204
	v_mul_f32_e32 v5, 0xbfb8aa3b, v205
	v_exp_f32_e32 v4, v4
	v_exp_f32_e32 v5, v5
	v_pk_fma_f32 v[20:21], v[66:67], v[136:137], v[20:21]
	s_lshl_b32 s6, s30, 8
	v_add_f32_e32 v4, 1.0, v4
	v_add_f32_e32 v5, 1.0, v5
	v_rcp_f32_e32 v4, v4
	v_rcp_f32_e32 v5, v5
	s_add_i32 s6, s6, s83
	v_mul_f32_e32 v17, 0xbfb8aa3b, v200
	v_add_u32_e32 v16, s6, v242
	v_pk_mul_f32 v[4:5], v[204:205], v[4:5]
	v_readlane_b32 s6, v253, 54
	v_pk_mul_f32 v[4:5], v[4:5], v[134:135]
	v_exp_f32_e32 v17, v17
	v_cvt_pk_bf16_f32 v64, v4, v5
	v_mul_f32_e32 v4, 0xbfb8aa3b, v202
	v_mul_f32_e32 v5, 0xbfb8aa3b, v203
	v_exp_f32_e32 v4, v4
	v_exp_f32_e32 v5, v5
	v_readlane_b32 s7, v253, 55
	v_lshlrev_b64 v[6:7], 1, v[188:189]
	v_add_f32_e32 v4, 1.0, v4
	v_add_f32_e32 v5, 1.0, v5
	v_rcp_f32_e32 v4, v4
	v_rcp_f32_e32 v5, v5
	v_add_f32_e32 v17, 1.0, v17
	s_andn2_b64 vcc, exec, s[4:5]
	v_pk_mul_f32 v[4:5], v[202:203], v[4:5]
	s_nop 0
	v_pk_mul_f32 v[4:5], v[4:5], v[132:133]
	s_nop 0
	v_cvt_pk_bf16_f32 v65, v4, v5
	v_mul_f32_e32 v4, 0xbfb8aa3b, v158
	v_mul_f32_e32 v5, 0xbfb8aa3b, v159
	v_exp_f32_e32 v4, v4
	v_exp_f32_e32 v5, v5
	v_add_f32_e32 v4, 1.0, v4
	v_add_f32_e32 v5, 1.0, v5
	v_rcp_f32_e32 v4, v4
	v_rcp_f32_e32 v5, v5
	s_nop 0
	v_pk_mul_f32 v[4:5], v[158:159], v[4:5]
	s_nop 0
	v_pk_mul_f32 v[4:5], v[4:5], v[54:55]
	s_nop 0
	v_cvt_pk_bf16_f32 v66, v4, v5
	v_mul_f32_e32 v4, 0xbfb8aa3b, v156
	v_mul_f32_e32 v5, 0xbfb8aa3b, v157
	v_exp_f32_e32 v4, v4
	v_exp_f32_e32 v5, v5
	v_add_f32_e32 v4, 1.0, v4
	v_add_f32_e32 v5, 1.0, v5
	v_rcp_f32_e32 v4, v4
	v_rcp_f32_e32 v5, v5
	s_nop 0
	v_pk_mul_f32 v[4:5], v[156:157], v[4:5]
	s_nop 0
	v_pk_mul_f32 v[4:5], v[4:5], v[52:53]
	s_nop 0
	v_cvt_pk_bf16_f32 v67, v4, v5
	v_mov_b64_e32 v[4:5], s[6:7]
	v_mad_i64_i32 v[18:19], s[6:7], v16, s10, v[4:5]
	v_lshl_add_u64 v[18:19], v[18:19], 0, v[6:7]
	global_store_dwordx4 v[18:19], v[64:67], off sc1
	v_rcp_f32_e32 v18, v17
	v_mul_f32_e32 v17, 0xbfb8aa3b, v201
	v_exp_f32_e32 v17, v17
	s_nop 0
	v_add_f32_e32 v17, 1.0, v17
	v_rcp_f32_e32 v19, v17
	v_mul_f32_e32 v17, 0xbfb8aa3b, v198
	v_exp_f32_e32 v17, v17
	v_pk_mul_f32 v[18:19], v[200:201], v[18:19]
	s_nop 0
	v_pk_mul_f32 v[18:19], v[18:19], v[130:131]
	v_add_f32_e32 v17, 1.0, v17
	v_cvt_pk_bf16_f32 v52, v18, v19
	v_rcp_f32_e32 v18, v17
	v_mul_f32_e32 v17, 0xbfb8aa3b, v199
	v_exp_f32_e32 v17, v17
	s_nop 0
	v_add_f32_e32 v17, 1.0, v17
	v_rcp_f32_e32 v19, v17
	v_mul_f32_e32 v17, 0xbfb8aa3b, v150
	v_exp_f32_e32 v17, v17
	v_pk_mul_f32 v[18:19], v[198:199], v[18:19]
	s_nop 0
	v_pk_mul_f32 v[18:19], v[18:19], v[128:129]
	v_add_f32_e32 v17, 1.0, v17
	v_cvt_pk_bf16_f32 v53, v18, v19
	v_rcp_f32_e32 v18, v17
	v_mul_f32_e32 v17, 0xbfb8aa3b, v151
	v_exp_f32_e32 v17, v17
	s_nop 0
	v_add_f32_e32 v17, 1.0, v17
	v_rcp_f32_e32 v19, v17
	v_mul_f32_e32 v17, 0xbfb8aa3b, v148
	v_exp_f32_e32 v17, v17
	v_pk_mul_f32 v[18:19], v[150:151], v[18:19]
	s_nop 0
	v_pk_mul_f32 v[18:19], v[18:19], v[38:39]
	v_add_f32_e32 v17, 1.0, v17
	v_cvt_pk_bf16_f32 v54, v18, v19
	v_rcp_f32_e32 v18, v17
	v_mul_f32_e32 v17, 0xbfb8aa3b, v149
	v_exp_f32_e32 v17, v17
	s_nop 0
	v_add_f32_e32 v17, 1.0, v17
	v_rcp_f32_e32 v19, v17
	v_add_u32_e32 v17, 16, v16
	v_pk_mul_f32 v[18:19], v[148:149], v[18:19]
	s_nop 0
	v_pk_mul_f32 v[18:19], v[18:19], v[36:37]
	s_nop 0
	v_cvt_pk_bf16_f32 v55, v18, v19
	v_mad_i64_i32 v[18:19], s[6:7], v17, s10, v[4:5]
	v_mul_f32_e32 v17, 0xbfb8aa3b, v196
	v_exp_f32_e32 v17, v17
	v_lshl_add_u64 v[18:19], v[18:19], 0, v[6:7]
	global_store_dwordx4 v[18:19], v[52:55], off sc1
	v_add_f32_e32 v17, 1.0, v17
	v_rcp_f32_e32 v18, v17
	v_mul_f32_e32 v17, 0xbfb8aa3b, v197
	v_exp_f32_e32 v17, v17
	s_nop 0
	v_add_f32_e32 v17, 1.0, v17
	v_rcp_f32_e32 v19, v17
	v_mul_f32_e32 v17, 0xbfb8aa3b, v194
	v_exp_f32_e32 v17, v17
	v_pk_mul_f32 v[18:19], v[196:197], v[18:19]
	s_nop 0
	v_pk_mul_f32 v[18:19], v[18:19], v[62:63]
	v_add_f32_e32 v17, 1.0, v17
	v_cvt_pk_bf16_f32 v36, v18, v19
	v_rcp_f32_e32 v18, v17
	v_mul_f32_e32 v17, 0xbfb8aa3b, v195
	v_exp_f32_e32 v17, v17
	s_nop 0
	v_add_f32_e32 v17, 1.0, v17
	v_rcp_f32_e32 v19, v17
	v_mul_f32_e32 v17, 0xbfb8aa3b, v110
	v_exp_f32_e32 v17, v17
	v_pk_mul_f32 v[18:19], v[194:195], v[18:19]
	s_nop 0
	v_pk_mul_f32 v[18:19], v[18:19], v[60:61]
	v_add_f32_e32 v17, 1.0, v17
	v_cvt_pk_bf16_f32 v37, v18, v19
	v_rcp_f32_e32 v18, v17
	v_mul_f32_e32 v17, 0xbfb8aa3b, v111
	v_exp_f32_e32 v17, v17
	s_nop 0
	v_add_f32_e32 v17, 1.0, v17
	v_rcp_f32_e32 v19, v17
	v_mul_f32_e32 v17, 0xbfb8aa3b, v108
	v_exp_f32_e32 v17, v17
	v_pk_mul_f32 v[18:19], v[110:111], v[18:19]
	s_nop 0
	v_pk_mul_f32 v[18:19], v[18:19], v[30:31]
	v_add_f32_e32 v17, 1.0, v17
	v_cvt_pk_bf16_f32 v38, v18, v19
	v_rcp_f32_e32 v18, v17
	v_mul_f32_e32 v17, 0xbfb8aa3b, v109
	v_exp_f32_e32 v17, v17
	s_nop 0
	v_add_f32_e32 v17, 1.0, v17
	v_rcp_f32_e32 v19, v17
	v_add_u32_e32 v17, 32, v16
	v_pk_mul_f32 v[18:19], v[108:109], v[18:19]
	s_nop 0
	v_pk_mul_f32 v[18:19], v[18:19], v[28:29]
	s_nop 0
	v_cvt_pk_bf16_f32 v39, v18, v19
	v_mad_i64_i32 v[18:19], s[6:7], v17, s10, v[4:5]
	v_mul_f32_e32 v17, 0xbfb8aa3b, v192
	v_exp_f32_e32 v17, v17
	v_lshl_add_u64 v[18:19], v[18:19], 0, v[6:7]
	global_store_dwordx4 v[18:19], v[36:39], off sc1
	v_add_f32_e32 v17, 1.0, v17
	v_rcp_f32_e32 v18, v17
	v_mul_f32_e32 v17, 0xbfb8aa3b, v193
	v_exp_f32_e32 v17, v17
	s_nop 0
	v_add_f32_e32 v17, 1.0, v17
	v_rcp_f32_e32 v19, v17
	v_mul_f32_e32 v17, 0xbfb8aa3b, v190
	v_exp_f32_e32 v17, v17
	v_pk_mul_f32 v[18:19], v[192:193], v[18:19]
	s_nop 0
	v_pk_mul_f32 v[18:19], v[18:19], v[58:59]
	v_add_f32_e32 v17, 1.0, v17
	v_cvt_pk_bf16_f32 v28, v18, v19
	v_rcp_f32_e32 v18, v17
	v_mul_f32_e32 v17, 0xbfb8aa3b, v191
	v_exp_f32_e32 v17, v17
	s_nop 0
	v_add_f32_e32 v17, 1.0, v17
	v_rcp_f32_e32 v19, v17
	v_mul_f32_e32 v17, 0xbfb8aa3b, v94
	v_exp_f32_e32 v17, v17
	v_pk_mul_f32 v[18:19], v[190:191], v[18:19]
	s_nop 0
	v_pk_mul_f32 v[18:19], v[18:19], v[56:57]
	v_add_f32_e32 v17, 1.0, v17
	v_cvt_pk_bf16_f32 v29, v18, v19
	v_rcp_f32_e32 v18, v17
	v_mul_f32_e32 v17, 0xbfb8aa3b, v95
	v_exp_f32_e32 v17, v17
	s_nop 0
	v_add_f32_e32 v17, 1.0, v17
	v_rcp_f32_e32 v19, v17
	v_mul_f32_e32 v17, 0xbfb8aa3b, v92
	v_exp_f32_e32 v17, v17
	v_pk_mul_f32 v[18:19], v[94:95], v[18:19]
	s_nop 0
	v_pk_mul_f32 v[18:19], v[18:19], v[26:27]
	v_add_f32_e32 v17, 1.0, v17
	v_cvt_pk_bf16_f32 v30, v18, v19
	v_rcp_f32_e32 v18, v17
	v_mul_f32_e32 v17, 0xbfb8aa3b, v93
	v_exp_f32_e32 v17, v17
	s_nop 0
	v_add_f32_e32 v17, 1.0, v17
	v_rcp_f32_e32 v19, v17
	v_add_u32_e32 v17, 48, v16
	v_pk_mul_f32 v[18:19], v[92:93], v[18:19]
	s_nop 0
	v_pk_mul_f32 v[18:19], v[18:19], v[24:25]
	s_nop 0
	v_cvt_pk_bf16_f32 v31, v18, v19
	v_mad_i64_i32 v[18:19], s[6:7], v17, s10, v[4:5]
	v_lshl_add_u64 v[18:19], v[18:19], 0, v[6:7]
	global_store_dwordx4 v[18:19], v[28:31], off sc1
	v_mul_f32_e32 v18, 0xbfb8aa3b, v126
	v_mul_f32_e32 v19, 0xbfb8aa3b, v127
	v_exp_f32_e32 v18, v18
	v_exp_f32_e32 v19, v19
	v_add_u32_e32 v17, 0x80, v16
	v_add_f32_e32 v18, 1.0, v18
	v_add_f32_e32 v19, 1.0, v19
	v_rcp_f32_e32 v18, v18
	v_rcp_f32_e32 v19, v19
	s_nop 0
	v_pk_mul_f32 v[18:19], v[126:127], v[18:19]
	s_nop 0
	v_pk_mul_f32 v[18:19], v[18:19], v[50:51]
	s_nop 0
	v_cvt_pk_bf16_f32 v24, v18, v19
	v_mul_f32_e32 v18, 0xbfb8aa3b, v124
	v_mul_f32_e32 v19, 0xbfb8aa3b, v125
	v_exp_f32_e32 v18, v18
	v_exp_f32_e32 v19, v19
	v_add_f32_e32 v18, 1.0, v18
	v_add_f32_e32 v19, 1.0, v19
	v_rcp_f32_e32 v18, v18
	v_rcp_f32_e32 v19, v19
	s_nop 0
	v_pk_mul_f32 v[18:19], v[124:125], v[18:19]
	s_nop 0
	v_pk_mul_f32 v[18:19], v[18:19], v[48:49]
	s_nop 0
	v_cvt_pk_bf16_f32 v25, v18, v19
	v_mul_f32_e32 v18, 0xbfb8aa3b, v154
	v_mul_f32_e32 v19, 0xbfb8aa3b, v155
	v_exp_f32_e32 v18, v18
	v_exp_f32_e32 v19, v19
	v_add_f32_e32 v18, 1.0, v18
	v_add_f32_e32 v19, 1.0, v19
	v_rcp_f32_e32 v18, v18
	v_rcp_f32_e32 v19, v19
	s_nop 0
	v_pk_mul_f32 v[18:19], v[154:155], v[18:19]
	s_nop 0
	v_pk_mul_f32 v[10:11], v[18:19], v[10:11]
	s_nop 0
	v_cvt_pk_bf16_f32 v26, v10, v11
	v_mul_f32_e32 v10, 0xbfb8aa3b, v152
	v_mul_f32_e32 v11, 0xbfb8aa3b, v153
	v_exp_f32_e32 v10, v10
	v_exp_f32_e32 v11, v11
	v_add_f32_e32 v10, 1.0, v10
	v_add_f32_e32 v11, 1.0, v11
	v_rcp_f32_e32 v10, v10
	v_rcp_f32_e32 v11, v11
	s_nop 0
	v_pk_mul_f32 v[10:11], v[152:153], v[10:11]
	s_nop 0
	v_pk_mul_f32 v[8:9], v[10:11], v[8:9]
	s_nop 0
	v_cvt_pk_bf16_f32 v27, v8, v9
	v_mad_i64_i32 v[8:9], s[6:7], v17, s10, v[4:5]
	v_lshl_add_u64 v[8:9], v[8:9], 0, v[6:7]
	global_store_dwordx4 v[8:9], v[24:27], off sc1
	v_mul_f32_e32 v8, 0xbfb8aa3b, v122
	v_mul_f32_e32 v9, 0xbfb8aa3b, v123
	v_exp_f32_e32 v8, v8
	v_exp_f32_e32 v9, v9
	v_add_f32_e32 v8, 1.0, v8
	v_add_f32_e32 v9, 1.0, v9
	v_rcp_f32_e32 v8, v8
	v_rcp_f32_e32 v9, v9
	s_nop 0
	v_pk_mul_f32 v[8:9], v[122:123], v[8:9]
	s_nop 0
	v_pk_mul_f32 v[8:9], v[8:9], v[46:47]
	s_nop 0
	v_cvt_pk_bf16_f32 v8, v8, v9
	v_mul_f32_e32 v9, 0xbfb8aa3b, v120
	v_exp_f32_e32 v9, v9
	s_nop 0
	v_add_f32_e32 v9, 1.0, v9
	v_rcp_f32_e32 v10, v9
	v_mul_f32_e32 v9, 0xbfb8aa3b, v121
	v_exp_f32_e32 v9, v9
	s_nop 0
	v_add_f32_e32 v9, 1.0, v9
	v_rcp_f32_e32 v11, v9
	s_nop 0
	v_pk_mul_f32 v[10:11], v[120:121], v[10:11]
	s_nop 0
	v_pk_mul_f32 v[10:11], v[10:11], v[44:45]
	s_nop 0
	v_cvt_pk_bf16_f32 v9, v10, v11
	v_mul_f32_e32 v10, 0xbfb8aa3b, v146
	v_mul_f32_e32 v11, 0xbfb8aa3b, v147
	v_exp_f32_e32 v10, v10
	v_exp_f32_e32 v11, v11
	v_add_f32_e32 v10, 1.0, v10
	v_add_f32_e32 v11, 1.0, v11
	v_rcp_f32_e32 v10, v10
	v_rcp_f32_e32 v11, v11
	s_nop 0
	v_pk_mul_f32 v[10:11], v[146:147], v[10:11]
	s_nop 0
	v_pk_mul_f32 v[10:11], v[10:11], v[14:15]
	s_nop 0
	v_cvt_pk_bf16_f32 v10, v10, v11
	v_mul_f32_e32 v11, 0xbfb8aa3b, v144
	v_exp_f32_e32 v11, v11
	s_nop 0
	v_add_f32_e32 v11, 1.0, v11
	v_rcp_f32_e32 v14, v11
	v_mul_f32_e32 v11, 0xbfb8aa3b, v145
	v_exp_f32_e32 v11, v11
	s_nop 0
	v_add_f32_e32 v11, 1.0, v11
	v_rcp_f32_e32 v15, v11
	s_nop 0
	v_pk_mul_f32 v[14:15], v[144:145], v[14:15]
	s_nop 0
	v_pk_mul_f32 v[12:13], v[14:15], v[12:13]
	s_nop 0
	v_cvt_pk_bf16_f32 v11, v12, v13
	v_add_u32_e32 v12, 0x90, v16
	v_mad_i64_i32 v[12:13], s[6:7], v12, s10, v[4:5]
	v_lshl_add_u64 v[12:13], v[12:13], 0, v[6:7]
	global_store_dwordx4 v[12:13], v[8:11], off sc1
	s_nop 1
	v_mul_f32_e32 v8, 0xbfb8aa3b, v118
	v_mul_f32_e32 v9, 0xbfb8aa3b, v119
	v_exp_f32_e32 v8, v8
	v_exp_f32_e32 v9, v9
	v_add_f32_e32 v8, 1.0, v8
	v_add_f32_e32 v9, 1.0, v9
	v_rcp_f32_e32 v8, v8
	v_rcp_f32_e32 v9, v9
	s_nop 0
	v_pk_mul_f32 v[8:9], v[118:119], v[8:9]
	s_nop 0
	v_pk_mul_f32 v[8:9], v[8:9], v[42:43]
	s_nop 0
	v_cvt_pk_bf16_f32 v8, v8, v9
	v_mul_f32_e32 v9, 0xbfb8aa3b, v116
	v_exp_f32_e32 v9, v9
	s_nop 0
	v_add_f32_e32 v9, 1.0, v9
	v_rcp_f32_e32 v10, v9
	v_mul_f32_e32 v9, 0xbfb8aa3b, v117
	v_exp_f32_e32 v9, v9
	s_nop 0
	v_add_f32_e32 v9, 1.0, v9
	v_rcp_f32_e32 v11, v9
	s_nop 0
	v_pk_mul_f32 v[10:11], v[116:117], v[10:11]
	s_nop 0
	v_pk_mul_f32 v[10:11], v[10:11], v[40:41]
	s_nop 0
	v_cvt_pk_bf16_f32 v9, v10, v11
	v_mul_f32_e32 v10, 0xbfb8aa3b, v86
	v_mul_f32_e32 v11, 0xbfb8aa3b, v87
	v_exp_f32_e32 v10, v10
	v_exp_f32_e32 v11, v11
	v_add_f32_e32 v10, 1.0, v10
	v_add_f32_e32 v11, 1.0, v11
	v_rcp_f32_e32 v10, v10
	v_rcp_f32_e32 v11, v11
	s_nop 0
	v_pk_mul_f32 v[10:11], v[86:87], v[10:11]
	s_nop 0
	v_pk_mul_f32 v[10:11], v[10:11], v[22:23]
	s_nop 0
	v_cvt_pk_bf16_f32 v10, v10, v11
	v_mul_f32_e32 v11, 0xbfb8aa3b, v84
	v_exp_f32_e32 v11, v11
	s_nop 0
	v_add_f32_e32 v11, 1.0, v11
	v_rcp_f32_e32 v12, v11
	v_mul_f32_e32 v11, 0xbfb8aa3b, v85
	v_exp_f32_e32 v11, v11
	s_nop 0
	v_add_f32_e32 v11, 1.0, v11
	v_rcp_f32_e32 v13, v11
	s_nop 0
	v_pk_mul_f32 v[12:13], v[84:85], v[12:13]
	s_nop 0
	v_pk_mul_f32 v[12:13], v[12:13], v[20:21]
	s_nop 0
	v_cvt_pk_bf16_f32 v11, v12, v13
	v_add_u32_e32 v12, 0xa0, v16
	v_mad_i64_i32 v[12:13], s[6:7], v12, s10, v[4:5]
	v_lshl_add_u64 v[12:13], v[12:13], 0, v[6:7]
	global_store_dwordx4 v[12:13], v[8:11], off sc1
	s_nop 1
	v_mul_f32_e32 v8, 0xbfb8aa3b, v114
	v_mul_f32_e32 v9, 0xbfb8aa3b, v115
	v_exp_f32_e32 v8, v8
	v_exp_f32_e32 v9, v9
	v_add_f32_e32 v8, 1.0, v8
	v_add_f32_e32 v9, 1.0, v9
	v_rcp_f32_e32 v8, v8
	v_rcp_f32_e32 v9, v9
	s_nop 0
	v_pk_mul_f32 v[8:9], v[114:115], v[8:9]
	s_nop 0
	v_pk_mul_f32 v[8:9], v[8:9], v[34:35]
	s_nop 0
	v_cvt_pk_bf16_f32 v8, v8, v9
	v_mul_f32_e32 v9, 0xbfb8aa3b, v112
	v_exp_f32_e32 v9, v9
	s_nop 0
	v_add_f32_e32 v9, 1.0, v9
	v_rcp_f32_e32 v10, v9
	v_mul_f32_e32 v9, 0xbfb8aa3b, v113
	v_exp_f32_e32 v9, v9
	s_nop 0
	v_add_f32_e32 v9, 1.0, v9
	v_rcp_f32_e32 v11, v9
	s_nop 0
	v_pk_mul_f32 v[10:11], v[112:113], v[10:11]
	s_nop 0
	v_pk_mul_f32 v[10:11], v[10:11], v[32:33]
	s_nop 0
	v_cvt_pk_bf16_f32 v9, v10, v11
	v_mul_f32_e32 v10, 0xbfb8aa3b, v82
	v_mul_f32_e32 v11, 0xbfb8aa3b, v83
	v_exp_f32_e32 v10, v10
	v_exp_f32_e32 v11, v11
	v_add_f32_e32 v10, 1.0, v10
	v_add_f32_e32 v11, 1.0, v11
	v_rcp_f32_e32 v10, v10
	v_rcp_f32_e32 v11, v11
	s_nop 0
	v_pk_mul_f32 v[10:11], v[82:83], v[10:11]
	s_nop 0
	v_pk_mul_f32 v[2:3], v[10:11], v[2:3]
	s_nop 0
	v_cvt_pk_bf16_f32 v10, v2, v3
	v_mul_f32_e32 v2, 0xbfb8aa3b, v80
	v_mul_f32_e32 v3, 0xbfb8aa3b, v81
	v_exp_f32_e32 v2, v2
	v_exp_f32_e32 v3, v3
	v_add_f32_e32 v2, 1.0, v2
	v_add_f32_e32 v3, 1.0, v3
	v_rcp_f32_e32 v2, v2
	v_rcp_f32_e32 v3, v3
	s_nop 0
	v_pk_mul_f32 v[2:3], v[80:81], v[2:3]
	s_nop 0
	v_pk_mul_f32 v[0:1], v[2:3], v[0:1]
	s_nop 0
	v_cvt_pk_bf16_f32 v11, v0, v1
	v_add_u32_e32 v0, 0xb0, v16
	v_mad_i64_i32 v[0:1], s[6:7], v0, s10, v[4:5]
	v_lshl_add_u64 v[0:1], v[0:1], 0, v[6:7]
	s_mov_b64 s[6:7], -1
	global_store_dwordx4 v[0:1], v[8:11], off sc1
	s_cbranch_vccnz .LBB0_1378
	s_andn2_b64 vcc, exec, s[14:15]
	s_cbranch_vccnz .LBB0_1377
	s_barrier
	s_branch .LBB0_1377

.LBB0_1440:
	s_or_b64 exec, exec, s[6:7]
	s_waitcnt vmcnt(0)
	v_mul_f32_e32 v6, v6, v7
	ds_write_b32 v44, v6 offset:8184
	s_waitcnt lgkmcnt(0)
	s_sub_i32 s6, 0, s5
	ds_read2_b32 v[50:51], v43 offset0:33 offset1:41
	ds_read2_b32 v[52:53], v43 offset1:8
	ds_read2_b32 v[54:55], v43 offset0:66 offset1:74
	ds_read2_b32 v[56:57], v43 offset0:99 offset1:107
	ds_read2_b32 v[58:59], v43 offset0:132 offset1:140
	ds_read2_b32 v[60:61], v43 offset0:165 offset1:173
	ds_read2_b32 v[62:63], v43 offset0:198 offset1:206
	ds_read2_b32 v[64:65], v43 offset0:231 offset1:239
	s_add_i32 s6, s6, s9
	v_add_u32_e32 v66, s6, v9
	s_ashr_i32 s5, s4, 31
	v_ashrrev_i32_e32 v67, 31, v66
	v_lshl_add_u64 v[6:7], s[4:5], 1, v[4:5]
	v_lshlrev_b64 v[68:69], 12, v[66:67]
	s_waitcnt lgkmcnt(6)
	v_cvt_pk_bf16_f32 v46, v52, v50
	s_waitcnt lgkmcnt(4)
	v_cvt_pk_bf16_f32 v47, v54, v56
	s_waitcnt lgkmcnt(2)
	v_cvt_pk_bf16_f32 v48, v58, v60
	s_waitcnt lgkmcnt(0)
	v_cvt_pk_bf16_f32 v49, v62, v64
	v_lshl_add_u64 v[68:69], v[6:7], 0, v[68:69]
	v_add_u32_e32 v50, 8, v66
	global_store_dwordx4 v[68:69], v[46:49], off sc1
	v_add_u32_e32 v68, 16, v66
	v_ashrrev_i32_e32 v69, 31, v68
	v_cvt_pk_bf16_f32 v46, v53, v51
	v_ashrrev_i32_e32 v51, 31, v50
	v_lshlrev_b64 v[50:51], 12, v[50:51]
	v_cvt_pk_bf16_f32 v47, v55, v57
	v_cvt_pk_bf16_f32 v48, v59, v61
	v_cvt_pk_bf16_f32 v49, v63, v65
	v_lshl_add_u64 v[50:51], v[6:7], 0, v[50:51]
	global_store_dwordx4 v[50:51], v[46:49], off sc1
	ds_read2_b32 v[50:51], v43 offset0:49 offset1:57
	ds_read2_b32 v[52:53], v43 offset0:16 offset1:24
	ds_read2_b32 v[54:55], v43 offset0:82 offset1:90
	ds_read2_b32 v[56:57], v43 offset0:115 offset1:123
	ds_read2_b32 v[58:59], v43 offset0:148 offset1:156
	ds_read2_b32 v[60:61], v43 offset0:181 offset1:189
	ds_read2_b32 v[62:63], v43 offset0:214 offset1:222
	ds_read2_b32 v[64:65], v43 offset0:247 offset1:255
	v_lshlrev_b64 v[68:69], 12, v[68:69]
	s_waitcnt lgkmcnt(6)
	v_cvt_pk_bf16_f32 v46, v52, v50
	s_waitcnt lgkmcnt(4)
	v_cvt_pk_bf16_f32 v47, v54, v56
	s_waitcnt lgkmcnt(2)
	v_cvt_pk_bf16_f32 v48, v58, v60
	s_waitcnt lgkmcnt(0)
	v_cvt_pk_bf16_f32 v49, v62, v64
	v_lshl_add_u64 v[68:69], v[6:7], 0, v[68:69]
	v_add_u32_e32 v50, 24, v66
	global_store_dwordx4 v[68:69], v[46:49], off sc1
	s_add_i32 s4, s13, 0x680
	s_add_i32 s9, s9, 0xd000
	v_cvt_pk_bf16_f32 v46, v53, v51
	v_ashrrev_i32_e32 v51, 31, v50
	v_lshlrev_b64 v[50:51], 12, v[50:51]
	v_cvt_pk_bf16_f32 v47, v55, v57
	v_cvt_pk_bf16_f32 v48, v59, v61
	v_cvt_pk_bf16_f32 v49, v63, v65
	v_lshl_add_u64 v[6:7], v[6:7], 0, v[50:51]
	global_store_dwordx4 v[6:7], v[46:49], off sc1
	s_waitcnt lgkmcnt(0)
	s_cmpk_lt_i32 s13, 0x180
	s_mov_b32 s13, s4
	s_cbranch_scc0 .LBB0_1696

.LBB0_1698:
	s_mul_hi_i32 s4, s10, 0x2e8ba2e9
	s_lshr_b32 s5, s4, 31
	s_ashr_i32 s4, s4, 6
	s_add_i32 s6, s4, s5
	s_mul_i32 s4, s6, 0xfffffea0
	s_add_i32 s5, s10, s4
	s_lshl_b32 s4, s6, 6
	s_mulk_i32 s6, 0xd400
	s_add_i32 s6, s9, s6
	s_ashr_i32 s7, s6, 31
	v_or_b32_e32 v34, s4, v8
	v_lshl_add_u64 v[44:45], s[6:7], 2, v[2:3]
	v_mad_i64_i32 v[16:17], s[14:15], v34, s93, v[44:45]
	v_or_b32_e32 v15, 2, v34
	global_load_dword v43, v[16:17], off nt
	v_mad_i64_i32 v[16:17], s[14:15], v15, s93, v[44:45]
	v_or_b32_e32 v15, 4, v34
	global_load_dword v48, v[16:17], off nt
	v_mad_i64_i32 v[16:17], s[14:15], v15, s93, v[44:45]
	v_or_b32_e32 v15, 6, v34
	global_load_dword v49, v[16:17], off nt
	v_mad_i64_i32 v[16:17], s[14:15], v15, s93, v[44:45]
	v_or_b32_e32 v15, 8, v34
	global_load_dword v50, v[16:17], off nt
	v_mad_i64_i32 v[16:17], s[14:15], v15, s93, v[44:45]
	v_or_b32_e32 v15, 10, v34
	global_load_dword v35, v[16:17], off nt
	v_mad_i64_i32 v[16:17], s[14:15], v15, s93, v[44:45]
	v_or_b32_e32 v15, 12, v34
	global_load_dword v37, v[16:17], off nt
	v_mad_i64_i32 v[16:17], s[14:15], v15, s93, v[44:45]
	v_or_b32_e32 v15, 14, v34
	global_load_dword v39, v[16:17], off nt
	v_mad_i64_i32 v[16:17], s[14:15], v15, s93, v[44:45]
	v_or_b32_e32 v15, 16, v34
	global_load_dword v41, v[16:17], off nt
	v_mad_i64_i32 v[16:17], s[14:15], v15, s93, v[44:45]
	v_or_b32_e32 v15, 18, v34
	global_load_dword v36, v[16:17], off nt
	v_mad_i64_i32 v[16:17], s[14:15], v15, s93, v[44:45]
	v_or_b32_e32 v15, 20, v34
	global_load_dword v38, v[16:17], off nt
	v_mad_i64_i32 v[16:17], s[14:15], v15, s93, v[44:45]
	v_or_b32_e32 v15, 22, v34
	global_load_dword v40, v[16:17], off nt
	v_mad_i64_i32 v[16:17], s[14:15], v15, s93, v[44:45]
	v_or_b32_e32 v15, 24, v34
	global_load_dword v42, v[16:17], off nt
	v_mad_i64_i32 v[16:17], s[14:15], v15, s93, v[44:45]
	global_load_dword v15, v[16:17], off nt
	v_or_b32_e32 v16, 26, v34
	v_mad_i64_i32 v[16:17], s[14:15], v16, s93, v[44:45]
	global_load_dword v18, v[16:17], off nt
	v_or_b32_e32 v16, 28, v34
	v_mad_i64_i32 v[16:17], s[14:15], v16, s93, v[44:45]
	global_load_dword v22, v[16:17], off nt
	v_or_b32_e32 v16, 30, v34
	v_mad_i64_i32 v[16:17], s[14:15], v16, s93, v[44:45]
	global_load_dword v28, v[16:17], off nt
	v_or_b32_e32 v16, 32, v34
	v_mad_i64_i32 v[16:17], s[14:15], v16, s93, v[44:45]
	global_load_dword v16, v[16:17], off nt
	v_or_b32_e32 v17, 34, v34
	v_mad_i64_i32 v[20:21], s[14:15], v17, s93, v[44:45]
	v_or_b32_e32 v17, 36, v34
	v_mad_i64_i32 v[24:25], s[14:15], v17, s93, v[44:45]
	v_or_b32_e32 v17, 38, v34
	v_mad_i64_i32 v[26:27], s[14:15], v17, s93, v[44:45]
	v_or_b32_e32 v17, 40, v34
	global_load_dword v20, v[20:21], off nt
	v_or_b32_e32 v19, 42, v34
	global_load_dword v24, v[24:25], off nt
	v_or_b32_e32 v31, 60, v34
	global_load_dword v30, v[26:27], off nt
	v_mad_i64_i32 v[26:27], s[14:15], v17, s93, v[44:45]
	global_load_dword v17, v[26:27], off nt
	v_mad_i64_i32 v[26:27], s[14:15], v19, s93, v[44:45]
	v_or_b32_e32 v19, 44, v34
	global_load_dword v23, v[26:27], off nt
	v_mad_i64_i32 v[26:27], s[14:15], v19, s93, v[44:45]
	v_or_b32_e32 v19, 46, v34
	v_mad_i64_i32 v[32:33], s[14:15], v19, s93, v[44:45]
	v_or_b32_e32 v19, 48, v34
	v_mad_i64_i32 v[46:47], s[14:15], v19, s93, v[44:45]
	v_or_b32_e32 v21, 50, v34
	global_load_dword v26, v[26:27], off nt
	s_cmpk_gt_i32 s5, 0xaf
	global_load_dword v32, v[32:33], off nt
	s_cselect_b32 s5, 0xffffea00, 0
	global_load_dword v19, v[46:47], off nt
	v_mad_i64_i32 v[46:47], s[14:15], v21, s93, v[44:45]
	v_or_b32_e32 v21, 52, v34
	global_load_dword v25, v[46:47], off nt
	v_mad_i64_i32 v[46:47], s[14:15], v21, s93, v[44:45]
	v_or_b32_e32 v21, 54, v34
	global_load_dword v29, v[46:47], off nt
	v_mad_i64_i32 v[46:47], s[14:15], v21, s93, v[44:45]
	v_or_b32_e32 v21, 56, v34
	global_load_dword v33, v[46:47], off nt
	v_mad_i64_i32 v[46:47], s[14:15], v21, s93, v[44:45]
	v_or_b32_e32 v27, 58, v34
	global_load_dword v21, v[46:47], off nt
	v_mad_i64_i32 v[46:47], s[14:15], v27, s93, v[44:45]
	v_or_b32_e32 v34, 62, v34
	global_load_dword v27, v[46:47], off nt
	v_mad_i64_i32 v[46:47], s[14:15], v31, s93, v[44:45]
	v_mad_i64_i32 v[44:45], s[14:15], v34, s93, v[44:45]
	global_load_dword v31, v[46:47], off nt
	global_load_dword v34, v[44:45], off nt
	s_waitcnt vmcnt(0)
	ds_write2_b32 v14, v43, v48 offset1:66
	ds_write2_b32 v14, v49, v50 offset0:132 offset1:198
	v_add_u32_e32 v43, 0x400, v14
	ds_write2_b32 v43, v35, v37 offset0:8 offset1:74
	ds_write2_b32 v43, v39, v41 offset0:140 offset1:206
	v_add_u32_e32 v35, 0x800, v14
	ds_write2_b32 v35, v36, v38 offset0:16 offset1:82
	ds_write2_b32 v35, v40, v42 offset0:148 offset1:214
	v_add_u32_e32 v35, 0xc00, v14
	ds_write2_b32 v35, v15, v18 offset0:24 offset1:90
	ds_write2_b32 v35, v22, v28 offset0:156 offset1:222
	v_add_u32_e32 v15, 0x1000, v14
	ds_write2_b32 v15, v16, v20 offset0:32 offset1:98
	ds_write2_b32 v15, v24, v30 offset0:164 offset1:230
	v_add_u32_e32 v15, 0x1400, v14
	ds_write2_b32 v15, v17, v23 offset0:40 offset1:106
	ds_write2_b32 v15, v26, v32 offset0:172 offset1:238
	v_add_u32_e32 v15, 0x1800, v14
	ds_write2_b32 v15, v19, v25 offset0:48 offset1:114
	ds_write2_b32 v15, v29, v33 offset0:180 offset1:246
	v_add_u32_e32 v15, 0x1c00, v14
	ds_write2_b32 v15, v21, v27 offset0:56 offset1:122
	ds_write2_b32 v15, v31, v34 offset0:188 offset1:254
	s_cselect_b32 s7, 0x80, 0
	s_add_i32 s5, s6, s5
	s_waitcnt lgkmcnt(0)
	s_lshl_b32 s5, s5, 1
	s_and_b32 s6, s6, 0x60
	s_and_b32 s5, s5, 0xffffff00
	s_or_b32 s6, s6, s7
	ds_read2_b32 v[22:23], v1 offset0:33 offset1:41
	ds_read2_b32 v[24:25], v1 offset1:8
	ds_read2_b32 v[26:27], v1 offset0:66 offset1:74
	ds_read2_b32 v[28:29], v1 offset0:99 offset1:107
	ds_read2_b32 v[30:31], v1 offset0:132 offset1:140
	ds_read2_b32 v[32:33], v1 offset0:165 offset1:173
	ds_read2_b32 v[34:35], v1 offset0:198 offset1:206
	ds_read2_b32 v[36:37], v1 offset0:231 offset1:239
	s_or_b32 s6, s6, s5
	v_or_b32_e32 v38, s6, v9
	s_ashr_i32 s5, s4, 31
	v_ashrrev_i32_e32 v39, 31, v38
	v_lshl_add_u64 v[20:21], s[4:5], 1, v[4:5]
	v_lshlrev_b64 v[38:39], 12, v[38:39]
	s_waitcnt lgkmcnt(6)
	v_cvt_pk_bf16_f32 v16, v24, v22
	s_waitcnt lgkmcnt(4)
	v_cvt_pk_bf16_f32 v17, v26, v28
	s_waitcnt lgkmcnt(2)
	v_cvt_pk_bf16_f32 v18, v30, v32
	s_waitcnt lgkmcnt(0)
	v_cvt_pk_bf16_f32 v19, v34, v36
	v_lshl_add_u64 v[38:39], v[20:21], 0, v[38:39]
	v_or_b32_e32 v22, s6, v6
	global_store_dwordx4 v[38:39], v[16:19], off sc1
	v_or_b32_e32 v38, s6, v7
	v_ashrrev_i32_e32 v39, 31, v38
	v_cvt_pk_bf16_f32 v16, v25, v23
	v_ashrrev_i32_e32 v23, 31, v22
	v_lshlrev_b64 v[22:23], 12, v[22:23]
	v_cvt_pk_bf16_f32 v17, v27, v29
	v_cvt_pk_bf16_f32 v18, v31, v33
	v_cvt_pk_bf16_f32 v19, v35, v37
	v_lshl_add_u64 v[22:23], v[20:21], 0, v[22:23]
	global_store_dwordx4 v[22:23], v[16:19], off sc1
	ds_read2_b32 v[22:23], v1 offset0:49 offset1:57
	ds_read2_b32 v[24:25], v1 offset0:16 offset1:24
	ds_read2_b32 v[26:27], v1 offset0:82 offset1:90
	ds_read2_b32 v[28:29], v1 offset0:115 offset1:123
	ds_read2_b32 v[30:31], v1 offset0:148 offset1:156
	ds_read2_b32 v[32:33], v1 offset0:181 offset1:189
	ds_read2_b32 v[34:35], v1 offset0:214 offset1:222
	ds_read2_b32 v[36:37], v1 offset0:247 offset1:255
	v_lshlrev_b64 v[38:39], 12, v[38:39]
	s_waitcnt lgkmcnt(6)
	v_cvt_pk_bf16_f32 v16, v24, v22
	s_waitcnt lgkmcnt(4)
	v_cvt_pk_bf16_f32 v17, v26, v28
	s_waitcnt lgkmcnt(2)
	v_cvt_pk_bf16_f32 v18, v30, v32
	s_waitcnt lgkmcnt(0)
	v_cvt_pk_bf16_f32 v19, v34, v36
	v_lshl_add_u64 v[38:39], v[20:21], 0, v[38:39]
	v_or_b32_e32 v22, s6, v13
	global_store_dwordx4 v[38:39], v[16:19], off sc1
	s_add_i32 s4, s10, 0x680
	s_add_i32 s9, s9, 0xd000
	v_cvt_pk_bf16_f32 v16, v25, v23
	v_ashrrev_i32_e32 v23, 31, v22
	v_lshlrev_b64 v[22:23], 12, v[22:23]
	v_cvt_pk_bf16_f32 v17, v27, v29
	v_cvt_pk_bf16_f32 v18, v31, v33
	v_cvt_pk_bf16_f32 v19, v35, v37
	v_lshl_add_u64 v[20:21], v[20:21], 0, v[22:23]
	global_store_dwordx4 v[20:21], v[16:19], off sc1
	s_waitcnt lgkmcnt(0)
	s_cmpk_lt_i32 s10, 0x2580
	s_mov_b32 s10, s4
	s_cbranch_scc1 .LBB0_1698

.LBB0_1701:
	s_ashr_i32 s4, s12, 31
	s_lshr_b32 s4, s4, 26
	s_add_i32 s4, s12, s4
	s_ashr_i32 s7, s4, 6
	s_andn2_b32 s4, s4, 63
	s_lshl_b32 s5, s7, 11
	v_or_b32_e32 v6, s4, v8
	s_sub_i32 s8, s6, s5
	v_or_b32_e32 v14, 2, v6
	s_ashr_i32 s9, s8, 31
	v_ashrrev_i32_e32 v7, 31, v6
	v_ashrrev_i32_e32 v15, 31, v14
	v_lshl_add_u64 v[4:5], s[8:9], 2, v[2:3]
	v_lshlrev_b64 v[12:13], 13, v[6:7]
	v_lshlrev_b64 v[14:15], 13, v[14:15]
	v_lshl_add_u64 v[12:13], v[4:5], 0, v[12:13]
	v_lshl_add_u64 v[14:15], v[4:5], 0, v[14:15]
	global_load_dword v12, v[12:13], off nt
	v_or_b32_e32 v16, 6, v6
	global_load_dword v13, v[14:15], off nt
	v_or_b32_e32 v14, 4, v6
	v_ashrrev_i32_e32 v15, 31, v14
	v_ashrrev_i32_e32 v17, 31, v16
	v_lshlrev_b64 v[14:15], 13, v[14:15]
	v_lshlrev_b64 v[16:17], 13, v[16:17]
	v_lshl_add_u64 v[14:15], v[4:5], 0, v[14:15]
	v_lshl_add_u64 v[16:17], v[4:5], 0, v[16:17]
	global_load_dword v14, v[14:15], off nt
	v_or_b32_e32 v18, 10, v6
	global_load_dword v15, v[16:17], off nt
	v_or_b32_e32 v16, 8, v6
	v_ashrrev_i32_e32 v17, 31, v16
	v_ashrrev_i32_e32 v19, 31, v18
	v_lshlrev_b64 v[16:17], 13, v[16:17]
	v_lshlrev_b64 v[18:19], 13, v[18:19]
	v_lshl_add_u64 v[16:17], v[4:5], 0, v[16:17]
	v_lshl_add_u64 v[18:19], v[4:5], 0, v[18:19]
	global_load_dword v16, v[16:17], off nt
	v_or_b32_e32 v20, 14, v6
	global_load_dword v17, v[18:19], off nt
	v_or_b32_e32 v18, 12, v6
	v_ashrrev_i32_e32 v19, 31, v18
	v_ashrrev_i32_e32 v21, 31, v20
	v_lshlrev_b64 v[18:19], 13, v[18:19]
	v_lshlrev_b64 v[20:21], 13, v[20:21]
	v_lshl_add_u64 v[18:19], v[4:5], 0, v[18:19]
	v_lshl_add_u64 v[20:21], v[4:5], 0, v[20:21]
	global_load_dword v18, v[18:19], off nt
	v_or_b32_e32 v22, 18, v6
	global_load_dword v19, v[20:21], off nt
	v_or_b32_e32 v20, 16, v6
	v_ashrrev_i32_e32 v21, 31, v20
	v_ashrrev_i32_e32 v23, 31, v22
	v_lshlrev_b64 v[20:21], 13, v[20:21]
	v_lshlrev_b64 v[22:23], 13, v[22:23]
	v_lshl_add_u64 v[20:21], v[4:5], 0, v[20:21]
	v_lshl_add_u64 v[22:23], v[4:5], 0, v[22:23]
	global_load_dword v20, v[20:21], off nt
	v_or_b32_e32 v24, 22, v6
	global_load_dword v21, v[22:23], off nt
	v_or_b32_e32 v22, 20, v6
	v_ashrrev_i32_e32 v23, 31, v22
	v_ashrrev_i32_e32 v25, 31, v24
	v_lshlrev_b64 v[22:23], 13, v[22:23]
	v_lshlrev_b64 v[24:25], 13, v[24:25]
	v_lshl_add_u64 v[22:23], v[4:5], 0, v[22:23]
	v_lshl_add_u64 v[24:25], v[4:5], 0, v[24:25]
	global_load_dword v22, v[22:23], off nt
	v_or_b32_e32 v26, 26, v6
	global_load_dword v23, v[24:25], off nt
	v_or_b32_e32 v24, 24, v6
	v_ashrrev_i32_e32 v25, 31, v24
	v_ashrrev_i32_e32 v27, 31, v26
	v_lshlrev_b64 v[24:25], 13, v[24:25]
	v_lshlrev_b64 v[26:27], 13, v[26:27]
	v_lshl_add_u64 v[24:25], v[4:5], 0, v[24:25]
	v_lshl_add_u64 v[26:27], v[4:5], 0, v[26:27]
	global_load_dword v24, v[24:25], off nt
	v_or_b32_e32 v28, 30, v6
	global_load_dword v25, v[26:27], off nt
	v_or_b32_e32 v26, 28, v6
	v_ashrrev_i32_e32 v27, 31, v26
	v_ashrrev_i32_e32 v29, 31, v28
	v_lshlrev_b64 v[26:27], 13, v[26:27]
	v_lshlrev_b64 v[28:29], 13, v[28:29]
	v_lshl_add_u64 v[26:27], v[4:5], 0, v[26:27]
	v_lshl_add_u64 v[28:29], v[4:5], 0, v[28:29]
	global_load_dword v26, v[26:27], off nt
	v_or_b32_e32 v30, 34, v6
	global_load_dword v27, v[28:29], off nt
	v_or_b32_e32 v28, 32, v6
	v_ashrrev_i32_e32 v29, 31, v28
	v_ashrrev_i32_e32 v31, 31, v30
	v_lshlrev_b64 v[28:29], 13, v[28:29]
	v_lshlrev_b64 v[30:31], 13, v[30:31]
	v_lshl_add_u64 v[28:29], v[4:5], 0, v[28:29]
	v_lshl_add_u64 v[30:31], v[4:5], 0, v[30:31]
	global_load_dword v28, v[28:29], off nt
	v_or_b32_e32 v32, 38, v6
	global_load_dword v29, v[30:31], off nt
	v_or_b32_e32 v30, 36, v6
	v_ashrrev_i32_e32 v31, 31, v30
	v_ashrrev_i32_e32 v33, 31, v32
	v_lshlrev_b64 v[30:31], 13, v[30:31]
	v_lshlrev_b64 v[32:33], 13, v[32:33]
	v_lshl_add_u64 v[30:31], v[4:5], 0, v[30:31]
	v_lshl_add_u64 v[32:33], v[4:5], 0, v[32:33]
	global_load_dword v30, v[30:31], off nt
	v_or_b32_e32 v34, 42, v6
	global_load_dword v31, v[32:33], off nt
	v_or_b32_e32 v32, 40, v6
	v_ashrrev_i32_e32 v33, 31, v32
	v_ashrrev_i32_e32 v35, 31, v34
	v_lshlrev_b64 v[32:33], 13, v[32:33]
	v_lshlrev_b64 v[34:35], 13, v[34:35]
	v_lshl_add_u64 v[32:33], v[4:5], 0, v[32:33]
	v_lshl_add_u64 v[34:35], v[4:5], 0, v[34:35]
	global_load_dword v32, v[32:33], off nt
	v_or_b32_e32 v36, 46, v6
	global_load_dword v33, v[34:35], off nt
	v_or_b32_e32 v34, 44, v6
	v_ashrrev_i32_e32 v35, 31, v34
	v_ashrrev_i32_e32 v37, 31, v36
	v_lshlrev_b64 v[34:35], 13, v[34:35]
	v_lshlrev_b64 v[36:37], 13, v[36:37]
	v_lshl_add_u64 v[34:35], v[4:5], 0, v[34:35]
	v_lshl_add_u64 v[36:37], v[4:5], 0, v[36:37]
	global_load_dword v34, v[34:35], off nt
	v_or_b32_e32 v38, 50, v6
	global_load_dword v35, v[36:37], off nt
	v_or_b32_e32 v36, 48, v6
	v_ashrrev_i32_e32 v37, 31, v36
	v_ashrrev_i32_e32 v39, 31, v38
	v_lshlrev_b64 v[36:37], 13, v[36:37]
	v_lshlrev_b64 v[38:39], 13, v[38:39]
	v_lshl_add_u64 v[36:37], v[4:5], 0, v[36:37]
	v_lshl_add_u64 v[38:39], v[4:5], 0, v[38:39]
	global_load_dword v36, v[36:37], off nt
	v_or_b32_e32 v40, 54, v6
	global_load_dword v37, v[38:39], off nt
	v_or_b32_e32 v38, 52, v6
	v_ashrrev_i32_e32 v39, 31, v38
	v_ashrrev_i32_e32 v41, 31, v40
	v_lshlrev_b64 v[38:39], 13, v[38:39]
	v_lshlrev_b64 v[40:41], 13, v[40:41]
	v_lshl_add_u64 v[38:39], v[4:5], 0, v[38:39]
	v_lshl_add_u64 v[40:41], v[4:5], 0, v[40:41]
	global_load_dword v38, v[38:39], off nt
	v_or_b32_e32 v42, 58, v6
	global_load_dword v39, v[40:41], off nt
	v_or_b32_e32 v40, 56, v6
	v_ashrrev_i32_e32 v41, 31, v40
	v_ashrrev_i32_e32 v43, 31, v42
	v_lshlrev_b64 v[40:41], 13, v[40:41]
	v_lshlrev_b64 v[42:43], 13, v[42:43]
	v_lshl_add_u64 v[40:41], v[4:5], 0, v[40:41]
	v_lshl_add_u64 v[42:43], v[4:5], 0, v[42:43]
	global_load_dword v40, v[40:41], off nt
	s_mul_i32 s7, s7, 0xff500000
	global_load_dword v41, v[42:43], off nt
	v_or_b32_e32 v42, 60, v6
	v_or_b32_e32 v6, 62, v6
	v_ashrrev_i32_e32 v43, 31, v42
	v_ashrrev_i32_e32 v7, 31, v6
	v_lshlrev_b64 v[42:43], 13, v[42:43]
	v_lshlrev_b64 v[6:7], 13, v[6:7]
	v_lshl_add_u64 v[42:43], v[4:5], 0, v[42:43]
	v_lshl_add_u64 v[4:5], v[4:5], 0, v[6:7]
	global_load_dword v42, v[42:43], off nt
	s_ashr_i32 s5, s4, 31
	global_load_dword v4, v[4:5], off nt
	v_add_u32_e32 v5, 0x400, v10
	s_waitcnt vmcnt(0)
	ds_write2_b32 v10, v12, v13 offset1:66
	ds_write2_b32 v10, v14, v15 offset0:132 offset1:198
	ds_write2_b32 v5, v16, v17 offset0:8 offset1:74
	ds_write2_b32 v5, v18, v19 offset0:140 offset1:206
	v_add_u32_e32 v5, 0x800, v10
	ds_write2_b32 v5, v20, v21 offset0:16 offset1:82
	ds_write2_b32 v5, v22, v23 offset0:148 offset1:214
	v_add_u32_e32 v5, 0xc00, v10
	ds_write2_b32 v5, v24, v25 offset0:24 offset1:90
	ds_write2_b32 v5, v26, v27 offset0:156 offset1:222
	v_add_u32_e32 v5, 0x1000, v10
	ds_write2_b32 v5, v28, v29 offset0:32 offset1:98
	ds_write2_b32 v5, v30, v31 offset0:164 offset1:230
	v_add_u32_e32 v5, 0x1400, v10
	ds_write2_b32 v5, v32, v33 offset0:40 offset1:106
	ds_write2_b32 v5, v34, v35 offset0:172 offset1:238
	v_add_u32_e32 v5, 0x1800, v10
	ds_write2_b32 v5, v36, v37 offset0:48 offset1:114
	ds_write2_b32 v5, v38, v39 offset0:180 offset1:246
	v_add_u32_e32 v5, 0x1c00, v10
	ds_write2_b32 v5, v40, v41 offset0:56 offset1:122
	ds_write2_b32 v5, v42, v4 offset0:188 offset1:254
	s_waitcnt lgkmcnt(0)
	ds_read2_b32 v[14:15], v11 offset0:33 offset1:41
	ds_read2_b32 v[16:17], v11 offset1:8
	ds_read2_b32 v[18:19], v11 offset0:66 offset1:74
	ds_read2_b32 v[20:21], v11 offset0:99 offset1:107
	ds_read2_b32 v[22:23], v11 offset0:132 offset1:140
	ds_read2_b32 v[24:25], v11 offset0:165 offset1:173
	ds_read2_b32 v[26:27], v11 offset0:198 offset1:206
	ds_read2_b32 v[28:29], v11 offset0:231 offset1:239
	v_add_u32_e32 v30, s7, v9
	v_lshl_add_u64 v[12:13], s[4:5], 1, v[0:1]
	v_ashrrev_i32_e32 v31, 31, v30
	s_waitcnt lgkmcnt(6)
	v_cvt_pk_bf16_f32 v4, v16, v14
	s_waitcnt lgkmcnt(4)
	v_cvt_pk_bf16_f32 v5, v18, v20
	s_waitcnt lgkmcnt(2)
	v_cvt_pk_bf16_f32 v6, v22, v24
	s_waitcnt lgkmcnt(0)
	v_cvt_pk_bf16_f32 v7, v26, v28
	v_lshl_add_u64 v[32:33], v[30:31], 1, v[12:13]
	v_add_u32_e32 v14, 0xb000, v30
	global_store_dwordx4 v[32:33], v[4:7], off sc1
	v_add_u32_e32 v32, 0x16000, v30
	v_ashrrev_i32_e32 v33, 31, v32
	v_cvt_pk_bf16_f32 v4, v17, v15
	v_ashrrev_i32_e32 v15, 31, v14
	v_cvt_pk_bf16_f32 v5, v19, v21
	v_cvt_pk_bf16_f32 v6, v23, v25
	v_cvt_pk_bf16_f32 v7, v27, v29
	v_lshl_add_u64 v[14:15], v[14:15], 1, v[12:13]
	global_store_dwordx4 v[14:15], v[4:7], off sc1
	ds_read2_b32 v[14:15], v11 offset0:49 offset1:57
	ds_read2_b32 v[16:17], v11 offset0:16 offset1:24
	ds_read2_b32 v[18:19], v11 offset0:82 offset1:90
	ds_read2_b32 v[20:21], v11 offset0:115 offset1:123
	ds_read2_b32 v[22:23], v11 offset0:148 offset1:156
	ds_read2_b32 v[24:25], v11 offset0:181 offset1:189
	ds_read2_b32 v[26:27], v11 offset0:214 offset1:222
	ds_read2_b32 v[28:29], v11 offset0:247 offset1:255
	v_lshl_add_u64 v[32:33], v[32:33], 1, v[12:13]
	s_waitcnt lgkmcnt(6)
	v_cvt_pk_bf16_f32 v4, v16, v14
	s_waitcnt lgkmcnt(4)
	v_cvt_pk_bf16_f32 v5, v18, v20
	s_waitcnt lgkmcnt(2)
	v_cvt_pk_bf16_f32 v6, v22, v24
	s_waitcnt lgkmcnt(0)
	v_cvt_pk_bf16_f32 v7, v26, v28
	v_add_u32_e32 v14, 0x21000, v30
	global_store_dwordx4 v[32:33], v[4:7], off sc1
	s_add_i32 s4, s12, 0x680
	s_add_i32 s6, s6, 0xd000
	v_cvt_pk_bf16_f32 v4, v17, v15
	v_ashrrev_i32_e32 v15, 31, v14
	v_cvt_pk_bf16_f32 v5, v19, v21
	v_cvt_pk_bf16_f32 v6, v23, v25
	v_cvt_pk_bf16_f32 v7, v27, v29
	v_lshl_add_u64 v[12:13], v[14:15], 1, v[12:13]
	global_store_dwordx4 v[12:13], v[4:7], off sc1
	s_waitcnt lgkmcnt(0)
	v_add_u32_e32 v9, 0x11e00000, v9
	s_cmpk_lt_i32 s12, 0xf80
	s_mov_b32 s12, s4
	s_cbranch_scc1 .LBB0_1701

.LBB0_1730:
	s_andn2_saveexec_b64 s[4:5], s[4:5]
	s_cbranch_execz .LBB0_1746
	v_mov_b32_e32 v1, s46
	v_add_co_u32_e32 v2, vcc, 0x3000, v1
	v_mov_b32_e32 v1, s47
	s_waitcnt vmcnt(0)
	v_addc_co_u32_e32 v3, vcc, 0, v1, vcc
	flat_atomic_add v1, v[2:3], v217 offset:1024 sc0
	v_cvt_f32_u32_e32 v2, v0
	v_sub_u32_e32 v3, 0, v0
	s_mov_b64 s[10:11], -1
	v_rcp_iflag_f32_e32 v2, v2
	s_nop 0
	v_mul_f32_e32 v2, 0x4f7ffffe, v2
	v_cvt_u32_f32_e32 v2, v2
	v_mul_lo_u32 v3, v3, v2
	v_mul_hi_u32 v3, v2, v3
	v_add_u32_e32 v2, v2, v3
	s_waitcnt vmcnt(0) lgkmcnt(0)
	v_mul_hi_u32 v2, v1, v2
	v_mul_lo_u32 v3, v2, v0
	v_sub_u32_e32 v3, v1, v3
	v_cmp_ge_u32_e32 vcc, v3, v0
	v_add_u32_e32 v4, 1, v2
	s_nop 0
	v_cndmask_b32_e32 v2, v2, v4, vcc
	v_sub_u32_e32 v4, v3, v0
	v_cndmask_b32_e32 v3, v3, v4, vcc
	v_cmp_ge_u32_e32 vcc, v3, v0
	v_add_u32_e32 v3, 1, v2
	s_nop 0
	v_cndmask_b32_e32 v2, v2, v3, vcc
	v_add_u32_e32 v3, 1, v1
	v_mad_u64_u32 v[0:1], s[4:5], v0, v2, v[0:1]
	s_add_u32 s4, s46, 0x3500
	s_addc_u32 s5, s47, 0
	v_cmp_ne_u32_e32 vcc, v3, v0
	v_mov_b64_e32 v[0:1], s[4:5]
	s_and_saveexec_b64 s[6:7], vcc
	s_cbranch_execz .LBB0_1743
	v_mov_b64_e32 v[0:1], s[4:5]
	flat_load_dword v0, v[0:1] sc1
	s_mov_b64 s[14:15], 0
	s_waitcnt vmcnt(0) lgkmcnt(0)
	v_cmp_eq_u32_e32 vcc, v0, v2
	s_and_saveexec_b64 s[12:13], vcc
	s_cbranch_execz .LBB0_1742
	s_add_u32 s10, s46, 0x200
	s_addc_u32 s11, s47, 0
	s_mov_b32 s9, 1
	s_branch .LBB0_1735

.LBB0_1765:
	s_movk_i32 s6, 0x2c0
	v_cmp_gt_i32_e32 vcc, s6, v91
	s_movk_i32 s6, 0x2bf
	v_cmp_lt_i32_e64 s[6:7], s6, v91
	s_mov_b64 s[34:35], 0
	s_and_saveexec_b64 s[94:95], s[6:7]
	s_xor_b64 s[6:7], exec, s[94:95]
	s_and_b64 s[34:35], s[26:27], exec
	s_or_saveexec_b64 s[6:7], s[6:7]
	v_mov_b32_e32 v92, 0xff
	v_mov_b32_e32 v0, s56
	v_mov_b32_e32 v1, s57
	v_mov_b32_e32 v2, s48
	s_xor_b64 exec, exec, s[6:7]
	s_andn2_b64 s[34:35], s[34:35], exec
	s_and_b64 s[94:95], s[28:29], exec
	v_mov_b32_e32 v92, 0
	v_mov_b32_e32 v0, s47
	v_mov_b32_e32 v1, s46
	v_mov_b32_e32 v2, s72
	s_or_b64 s[34:35], s[34:35], s[94:95]
	s_or_b64 exec, exec, s[6:7]
	s_and_saveexec_b64 s[6:7], s[34:35]
	s_mov_b32 s96, s74
	s_cbranch_execz .LBB0_1764
	v_mov_b32_e32 v3, 0xfffffd40
	v_cndmask_b32_e64 v3, v3, 0, vcc
	v_readlane_b32 s34, v254, 0
	v_add_lshl_u32 v24, v3, v91, 3
	v_readlane_b32 s35, v254, 1
	v_ashrrev_i32_e32 v25, 31, v24
	v_lshlrev_b64 v[88:89], 1, v[24:25]
	v_mov_b64_e32 v[4:5], s[34:35]
	v_mad_i64_i32 v[6:7], s[34:35], v0, s43, v[4:5]
	v_mad_i64_i32 v[8:9], s[34:35], v1, s43, v[4:5]
	v_lshl_add_u64 v[12:13], v[6:7], 0, v[88:89]
	v_lshl_add_u64 v[16:17], v[8:9], 0, v[88:89]
	v_mad_i64_i32 v[4:5], s[34:35], v2, s43, v[4:5]
	global_load_dwordx4 v[0:3], v[12:13], off
	global_load_dwordx4 v[8:11], v[16:17], off
	v_lshl_add_u64 v[20:21], v[4:5], 0, v[88:89]
	global_load_dwordx4 v[4:7], v[20:21], off
	v_add_co_u32_e32 v12, vcc, s45, v12
	v_lshlrev_b64 v[24:25], 2, v[24:25]
	s_nop 0
	v_addc_co_u32_e32 v13, vcc, 0, v13, vcc
	v_add_co_u32_e32 v16, vcc, s45, v16
	v_lshl_add_u64 v[28:29], s[54:55], 0, v[24:25]
	s_nop 0
	v_addc_co_u32_e32 v17, vcc, 0, v17, vcc
	v_add_co_u32_e32 v20, vcc, s45, v20
	v_lshl_add_u64 v[32:33], s[10:11], 0, v[24:25]
	s_nop 0
	v_addc_co_u32_e32 v21, vcc, 0, v21, vcc
	v_lshl_add_u64 v[36:37], s[12:13], 0, v[24:25]
	v_lshl_add_u64 v[40:41], s[2:3], 0, v[24:25]
	v_lshl_add_u64 v[44:45], s[14:15], 0, v[24:25]
	v_lshl_add_u64 v[48:49], s[16:17], 0, v[24:25]
	v_lshl_add_u64 v[52:53], s[18:19], 0, v[24:25]
	v_lshl_add_u64 v[84:85], s[20:21], 0, v[24:25]
	global_load_dwordx4 v[12:15], v[12:13], off offset:3072
	v_readlane_b32 s34, v253, 54
	global_load_dwordx4 v[16:19], v[16:17], off offset:3072
	v_readlane_b32 s35, v253, 55
	global_load_dwordx4 v[20:23], v[20:21], off offset:3072
	s_nop 0
	global_load_dwordx4 v[24:27], v[28:29], off offset:16
	global_load_dwordx4 v[56:59], v[28:29], off
	s_nop 0
	global_load_dwordx4 v[28:31], v[32:33], off offset:16
	global_load_dwordx4 v[80:83], v[32:33], off
	s_nop 0
	global_load_dwordx4 v[32:35], v[36:37], off offset:16
	global_load_dwordx4 v[60:63], v[36:37], off
	s_nop 0
	global_load_dwordx4 v[36:39], v[40:41], off offset:16
	global_load_dwordx4 v[68:71], v[40:41], off
	s_nop 0
	global_load_dwordx4 v[40:43], v[44:45], off offset:16
	global_load_dwordx4 v[64:67], v[44:45], off
	s_nop 0
	global_load_dwordx4 v[44:47], v[48:49], off offset:16
	global_load_dwordx4 v[72:75], v[48:49], off
	s_nop 0
	global_load_dwordx4 v[48:51], v[52:53], off offset:16
	global_load_dwordx4 v[76:79], v[52:53], off
	s_nop 0
	global_load_dwordx4 v[52:55], v[84:85], off offset:16
	s_nop 0
	global_load_dwordx4 v[84:87], v[84:85], off
	s_waitcnt vmcnt(0)
	v_lshlrev_b32_e32 v94, 16, v0
	v_lshlrev_b32_e32 v96, 16, v8
	v_and_b32_e32 v97, 0xffff0000, v8
	v_and_b32_e32 v95, 0xffff0000, v0
	v_lshlrev_b32_e32 v98, 16, v4
	v_and_b32_e32 v99, 0xffff0000, v4
	v_lshlrev_b32_e32 v8, 16, v9
	v_and_b32_e32 v9, 0xffff0000, v9
	v_lshlrev_b32_e32 v4, 16, v5
	v_and_b32_e32 v5, 0xffff0000, v5
	v_pk_mul_f32 v[80:81], v[80:81], v[96:97]
	s_nop 0
	v_pk_fma_f32 v[56:57], v[56:57], v[94:95], v[80:81]
	v_pk_mul_f32 v[8:9], v[82:83], v[8:9]
	v_pk_fma_f32 v[56:57], v[60:61], v[98:99], v[56:57]
	v_lshlrev_b32_e32 v100, 16, v12
	v_pk_add_f32 v[56:57], v[68:69], v[56:57]
	v_lshlrev_b32_e32 v102, 16, v16
	v_mul_f32_e32 v0, 0xbfb8aa3b, v56
	v_exp_f32_e32 v0, v0
	v_and_b32_e32 v103, 0xffff0000, v16
	v_and_b32_e32 v101, 0xffff0000, v12
	v_pk_mul_f32 v[68:69], v[72:73], v[102:103]
	v_add_f32_e32 v0, 1.0, v0
	v_rcp_f32_e32 v60, v0
	v_mul_f32_e32 v0, 0xbfb8aa3b, v57
	v_exp_f32_e32 v0, v0
	v_lshlrev_b32_e32 v104, 16, v20
	v_and_b32_e32 v105, 0xffff0000, v20
	v_pk_fma_f32 v[64:65], v[64:65], v[100:101], v[68:69]
	v_add_f32_e32 v0, 1.0, v0
	v_rcp_f32_e32 v61, v0
	v_pk_fma_f32 v[64:65], v[76:77], v[104:105], v[64:65]
	v_lshlrev_b32_e32 v16, 16, v17
	v_pk_add_f32 v[64:65], v[84:85], v[64:65]
	v_pk_mul_f32 v[56:57], v[56:57], v[60:61]
	v_and_b32_e32 v17, 0xffff0000, v17
	v_pk_mul_f32 v[56:57], v[56:57], v[64:65]
	v_lshlrev_b32_e32 v12, 16, v13
	v_cvt_pk_bf16_f32 v0, v56, v57
	v_lshlrev_b32_e32 v56, 16, v1
	v_and_b32_e32 v57, 0xffff0000, v1
	v_pk_fma_f32 v[8:9], v[58:59], v[56:57], v[8:9]
	v_and_b32_e32 v13, 0xffff0000, v13
	v_pk_fma_f32 v[4:5], v[62:63], v[4:5], v[8:9]
	v_pk_mul_f32 v[16:17], v[74:75], v[16:17]
	v_pk_add_f32 v[4:5], v[70:71], v[4:5]
	v_lshlrev_b32_e32 v20, 16, v21
	v_mul_f32_e32 v1, 0xbfb8aa3b, v4
	v_exp_f32_e32 v1, v1
	v_and_b32_e32 v21, 0xffff0000, v21
	v_pk_fma_f32 v[12:13], v[66:67], v[12:13], v[16:17]
	v_lshlrev_b32_e32 v16, 16, v14
	v_add_f32_e32 v1, 1.0, v1
	v_rcp_f32_e32 v8, v1
	v_mul_f32_e32 v1, 0xbfb8aa3b, v5
	v_exp_f32_e32 v1, v1
	v_pk_fma_f32 v[12:13], v[78:79], v[20:21], v[12:13]
	v_lshlrev_b32_e32 v20, 16, v18
	v_pk_add_f32 v[12:13], v[86:87], v[12:13]
	v_add_f32_e32 v1, 1.0, v1
	v_rcp_f32_e32 v9, v1
	v_and_b32_e32 v21, 0xffff0000, v18
	v_and_b32_e32 v17, 0xffff0000, v14
	v_lshlrev_b32_e32 v56, 16, v22
	v_pk_mul_f32 v[4:5], v[4:5], v[8:9]
	v_lshlrev_b32_e32 v8, 16, v10
	v_pk_mul_f32 v[4:5], v[4:5], v[12:13]
	v_and_b32_e32 v9, 0xffff0000, v10
	v_cvt_pk_bf16_f32 v1, v4, v5
	v_lshlrev_b32_e32 v4, 16, v2
	v_and_b32_e32 v5, 0xffff0000, v2
	v_pk_mul_f32 v[8:9], v[28:29], v[8:9]
	v_lshlrev_b32_e32 v12, 16, v6
	v_and_b32_e32 v13, 0xffff0000, v6
	v_pk_fma_f32 v[4:5], v[24:25], v[4:5], v[8:9]
	v_and_b32_e32 v57, 0xffff0000, v22
	v_pk_fma_f32 v[4:5], v[32:33], v[12:13], v[4:5]
	v_pk_mul_f32 v[12:13], v[44:45], v[20:21]
	v_pk_add_f32 v[4:5], v[36:37], v[4:5]
	v_pk_fma_f32 v[12:13], v[40:41], v[16:17], v[12:13]
	v_mul_f32_e32 v2, 0xbfb8aa3b, v4
	v_exp_f32_e32 v2, v2
	v_pk_fma_f32 v[12:13], v[48:49], v[56:57], v[12:13]
	v_lshlrev_b32_e32 v6, 16, v7
	v_pk_add_f32 v[12:13], v[52:53], v[12:13]
	v_add_f32_e32 v2, 1.0, v2
	v_rcp_f32_e32 v8, v2
	v_mul_f32_e32 v2, 0xbfb8aa3b, v5
	v_exp_f32_e32 v2, v2
	v_and_b32_e32 v7, 0xffff0000, v7
	v_lshlrev_b32_e32 v10, 16, v15
	v_lshlrev_b32_e32 v14, 16, v23
	v_add_f32_e32 v2, 1.0, v2
	v_rcp_f32_e32 v9, v2
	s_nop 0
	v_pk_mul_f32 v[4:5], v[4:5], v[8:9]
	s_nop 0
	v_pk_mul_f32 v[4:5], v[4:5], v[12:13]
	v_lshlrev_b32_e32 v8, 16, v11
	v_and_b32_e32 v9, 0xffff0000, v11
	v_cvt_pk_bf16_f32 v2, v4, v5
	v_lshlrev_b32_e32 v4, 16, v3
	v_and_b32_e32 v5, 0xffff0000, v3
	v_pk_mul_f32 v[8:9], v[30:31], v[8:9]
	v_lshlrev_b32_e32 v12, 16, v19
	v_pk_fma_f32 v[4:5], v[26:27], v[4:5], v[8:9]
	v_and_b32_e32 v13, 0xffff0000, v19
	v_pk_fma_f32 v[4:5], v[34:35], v[6:7], v[4:5]
	v_and_b32_e32 v11, 0xffff0000, v15
	v_pk_add_f32 v[4:5], v[38:39], v[4:5]
	v_pk_mul_f32 v[8:9], v[46:47], v[12:13]
	v_mul_f32_e32 v3, 0xbfb8aa3b, v4
	v_exp_f32_e32 v3, v3
	v_and_b32_e32 v15, 0xffff0000, v23
	v_pk_fma_f32 v[8:9], v[42:43], v[10:11], v[8:9]
	v_add_f32_e32 v3, 1.0, v3
	v_rcp_f32_e32 v6, v3
	v_mul_f32_e32 v3, 0xbfb8aa3b, v5
	v_exp_f32_e32 v3, v3
	v_pk_fma_f32 v[8:9], v[50:51], v[14:15], v[8:9]
	v_add_f32_e32 v3, 1.0, v3
	v_rcp_f32_e32 v7, v3
	v_pk_add_f32 v[8:9], v[54:55], v[8:9]
	v_pk_mul_f32 v[4:5], v[4:5], v[6:7]
	s_nop 0
	v_pk_mul_f32 v[4:5], v[4:5], v[8:9]
	v_or_b32_e32 v6, s49, v92
	v_cvt_pk_bf16_f32 v3, v4, v5
	v_mov_b64_e32 v[4:5], s[34:35]
	v_mad_i64_i32 v[4:5], s[34:35], v6, s92, v[4:5]
	v_lshl_add_u64 v[4:5], v[4:5], 0, v[88:89]
	global_store_dwordx4 v[4:5], v[0:3], off sc1
	s_branch .LBB0_1764

.LBB0_1804:
	s_mul_hi_i32 s18, s95, 0x38e38e39
	s_lshr_b32 s19, s18, 31
	s_ashr_i32 s20, s18, 1
	s_lshl_b32 s18, s92, 8
	v_mov_b32_e32 v128, v156
	v_mov_b32_e32 v129, v157
	s_or_b32 s18, s18, s36
	s_add_i32 s20, s20, s19
	v_lshl_add_u32 v130, v129, 2, s18
	v_ashrrev_i32_e32 v131, 31, v130
	v_readlane_b32 s88, v254, 50
	s_cmp_eq_u32 s57, 0
	v_lshlrev_b64 v[150:151], 2, v[130:131]
	v_readlane_b32 s89, v254, 51
	s_cbranch_scc1 .LBB0_1810
	s_lshl_b32 s19, s94, 10
	s_lshl_b32 s18, s20, 8
	s_add_i32 s19, s19, s35
	s_add_i32 s19, s19, s18
	v_add_u32_e32 v130, s19, v128
	v_ashrrev_i32_e32 v131, 31, v130
	v_readlane_b32 s18, v253, 62
	v_lshlrev_b64 v[132:133], 13, v[130:131]
	v_readlane_b32 s19, v253, 63
	s_nop 1
	v_lshl_add_u64 v[132:133], s[18:19], 0, v[132:133]
	v_lshl_add_u64 v[132:133], v[132:133], 0, v[150:151]
	global_store_dwordx4 v[132:133], v[124:127], off sc1
	global_store_dwordx4 v[132:133], v[120:123], off offset:64 sc1
	global_store_dwordx4 v[132:133], v[104:107], off offset:512 sc1
	global_store_dwordx4 v[132:133], v[96:99], off offset:576 sc1
	v_add_u32_e32 v132, 16, v130
	v_ashrrev_i32_e32 v133, 31, v132
	v_lshlrev_b64 v[132:133], 13, v[132:133]
	v_lshl_add_u64 v[132:133], s[18:19], 0, v[132:133]
	v_lshl_add_u64 v[132:133], v[132:133], 0, v[150:151]
	global_store_dwordx4 v[132:133], v[116:119], off sc1
	global_store_dwordx4 v[132:133], v[112:115], off offset:64 sc1
	global_store_dwordx4 v[132:133], v[88:91], off offset:512 sc1
	global_store_dwordx4 v[132:133], v[84:87], off offset:576 sc1
	v_add_u32_e32 v132, 32, v130
	v_ashrrev_i32_e32 v133, 31, v132
	v_lshlrev_b64 v[132:133], 13, v[132:133]
	v_lshl_add_u64 v[132:133], s[18:19], 0, v[132:133]
	v_lshl_add_u64 v[132:133], v[132:133], 0, v[150:151]
	global_store_dwordx4 v[132:133], v[108:111], off sc1
	global_store_dwordx4 v[132:133], v[100:103], off offset:64 sc1
	global_store_dwordx4 v[132:133], v[80:83], off offset:512 sc1
	global_store_dwordx4 v[132:133], v[76:79], off offset:576 sc1
	v_add_u32_e32 v132, 48, v130
	v_ashrrev_i32_e32 v133, 31, v132
	v_lshlrev_b64 v[132:133], 13, v[132:133]
	v_lshl_add_u64 v[132:133], s[18:19], 0, v[132:133]
	v_lshl_add_u64 v[132:133], v[132:133], 0, v[150:151]
	global_store_dwordx4 v[132:133], v[92:95], off sc1
	global_store_dwordx4 v[132:133], v[72:75], off offset:64 sc1
	global_store_dwordx4 v[132:133], v[68:71], off offset:512 sc1
	global_store_dwordx4 v[132:133], v[64:67], off offset:576 sc1
	v_add_u32_e32 v132, 0x80, v130
	v_ashrrev_i32_e32 v133, 31, v132
	v_lshlrev_b64 v[132:133], 13, v[132:133]
	v_lshl_add_u64 v[132:133], s[18:19], 0, v[132:133]
	v_lshl_add_u64 v[132:133], v[132:133], 0, v[150:151]
	global_store_dwordx4 v[132:133], v[60:63], off sc1
	global_store_dwordx4 v[132:133], v[56:59], off offset:64 sc1
	global_store_dwordx4 v[132:133], v[40:43], off offset:512 sc1
	global_store_dwordx4 v[132:133], v[36:39], off offset:576 sc1
	v_add_u32_e32 v132, 0x90, v130
	v_ashrrev_i32_e32 v133, 31, v132
	v_lshlrev_b64 v[132:133], 13, v[132:133]
	v_lshl_add_u64 v[132:133], s[18:19], 0, v[132:133]
	v_lshl_add_u64 v[132:133], v[132:133], 0, v[150:151]
	global_store_dwordx4 v[132:133], v[52:55], off sc1
	global_store_dwordx4 v[132:133], v[48:51], off offset:64 sc1
	global_store_dwordx4 v[132:133], v[28:31], off offset:512 sc1
	global_store_dwordx4 v[132:133], v[24:27], off offset:576 sc1
	v_add_u32_e32 v132, 0xa0, v130
	v_add_u32_e32 v130, 0xb0, v130
	v_ashrrev_i32_e32 v133, 31, v132
	v_ashrrev_i32_e32 v131, 31, v130
	v_lshlrev_b64 v[132:133], 13, v[132:133]
	v_lshlrev_b64 v[130:131], 13, v[130:131]
	v_lshl_add_u64 v[132:133], s[18:19], 0, v[132:133]
	v_lshl_add_u64 v[130:131], s[18:19], 0, v[130:131]
	v_lshl_add_u64 v[132:133], v[132:133], 0, v[150:151]
	v_lshl_add_u64 v[130:131], v[130:131], 0, v[150:151]
	global_store_dwordx4 v[132:133], v[44:47], off sc1
	global_store_dwordx4 v[132:133], v[32:35], off offset:64 sc1
	global_store_dwordx4 v[132:133], v[20:23], off offset:512 sc1
	global_store_dwordx4 v[132:133], v[12:15], off offset:576 sc1
	global_store_dwordx4 v[130:131], v[16:19], off sc1
	global_store_dwordx4 v[130:131], v[8:11], off offset:64 sc1
	global_store_dwordx4 v[130:131], v[4:7], off offset:512 sc1
	global_store_dwordx4 v[130:131], v[0:3], off offset:576 sc1
	s_cbranch_execnz .LBB0_1807
.LBB0_1806:
	s_mul_i32 s18, s20, 9
	s_cmp_lg_u32 s95, s18
	s_cselect_b32 s18, s20, 4
	s_mul_hi_i32 s19, s18, 0xc000
	s_mul_i32 s18, s18, 0xc000
	s_add_u32 s18, s33, s18
	s_addc_u32 s19, s34, s19
	v_lshl_add_u64 v[130:131], s[18:19], 0, v[150:151]
	s_lshl_b32 s18, s95, 8
	s_add_i32 s18, s18, s35
	v_readlane_b32 s20, v253, 50
	v_add_u32_e32 v154, s18, v128
	v_readlane_b32 s21, v253, 51
	v_ashrrev_i32_e32 v155, 31, v154
	v_add_u32_e32 v178, 16, v154
	v_add_u32_e32 v194, 32, v154
	v_add_u32_e32 v210, 48, v154
	v_lshl_add_u64 v[152:153], s[20:21], 0, v[150:151]
	v_lshlrev_b64 v[224:225], 13, v[154:155]
	v_ashrrev_i32_e32 v179, 31, v178
	v_ashrrev_i32_e32 v195, 31, v194
	v_ashrrev_i32_e32 v211, 31, v210
	v_lshl_add_u64 v[172:173], v[152:153], 0, v[224:225]
	v_lshlrev_b64 v[228:229], 13, v[178:179]
	v_lshlrev_b64 v[246:247], 13, v[194:195]
	v_lshlrev_b64 v[248:249], 13, v[210:211]
	global_load_dwordx4 v[160:163], v[172:173], off
	global_load_dwordx4 v[140:143], v[130:131], off
	global_load_dwordx4 v[136:139], v[130:131], off offset:64
	global_load_dwordx4 v[164:167], v[172:173], off offset:64
	global_load_dwordx4 v[168:171], v[172:173], off offset:512
	global_load_dwordx4 v[132:135], v[130:131], off offset:512
	s_nop 0
	global_load_dwordx4 v[128:131], v[130:131], off offset:576
	s_nop 0
	global_load_dwordx4 v[172:175], v[172:173], off offset:576
	v_lshl_add_u64 v[190:191], v[152:153], 0, v[228:229]
	v_lshl_add_u64 v[206:207], v[152:153], 0, v[246:247]
	v_lshl_add_u64 v[242:243], v[152:153], 0, v[248:249]
	global_load_dwordx4 v[178:181], v[190:191], off
	global_load_dwordx4 v[182:185], v[190:191], off offset:64
	global_load_dwordx4 v[186:189], v[190:191], off offset:512
	s_nop 0
	global_load_dwordx4 v[190:193], v[190:191], off offset:576
	s_nop 0
	global_load_dwordx4 v[194:197], v[206:207], off
	global_load_dwordx4 v[198:201], v[206:207], off offset:64
	global_load_dwordx4 v[202:205], v[206:207], off offset:512
	s_nop 0
	global_load_dwordx4 v[206:209], v[206:207], off offset:576
	s_nop 0
	global_load_dwordx4 v[210:213], v[242:243], off
	global_load_dwordx4 v[220:223], v[242:243], off offset:64
	global_load_dwordx4 v[238:241], v[242:243], off offset:512
	s_nop 0
	global_load_dwordx4 v[242:245], v[242:243], off offset:576
	v_lshl_add_u64 v[224:225], s[20:21], 0, v[224:225]
	v_lshl_add_u64 v[224:225], v[224:225], 0, v[150:151]
	v_lshl_add_u64 v[228:229], s[20:21], 0, v[228:229]
	v_lshl_add_u64 v[248:249], s[20:21], 0, v[248:249]
	v_lshl_add_u64 v[246:247], s[20:21], 0, v[246:247]
	v_lshl_add_u64 v[228:229], v[228:229], 0, v[150:151]
	v_lshl_add_u64 v[248:249], v[248:249], 0, v[150:151]
	v_lshl_add_u64 v[246:247], v[246:247], 0, v[150:151]
	s_waitcnt vmcnt(0)
	v_pk_fma_f32 v[126:127], v[126:127], v[142:143], v[162:163]
	v_pk_fma_f32 v[124:125], v[124:125], v[140:141], v[160:161]
	v_pk_fma_f32 v[122:123], v[122:123], v[138:139], v[166:167]
	v_pk_fma_f32 v[120:121], v[120:121], v[136:137], v[164:165]
	v_pk_fma_f32 v[106:107], v[106:107], v[134:135], v[170:171]
	v_pk_fma_f32 v[104:105], v[104:105], v[132:133], v[168:169]
	v_pk_fma_f32 v[98:99], v[98:99], v[130:131], v[174:175]
	v_pk_fma_f32 v[96:97], v[96:97], v[128:129], v[172:173]
	global_store_dwordx4 v[224:225], v[124:127], off sc1
	global_store_dwordx4 v[224:225], v[120:123], off offset:64 sc1
	global_store_dwordx4 v[224:225], v[104:107], off offset:512 sc1
	global_store_dwordx4 v[224:225], v[96:99], off offset:576 sc1
	v_pk_fma_f32 v[90:91], v[90:91], v[134:135], v[188:189]
	v_pk_fma_f32 v[80:81], v[80:81], v[132:133], v[202:203]
	v_pk_fma_f32 v[98:99], v[118:119], v[142:143], v[180:181]
	v_pk_fma_f32 v[96:97], v[116:117], v[140:141], v[178:179]
	v_pk_fma_f32 v[66:67], v[66:67], v[130:131], v[244:245]
	v_pk_fma_f32 v[64:65], v[64:65], v[128:129], v[242:243]
	v_pk_fma_f32 v[106:107], v[114:115], v[138:139], v[184:185]
	v_pk_fma_f32 v[104:105], v[112:113], v[136:137], v[182:183]
	v_pk_fma_f32 v[88:89], v[88:89], v[132:133], v[186:187]
	v_pk_fma_f32 v[86:87], v[86:87], v[130:131], v[192:193]
	v_pk_fma_f32 v[84:85], v[84:85], v[128:129], v[190:191]
	v_pk_fma_f32 v[110:111], v[110:111], v[142:143], v[196:197]
	v_pk_fma_f32 v[108:109], v[108:109], v[140:141], v[194:195]
	v_pk_fma_f32 v[102:103], v[102:103], v[138:139], v[200:201]
	v_pk_fma_f32 v[100:101], v[100:101], v[136:137], v[198:199]
	v_pk_fma_f32 v[82:83], v[82:83], v[134:135], v[204:205]
	v_pk_fma_f32 v[78:79], v[78:79], v[130:131], v[208:209]
	v_pk_fma_f32 v[76:77], v[76:77], v[128:129], v[206:207]
	v_pk_fma_f32 v[94:95], v[94:95], v[142:143], v[212:213]
	v_pk_fma_f32 v[92:93], v[92:93], v[140:141], v[210:211]
	global_store_dwordx4 v[228:229], v[96:99], off sc1
	global_store_dwordx4 v[228:229], v[104:107], off offset:64 sc1
	global_store_dwordx4 v[228:229], v[88:91], off offset:512 sc1
	global_store_dwordx4 v[228:229], v[84:87], off offset:576 sc1
	global_store_dwordx4 v[246:247], v[108:111], off sc1
	global_store_dwordx4 v[246:247], v[100:103], off offset:64 sc1
	global_store_dwordx4 v[246:247], v[80:83], off offset:512 sc1
	global_store_dwordx4 v[246:247], v[76:79], off offset:576 sc1
	global_store_dwordx4 v[248:249], v[92:95], off sc1
	global_store_dwordx4 v[248:249], v[64:67], off offset:576 sc1
	v_add_u32_e32 v80, 0x90, v154
	v_add_u32_e32 v96, 0xa0, v154
	v_add_u32_e32 v64, 0x80, v154
	v_pk_fma_f32 v[74:75], v[74:75], v[138:139], v[222:223]
	v_pk_fma_f32 v[72:73], v[72:73], v[136:137], v[220:221]
	v_pk_fma_f32 v[70:71], v[70:71], v[134:135], v[240:241]
	v_pk_fma_f32 v[68:69], v[68:69], v[132:133], v[238:239]
	v_ashrrev_i32_e32 v65, 31, v64
	v_ashrrev_i32_e32 v81, 31, v80
	v_ashrrev_i32_e32 v97, 31, v96
	global_store_dwordx4 v[248:249], v[72:75], off offset:64 sc1
	global_store_dwordx4 v[248:249], v[68:71], off offset:512 sc1
	v_lshlrev_b64 v[160:161], 13, v[64:65]
	v_lshlrev_b64 v[162:163], 13, v[80:81]
	v_lshlrev_b64 v[164:165], 13, v[96:97]
	v_add_u32_e32 v112, 0xb0, v154
	v_lshl_add_u64 v[76:77], v[152:153], 0, v[160:161]
	v_lshl_add_u64 v[92:93], v[152:153], 0, v[162:163]
	v_lshl_add_u64 v[108:109], v[152:153], 0, v[164:165]
	v_ashrrev_i32_e32 v113, 31, v112
	global_load_dwordx4 v[64:67], v[76:77], off
	global_load_dwordx4 v[68:71], v[76:77], off offset:64
	global_load_dwordx4 v[72:75], v[76:77], off offset:512
	s_nop 0
	global_load_dwordx4 v[76:79], v[76:77], off offset:576
	s_nop 0
	global_load_dwordx4 v[80:83], v[92:93], off
	global_load_dwordx4 v[84:87], v[92:93], off offset:64
	global_load_dwordx4 v[88:91], v[92:93], off offset:512
	s_nop 0
	global_load_dwordx4 v[92:95], v[92:93], off offset:576
	s_nop 0
	global_load_dwordx4 v[96:99], v[108:109], off
	global_load_dwordx4 v[100:103], v[108:109], off offset:64
	global_load_dwordx4 v[104:107], v[108:109], off offset:512
	s_nop 0
	global_load_dwordx4 v[108:111], v[108:109], off offset:576
	v_lshlrev_b64 v[154:155], 13, v[112:113]
	v_lshl_add_u64 v[124:125], v[152:153], 0, v[154:155]
	global_load_dwordx4 v[112:115], v[124:125], off
	global_load_dwordx4 v[116:119], v[124:125], off offset:64
	global_load_dwordx4 v[120:123], v[124:125], off offset:512
	s_nop 0
	global_load_dwordx4 v[124:127], v[124:125], off offset:576
	v_lshl_add_u64 v[152:153], s[20:21], 0, v[160:161]
	v_lshl_add_u64 v[160:161], s[20:21], 0, v[162:163]
	v_lshl_add_u64 v[162:163], s[20:21], 0, v[164:165]
	v_lshl_add_u64 v[152:153], v[152:153], 0, v[150:151]
	v_lshl_add_u64 v[162:163], v[162:163], 0, v[150:151]
	v_lshl_add_u64 v[160:161], v[160:161], 0, v[150:151]
	s_waitcnt vmcnt(15)
	v_pk_fma_f32 v[62:63], v[62:63], v[142:143], v[66:67]
	v_pk_fma_f32 v[60:61], v[60:61], v[140:141], v[64:65]
	s_waitcnt vmcnt(14)
	v_pk_fma_f32 v[58:59], v[58:59], v[138:139], v[70:71]
	v_pk_fma_f32 v[56:57], v[56:57], v[136:137], v[68:69]
	s_waitcnt vmcnt(13)
	v_pk_fma_f32 v[42:43], v[42:43], v[134:135], v[74:75]
	s_waitcnt vmcnt(4)
	v_pk_fma_f32 v[14:15], v[14:15], v[130:131], v[110:111]
	v_pk_fma_f32 v[12:13], v[12:13], v[128:129], v[108:109]
	v_pk_fma_f32 v[40:41], v[40:41], v[132:133], v[72:73]
	v_pk_fma_f32 v[38:39], v[38:39], v[130:131], v[78:79]
	v_pk_fma_f32 v[36:37], v[36:37], v[128:129], v[76:77]
	v_pk_fma_f32 v[54:55], v[54:55], v[142:143], v[82:83]
	v_pk_fma_f32 v[52:53], v[52:53], v[140:141], v[80:81]
	v_pk_fma_f32 v[50:51], v[50:51], v[138:139], v[86:87]
	v_pk_fma_f32 v[48:49], v[48:49], v[136:137], v[84:85]
	v_pk_fma_f32 v[30:31], v[30:31], v[134:135], v[90:91]
	v_pk_fma_f32 v[28:29], v[28:29], v[132:133], v[88:89]
	v_pk_fma_f32 v[26:27], v[26:27], v[130:131], v[94:95]
	v_pk_fma_f32 v[24:25], v[24:25], v[128:129], v[92:93]
	v_pk_fma_f32 v[46:47], v[46:47], v[142:143], v[98:99]
	v_pk_fma_f32 v[44:45], v[44:45], v[140:141], v[96:97]
	v_pk_fma_f32 v[34:35], v[34:35], v[138:139], v[102:103]
	v_pk_fma_f32 v[32:33], v[32:33], v[136:137], v[100:101]
	v_pk_fma_f32 v[22:23], v[22:23], v[134:135], v[106:107]
	v_pk_fma_f32 v[20:21], v[20:21], v[132:133], v[104:105]
	global_store_dwordx4 v[152:153], v[60:63], off sc1
	global_store_dwordx4 v[152:153], v[56:59], off offset:64 sc1
	global_store_dwordx4 v[152:153], v[40:43], off offset:512 sc1
	global_store_dwordx4 v[152:153], v[36:39], off offset:576 sc1
	global_store_dwordx4 v[160:161], v[52:55], off sc1
	global_store_dwordx4 v[160:161], v[48:51], off offset:64 sc1
	global_store_dwordx4 v[160:161], v[28:31], off offset:512 sc1
	global_store_dwordx4 v[160:161], v[24:27], off offset:576 sc1
	global_store_dwordx4 v[162:163], v[44:47], off sc1
	global_store_dwordx4 v[162:163], v[32:35], off offset:64 sc1
	global_store_dwordx4 v[162:163], v[20:23], off offset:512 sc1
	global_store_dwordx4 v[162:163], v[12:15], off offset:576 sc1
	s_waitcnt vmcnt(14)
	v_pk_fma_f32 v[10:11], v[10:11], v[138:139], v[118:119]
	v_pk_fma_f32 v[8:9], v[8:9], v[136:137], v[116:117]
	v_lshl_add_u64 v[12:13], s[20:21], 0, v[154:155]
	v_lshl_add_u64 v[20:21], v[12:13], 0, v[150:151]
	v_pk_fma_f32 v[14:15], v[18:19], v[142:143], v[114:115]
	v_pk_fma_f32 v[12:13], v[16:17], v[140:141], v[112:113]
	s_waitcnt vmcnt(13)
	v_pk_fma_f32 v[6:7], v[6:7], v[134:135], v[122:123]
	v_pk_fma_f32 v[4:5], v[4:5], v[132:133], v[120:121]
	s_waitcnt vmcnt(12)
	v_pk_fma_f32 v[2:3], v[2:3], v[130:131], v[126:127]
	v_pk_fma_f32 v[0:1], v[0:1], v[128:129], v[124:125]
	global_store_dwordx4 v[20:21], v[12:15], off sc1
	global_store_dwordx4 v[20:21], v[8:11], off offset:64 sc1
	global_store_dwordx4 v[20:21], v[4:7], off offset:512 sc1
	global_store_dwordx4 v[20:21], v[0:3], off offset:576 sc1

.LBB0_1842:
	v_mov_b32_e32 v1, s36
	v_add_co_u32_e32 v2, vcc, 0x3000, v1
	v_mov_b32_e32 v1, s37
	s_waitcnt vmcnt(0)
	v_addc_co_u32_e32 v3, vcc, 0, v1, vcc
	flat_atomic_add v1, v[2:3], v217 offset:1024 sc0
	v_cvt_f32_u32_e32 v2, v0
	v_sub_u32_e32 v3, 0, v0
	s_mov_b64 s[8:9], -1
	v_rcp_iflag_f32_e32 v2, v2
	s_nop 0
	v_mul_f32_e32 v2, 0x4f7ffffe, v2
	v_cvt_u32_f32_e32 v2, v2
	v_mul_lo_u32 v3, v3, v2
	v_mul_hi_u32 v3, v2, v3
	v_add_u32_e32 v2, v2, v3
	s_waitcnt vmcnt(0) lgkmcnt(0)
	v_mul_hi_u32 v2, v1, v2
	v_mul_lo_u32 v3, v2, v0
	v_sub_u32_e32 v3, v1, v3
	v_cmp_ge_u32_e32 vcc, v3, v0
	v_add_u32_e32 v4, 1, v2
	s_nop 0
	v_cndmask_b32_e32 v2, v2, v4, vcc
	v_sub_u32_e32 v4, v3, v0
	v_cndmask_b32_e32 v3, v3, v4, vcc
	v_cmp_ge_u32_e32 vcc, v3, v0
	v_add_u32_e32 v3, 1, v2
	s_nop 0
	v_cndmask_b32_e32 v2, v2, v3, vcc
	v_add_u32_e32 v3, 1, v1
	v_mad_u64_u32 v[0:1], s[4:5], v0, v2, v[0:1]
	s_add_u32 s4, s36, 0x3500
	s_addc_u32 s5, s37, 0
	v_cmp_ne_u32_e32 vcc, v3, v0
	v_mov_b64_e32 v[0:1], s[4:5]
	s_and_saveexec_b64 s[6:7], vcc
	s_cbranch_execz .LBB0_1854
	v_mov_b64_e32 v[0:1], s[4:5]
	flat_load_dword v0, v[0:1] sc1
	s_mov_b64 s[12:13], 0
	s_waitcnt vmcnt(0) lgkmcnt(0)
	v_cmp_eq_u32_e32 vcc, v0, v2
	s_and_saveexec_b64 s[10:11], vcc
	s_cbranch_execz .LBB0_1853
	s_add_u32 s8, s36, 0x200
	s_addc_u32 s9, s37, 0
	s_mov_b32 s25, 1
	s_branch .LBB0_1846
